# EpiResid epilogue: prefetch residual rows 2..7 at epilogue start into free fragment registers (on top of combine + rss hoist)
# baseline (speedup 1.0000x reference)
;     __device__ __forceinline__ void operator()(const f32x4 (&acc)[2][2][4][2], const Unit& u, int wr, int wc, int fr, int fq, PG8_LAS unsigned char*) const {
;         const int col0 = u.pn * BM + wc * 32 + 4 * fq;
;         u32x2 cur[2][2], nxt[2][2];
;         { const size_t off = (size_t)(u.pm * BM + wr * 64 + fr) * 1024 + col0;
; #pragma unroll
;           for (int bj = 0; bj < 2; ++bj)
; #pragma unroll
;             for (int n = 0; n < 2; ++n) cur[bj][n] = *(const u32x2*)(xb + off + bj * HALF + n * 16); }
; #pragma unroll
;         for (int ri = 0; ri < 8; ++ri) {
;             const int ai = ri >> 2, m = ri & 3;
;             const int row = u.pm * BM + ai * HALF + wr * 64 + m * 16 + fr; float ss = 0.f;
;             if (ri < 7) { const int ai2 = (ri + 1) >> 2, m2 = (ri + 1) & 3; const size_t off2 = (size_t)(u.pm * BM + ai2 * HALF + wr * 64 + m2 * 16 + fr) * 1024 + col0;
; #pragma unroll
;                 for (int bj = 0; bj < 2; ++bj)
; #pragma unroll
;                     for (int n = 0; n < 2; ++n) nxt[bj][n] = *(const u32x2*)(xb + off2 + bj * HALF + n * 16); }
; #pragma unroll
;             for (int bj = 0; bj < 2; ++bj)
; #pragma unroll
;                 for (int n = 0; n < 2; ++n) { const u32x2 bb = cur[bj][n]; const f32x4 av = acc[ai][bj][m][n];
;                     const float o0 = __uint_as_float(bb.x << 16) + av[0], o1 = __uint_as_float(bb.x & 0xffff0000u) + av[1], o2 = __uint_as_float(bb.y << 16) + av[2], o3 = __uint_as_float(bb.y & 0xffff0000u) + av[3];
;                     ss += (o0 * o0 + o1 * o1) + (o2 * o2 + o3 * o3);
;                     cur[bj][n].x = cvt_pk_bf16(o0, o1); cur[bj][n].y = cvt_pk_bf16(o2, o3); }
; #pragma unroll
;             for (int bj = 0; bj < 2; ++bj) { unsigned a0 = cur[bj][0].x, a1 = cur[bj][0].y, b0 = cur[bj][1].x, b1 = cur[bj][1].y;
;                 { auto r = __builtin_amdgcn_permlane16_swap(a0, b0, false, false); a0 = r[0]; b0 = r[1]; }
;                 { auto r = __builtin_amdgcn_permlane16_swap(a1, b1, false, false); a1 = r[0]; b1 = r[1]; }
;                 u32x4 w; w.x = a0; w.y = a1; w.z = b0; w.w = b1; *(u32x4*)(xb + (size_t)row * 1024 + u.pn * BM + wc * 32 + bj * HALF + ((fq & 1) << 4) + ((fq >> 1) << 3)) = w; }
;             ss += __shfl_xor(ss, 16); ss += __shfl_xor(ss, 32);
;             if (fq == 0) atomicAdd(rss_next + row, (unsigned long long)(ss * 4294967296.0f));
.LBB0_436:
	s_lshl_b32 s70, s70, 8
	v_lshl_add_u32 v146, s68, 8, v160
	v_or_b32_e32 v144, s70, v162
	v_ashrrev_i32_e32 v147, 31, v146
	v_ashrrev_i32_e32 v145, 31, v144
	v_lshlrev_b64 v[148:149], 11, v[146:147]
	v_lshl_add_u64 v[152:153], s[26:27], 0, v[148:149]
	v_lshlrev_b64 v[154:155], 1, v[144:145]
	v_lshl_add_u64 v[148:149], v[152:153], 0, v[154:155]
	global_load_dwordx2 v[168:169], v[148:149], off
	global_load_dwordx2 v[170:171], v[148:149], off offset:32
	global_load_dwordx2 v[172:173], v[148:149], off offset:256
	global_load_dwordx2 v[174:175], v[148:149], off offset:288
	v_or_b32_e32 v148, 16, v146
	v_ashrrev_i32_e32 v149, 31, v148
	v_lshlrev_b64 v[150:151], 11, v[148:149]
	s_ashr_i32 s71, s70, 31
	v_lshl_add_u64 v[150:151], s[26:27], 0, v[150:151]
	v_lshl_add_u64 v[152:153], s[70:71], 1, v[152:153]
	v_lshl_add_u64 v[176:177], v[150:151], 0, v[154:155]
	v_lshl_add_u64 v[178:179], v[152:153], 0, s[8:9]
	global_load_dwordx2 v[158:159], v[176:177], off
	global_load_dwordx2 v[156:157], v[176:177], off offset:32
	global_load_dwordx2 v[154:155], v[176:177], off offset:256
	global_load_dwordx2 v[152:153], v[176:177], off offset:288
	s_mov_b64 s[98:99], 0x8000
	v_lshl_add_u64 v[252:253], v[176:177], 0, s[98:99]
	global_load_dwordx2 v[186:187], v[252:253], off
	global_load_dwordx2 v[188:189], v[252:253], off offset:32
	global_load_dwordx2 v[190:191], v[252:253], off offset:256
	global_load_dwordx2 v[192:193], v[252:253], off offset:288
	s_mov_b64 s[98:99], 0x10000
	v_lshl_add_u64 v[252:253], v[176:177], 0, s[98:99]
	global_load_dwordx2 v[194:195], v[252:253], off
	global_load_dwordx2 v[196:197], v[252:253], off offset:32
	global_load_dwordx2 v[198:199], v[252:253], off offset:256
	global_load_dwordx2 v[200:201], v[252:253], off offset:288
	s_mov_b64 s[98:99], 0x38000
	v_lshl_add_u64 v[252:253], v[176:177], 0, s[98:99]
	global_load_dwordx2 v[202:203], v[252:253], off
	global_load_dwordx2 v[204:205], v[252:253], off offset:32
	global_load_dwordx2 v[206:207], v[252:253], off offset:256
	global_load_dwordx2 v[208:209], v[252:253], off offset:288
	s_mov_b64 s[98:99], 0x40000
	v_lshl_add_u64 v[252:253], v[176:177], 0, s[98:99]
	global_load_dwordx2 v[210:211], v[252:253], off
	global_load_dwordx2 v[212:213], v[252:253], off offset:32
	global_load_dwordx2 v[216:217], v[252:253], off offset:256
	global_load_dwordx2 v[218:219], v[252:253], off offset:288
	s_mov_b64 s[98:99], 0x48000
	v_lshl_add_u64 v[252:253], v[176:177], 0, s[98:99]
	global_load_dwordx2 v[220:221], v[252:253], off
	global_load_dwordx2 v[222:223], v[252:253], off offset:32
	global_load_dwordx2 v[224:225], v[252:253], off offset:256
	global_load_dwordx2 v[226:227], v[252:253], off offset:288
	s_mov_b64 s[98:99], 0x50000
	v_lshl_add_u64 v[252:253], v[176:177], 0, s[98:99]
	global_load_dwordx2 v[228:229], v[252:253], off
	global_load_dwordx2 v[230:231], v[252:253], off offset:32
	global_load_dwordx2 v[232:233], v[252:253], off offset:256
	global_load_dwordx2 v[234:235], v[252:253], off offset:288
	v_xor_b32_e32 v143, 16, v166
	s_waitcnt vmcnt(24)
	v_lshlrev_b32_e32 v167, 16, v168
	v_and_b32_e32 v168, 0xffff0000, v168
	v_lshlrev_b32_e32 v176, 16, v169
	v_and_b32_e32 v169, 0xffff0000, v169
	v_lshlrev_b32_e32 v177, 16, v170
	v_and_b32_e32 v170, 0xffff0000, v170
	v_lshlrev_b32_e32 v180, 16, v171
	v_and_b32_e32 v171, 0xffff0000, v171
	v_lshlrev_b32_e32 v181, 16, v172
	v_and_b32_e32 v172, 0xffff0000, v172
	v_lshlrev_b32_e32 v182, 16, v173
	v_and_b32_e32 v173, 0xffff0000, v173
	v_lshlrev_b32_e32 v183, 16, v174
	v_and_b32_e32 v174, 0xffff0000, v174
	v_add_f32_e32 v125, v125, v168
	v_add_f32_e32 v127, v127, v169
	v_add_f32_e32 v121, v121, v170
	v_add_f32_e32 v123, v123, v171
	v_lshlrev_b32_e32 v184, 16, v175
	v_and_b32_e32 v175, 0xffff0000, v175
	v_add_f32_e32 v124, v124, v167
	v_add_f32_e32 v126, v126, v176
	v_add_f32_e32 v120, v120, v177
	v_add_f32_e32 v122, v122, v180
	v_add_f32_e32 v167, v116, v181
	v_add_f32_e32 v116, v117, v172
	v_add_f32_e32 v168, v118, v182
	v_add_f32_e32 v117, v119, v173
	v_add_f32_e32 v169, v112, v183
	v_add_f32_e32 v118, v113, v174
	v_mul_f32_e32 v171, v125, v125
	v_mul_f32_e32 v172, v127, v127
	v_cvt_pk_bf16_f32 v112, v124, v125
	v_cvt_pk_bf16_f32 v113, v126, v127
	v_mul_f32_e32 v125, v121, v121
	v_mul_f32_e32 v127, v123, v123
	v_add_f32_e32 v170, v114, v184
	v_add_f32_e32 v119, v115, v175
	v_cvt_pk_bf16_f32 v114, v120, v121
	v_cvt_pk_bf16_f32 v115, v122, v123
	v_mul_f32_e32 v121, v116, v116
	v_mul_f32_e32 v123, v117, v117
	v_fmac_f32_e32 v171, v124, v124
	v_fmac_f32_e32 v172, v126, v126
	v_fmac_f32_e32 v125, v120, v120
	v_fmac_f32_e32 v127, v122, v122
	v_mul_f32_e32 v173, v118, v118
	v_mul_f32_e32 v174, v119, v119
	v_fmac_f32_e32 v121, v167, v167
	v_fmac_f32_e32 v123, v168, v168
	v_add_f32_e32 v120, v171, v172
	v_add_f32_e32 v122, v125, v127
	v_fmac_f32_e32 v173, v169, v169
	v_fmac_f32_e32 v174, v170, v170
	v_add_f32_e32 v121, v121, v123
	v_add_f32_e32 v120, v120, v122
	v_add_f32_e32 v123, v173, v174
	v_add_f32_e32 v120, v120, v121
	v_add_f32_e32 v122, v120, v123
	v_and_b32_e32 v120, 64, v166
	v_add_u32_e32 v123, 64, v120
	v_cmp_lt_i32_e32 vcc, v143, v123
	v_permlane16_swap_b32_e32 v112, v114
	s_nop 0
	v_cndmask_b32_e32 v120, v166, v143, vcc
	v_lshlrev_b32_e32 v124, 2, v120
	ds_bpermute_b32 v125, v124, v122
	v_lshl_add_u64 v[120:121], v[178:179], 0, v[132:133]
	v_mov_b32_e32 v143, v133
	v_permlane16_swap_b32_e32 v113, v115
	v_lshl_add_u64 v[120:121], v[120:121], 0, v[142:143]
	v_cvt_pk_bf16_f32 v116, v167, v116
	v_cvt_pk_bf16_f32 v117, v168, v117
	v_cvt_pk_bf16_f32 v118, v169, v118
	v_cvt_pk_bf16_f32 v119, v170, v119
	global_store_dwordx4 v[120:121], v[112:115], off
	v_permlane16_swap_b32_e32 v116, v118
	s_nop 0
	v_xor_b32_e32 v113, 32, v166
	v_cmp_lt_i32_e32 vcc, v113, v123
	s_waitcnt lgkmcnt(0)
	v_add_f32_e32 v112, v122, v125
	v_permlane16_swap_b32_e32 v117, v119
	v_cndmask_b32_e32 v113, v166, v113, vcc
	v_lshlrev_b32_e32 v125, 2, v113
	ds_bpermute_b32 v113, v125, v112
	global_store_dwordx4 v[120:121], v[116:119], off offset:256
	s_and_saveexec_b64 s[68:69], s[4:5]
	s_cbranch_execz .LBB0_438
	s_waitcnt lgkmcnt(0)
	v_add_f32_e32 v112, v112, v113
	v_mul_f32_e32 v112, 0x4f800000, v112
	v_trunc_f32_e32 v112, v112
	v_mul_f32_e32 v113, 0x2f800000, v112
	v_floor_f32_e32 v113, v113
	v_fmac_f32_e32 v112, 0xcf800000, v113
	v_cvt_u32_f32_e32 v112, v112
	v_cvt_u32_f32_e32 v113, v113
	v_lshl_add_u64 v[114:115], v[146:147], 3, s[12:13]
	global_atomic_add_x2 v[114:115], v[112:113], off
; __device__ __forceinline__ unsigned cvt_pk_bf16(float lo, float hi) { unsigned r; asm volatile("v_cvt_pk_bf16_f32 %0, %1, %2" : "=v"(r) : "v"(lo), "v"(hi)); return r; }
;     __device__ __forceinline__ void operator()(const f32x4 (&acc)[2][2][4][2], const Unit& u, int wr, int wc, int fr, int fq, PG8_LAS unsigned char*) const {
;     ...
;         for (int ri = 0; ri < 8; ++ri) {
;             const int ai = ri >> 2, m = ri & 3;
;             const int row = u.pm * BM + ai * HALF + wr * 64 + m * 16 + fr; float ss = 0.f;
;             if (ri < 7) { const int ai2 = (ri + 1) >> 2, m2 = (ri + 1) & 3; const size_t off2 = (size_t)(u.pm * BM + ai2 * HALF + wr * 64 + m2 * 16 + fr) * 1024 + col0;
; #pragma unroll
;                 for (int bj = 0; bj < 2; ++bj)
; #pragma unroll
;                     for (int n = 0; n < 2; ++n) nxt[bj][n] = *(const u32x2*)(xb + off2 + bj * HALF + n * 16); }
; #pragma unroll
;             for (int bj = 0; bj < 2; ++bj)
; #pragma unroll
;                 for (int n = 0; n < 2; ++n) { const u32x2 bb = cur[bj][n]; const f32x4 av = acc[ai][bj][m][n];
;                     const float o0 = __uint_as_float(bb.x << 16) + av[0], o1 = __uint_as_float(bb.x & 0xffff0000u) + av[1], o2 = __uint_as_float(bb.y << 16) + av[2], o3 = __uint_as_float(bb.y & 0xffff0000u) + av[3];
;                     ss += (o0 * o0 + o1 * o1) + (o2 * o2 + o3 * o3);
;                     cur[bj][n].x = cvt_pk_bf16(o0, o1); cur[bj][n].y = cvt_pk_bf16(o2, o3); }
; #pragma unroll
;             for (int bj = 0; bj < 2; ++bj) { unsigned a0 = cur[bj][0].x, a1 = cur[bj][0].y, b0 = cur[bj][1].x, b1 = cur[bj][1].y;
;                 { auto r = __builtin_amdgcn_permlane16_swap(a0, b0, false, false); a0 = r[0]; b0 = r[1]; }
;                 { auto r = __builtin_amdgcn_permlane16_swap(a1, b1, false, false); a1 = r[0]; b1 = r[1]; }
;                 u32x4 w; w.x = a0; w.y = a1; w.z = b0; w.w = b1; *(u32x4*)(xb + (size_t)row * 1024 + u.pn * BM + wc * 32 + bj * HALF + ((fq & 1) << 4) + ((fq >> 1) << 3)) = w; }
;             ss += __shfl_xor(ss, 16); ss += __shfl_xor(ss, 32);
;             if (fq == 0) atomicAdd(rss_next + row, (unsigned long long)(ss * 4294967296.0f));
.LBB0_438:
	s_or_b64 exec, exec, s[68:69]
	v_or_b32_e32 v112, 32, v146
	s_waitcnt lgkmcnt(0)
	v_ashrrev_i32_e32 v113, 31, v112
	v_lshlrev_b64 v[114:115], 11, v[112:113]
	v_lshl_add_u64 v[114:115], s[26:27], 0, v[114:115]
	v_lshl_add_u64 v[116:117], v[144:145], 1, v[114:115]
	v_lshlrev_b32_e32 v126, 16, v158
	v_add_f32_e32 v108, v108, v126
	v_and_b32_e32 v126, 0xffff0000, v158
	v_add_f32_e32 v109, v109, v126
	v_lshlrev_b32_e32 v126, 16, v159
	v_add_f32_e32 v110, v110, v126
	v_and_b32_e32 v126, 0xffff0000, v159
	v_add_f32_e32 v111, v111, v126
	v_mul_f32_e32 v126, v109, v109
	v_mul_f32_e32 v127, v111, v111
	v_fmac_f32_e32 v126, v108, v108
	v_fmac_f32_e32 v127, v110, v110
	v_cvt_pk_bf16_f32 v108, v108, v109
	v_cvt_pk_bf16_f32 v109, v110, v111
	v_lshlrev_b32_e32 v110, 16, v156
	v_add_f32_e32 v104, v104, v110
	v_and_b32_e32 v110, 0xffff0000, v156
	v_add_f32_e32 v105, v105, v110
	v_lshlrev_b32_e32 v110, 16, v157
	v_add_f32_e32 v106, v106, v110
	v_and_b32_e32 v110, 0xffff0000, v157
	v_add_f32_e32 v107, v107, v110
	v_mul_f32_e32 v110, v105, v105
	v_mul_f32_e32 v111, v107, v107
	v_fmac_f32_e32 v110, v104, v104
	v_fmac_f32_e32 v111, v106, v106
	v_add_f32_e32 v126, v126, v127
	v_add_f32_e32 v110, v110, v111
	v_add_f32_e32 v126, v126, v110
	v_cvt_pk_bf16_f32 v110, v104, v105
	v_lshlrev_b32_e32 v104, 16, v154
	v_add_f32_e32 v100, v100, v104
	v_and_b32_e32 v104, 0xffff0000, v154
	v_add_f32_e32 v101, v101, v104
	v_lshlrev_b32_e32 v104, 16, v155
	v_add_f32_e32 v102, v102, v104
	v_and_b32_e32 v104, 0xffff0000, v155
	v_add_f32_e32 v103, v103, v104
	v_mul_f32_e32 v104, v101, v101
	v_mul_f32_e32 v105, v103, v103
	v_cvt_pk_bf16_f32 v111, v106, v107
	v_fmac_f32_e32 v104, v100, v100
	v_fmac_f32_e32 v105, v102, v102
	v_cvt_pk_bf16_f32 v100, v100, v101
	v_cvt_pk_bf16_f32 v101, v102, v103
	v_lshlrev_b32_e32 v102, 16, v152
	v_add_f32_e32 v96, v96, v102
	v_and_b32_e32 v102, 0xffff0000, v152
	v_add_f32_e32 v97, v97, v102
	v_lshlrev_b32_e32 v102, 16, v153
	v_add_f32_e32 v98, v98, v102
	v_and_b32_e32 v102, 0xffff0000, v153
	v_add_f32_e32 v99, v99, v102
	v_mul_f32_e32 v102, v97, v97
	v_mul_f32_e32 v103, v99, v99
	v_add_f32_e32 v104, v104, v105
	v_fmac_f32_e32 v102, v96, v96
	v_fmac_f32_e32 v103, v98, v98
	v_add_f32_e32 v105, v102, v103
	v_cvt_pk_bf16_f32 v102, v96, v97
	v_cvt_pk_bf16_f32 v103, v98, v99
	v_add_f32_e32 v98, v126, v104
	v_add_f32_e32 v104, v98, v105
	ds_bpermute_b32 v105, v124, v104
	v_lshl_add_u64 v[96:97], s[70:71], 1, v[150:151]
	v_lshl_add_u64 v[96:97], v[96:97], 0, s[8:9]
	v_lshl_add_u64 v[96:97], v[96:97], 0, v[132:133]
	v_lshl_add_u64 v[98:99], v[96:97], 0, v[142:143]
	s_waitcnt lgkmcnt(0)
	v_add_f32_e32 v96, v104, v105
	ds_bpermute_b32 v97, v125, v96
	v_permlane16_swap_b32_e32 v108, v110
	v_permlane16_swap_b32_e32 v109, v111
	v_permlane16_swap_b32_e32 v100, v102
	v_permlane16_swap_b32_e32 v101, v103
	global_store_dwordx4 v[98:99], v[108:111], off
	global_store_dwordx4 v[98:99], v[100:103], off offset:256
	s_and_saveexec_b64 s[68:69], s[4:5]
	s_cbranch_execz .LBB0_440
	s_waitcnt lgkmcnt(0)
	v_add_f32_e32 v96, v96, v97
	v_mul_f32_e32 v96, 0x4f800000, v96
	v_trunc_f32_e32 v96, v96
	v_mul_f32_e32 v97, 0x2f800000, v96
	v_floor_f32_e32 v97, v97
	v_fmac_f32_e32 v96, 0xcf800000, v97
	v_cvt_u32_f32_e32 v96, v96
	v_cvt_u32_f32_e32 v97, v97
	v_lshl_add_u64 v[98:99], v[148:149], 3, s[12:13]
	global_atomic_add_x2 v[98:99], v[96:97], off
.LBB0_440:
	s_or_b64 exec, exec, s[68:69]
	v_or_b32_e32 v96, 48, v146
	s_waitcnt lgkmcnt(0)
	v_ashrrev_i32_e32 v97, 31, v96
	v_lshlrev_b64 v[98:99], 11, v[96:97]
	v_lshl_add_u64 v[98:99], s[26:27], 0, v[98:99]
	v_lshl_add_u64 v[100:101], v[144:145], 1, v[98:99]
	s_waitcnt vmcnt(24)
	v_mov_b64_e32 v[122:123], v[186:187]
	v_mov_b64_e32 v[120:121], v[188:189]
	v_mov_b64_e32 v[118:119], v[190:191]
	v_mov_b64_e32 v[116:117], v[192:193]
	v_lshlrev_b32_e32 v108, 16, v122
	v_add_f32_e32 v92, v92, v108
	v_and_b32_e32 v108, 0xffff0000, v122
	v_add_f32_e32 v93, v93, v108
	v_lshlrev_b32_e32 v108, 16, v123
	v_add_f32_e32 v94, v94, v108
	v_and_b32_e32 v108, 0xffff0000, v123
	v_add_f32_e32 v95, v95, v108
	v_mul_f32_e32 v108, v93, v93
	v_mul_f32_e32 v109, v95, v95
	v_fmac_f32_e32 v108, v92, v92
	v_fmac_f32_e32 v109, v94, v94
	v_cvt_pk_bf16_f32 v92, v92, v93
	v_cvt_pk_bf16_f32 v93, v94, v95
	v_lshlrev_b32_e32 v94, 16, v120
	v_add_f32_e32 v88, v88, v94
	v_and_b32_e32 v94, 0xffff0000, v120
	v_add_f32_e32 v89, v89, v94
	v_lshlrev_b32_e32 v94, 16, v121
	v_add_f32_e32 v90, v90, v94
	v_and_b32_e32 v94, 0xffff0000, v121
	v_add_f32_e32 v91, v91, v94
	v_mul_f32_e32 v94, v89, v89
	v_mul_f32_e32 v95, v91, v91
	v_fmac_f32_e32 v94, v88, v88
	v_fmac_f32_e32 v95, v90, v90
	v_add_f32_e32 v108, v108, v109
	v_add_f32_e32 v94, v94, v95
	v_add_f32_e32 v108, v108, v94
	v_cvt_pk_bf16_f32 v94, v88, v89
	v_lshlrev_b32_e32 v88, 16, v118
	v_add_f32_e32 v84, v84, v88
	v_and_b32_e32 v88, 0xffff0000, v118
	v_add_f32_e32 v85, v85, v88
	v_lshlrev_b32_e32 v88, 16, v119
	v_add_f32_e32 v86, v86, v88
	v_and_b32_e32 v88, 0xffff0000, v119
	v_add_f32_e32 v87, v87, v88
	v_mul_f32_e32 v88, v85, v85
	v_mul_f32_e32 v89, v87, v87
	v_cvt_pk_bf16_f32 v95, v90, v91
	v_fmac_f32_e32 v88, v84, v84
	v_fmac_f32_e32 v89, v86, v86
	v_cvt_pk_bf16_f32 v84, v84, v85
	v_cvt_pk_bf16_f32 v85, v86, v87
	v_lshlrev_b32_e32 v86, 16, v116
	v_add_f32_e32 v80, v80, v86
	v_and_b32_e32 v86, 0xffff0000, v116
	v_add_f32_e32 v81, v81, v86
	v_lshlrev_b32_e32 v86, 16, v117
	v_add_f32_e32 v82, v82, v86
	v_and_b32_e32 v86, 0xffff0000, v117
	v_add_f32_e32 v83, v83, v86
	v_mul_f32_e32 v86, v81, v81
	v_mul_f32_e32 v87, v83, v83
	v_add_f32_e32 v88, v88, v89
	v_fmac_f32_e32 v86, v80, v80
	v_fmac_f32_e32 v87, v82, v82
	v_add_f32_e32 v89, v86, v87
	v_cvt_pk_bf16_f32 v86, v80, v81
	v_cvt_pk_bf16_f32 v87, v82, v83
	v_add_f32_e32 v82, v108, v88
	v_add_f32_e32 v88, v82, v89
	ds_bpermute_b32 v89, v124, v88
	v_lshl_add_u64 v[80:81], s[70:71], 1, v[114:115]
	v_lshl_add_u64 v[80:81], v[80:81], 0, s[8:9]
	v_lshl_add_u64 v[80:81], v[80:81], 0, v[132:133]
	v_mov_b32_e32 v143, v133
	v_lshl_add_u64 v[82:83], v[80:81], 0, v[142:143]
	s_waitcnt lgkmcnt(0)
	v_add_f32_e32 v80, v88, v89
	ds_bpermute_b32 v81, v125, v80
	v_permlane16_swap_b32_e32 v92, v94
	v_permlane16_swap_b32_e32 v93, v95
	v_permlane16_swap_b32_e32 v84, v86
	v_permlane16_swap_b32_e32 v85, v87
	global_store_dwordx4 v[82:83], v[92:95], off
	global_store_dwordx4 v[82:83], v[84:87], off offset:256
	s_and_saveexec_b64 s[68:69], s[4:5]
	s_cbranch_execz .LBB0_442
	s_waitcnt lgkmcnt(0)
	v_add_f32_e32 v80, v80, v81
	v_mul_f32_e32 v80, 0x4f800000, v80
	v_trunc_f32_e32 v80, v80
	v_mul_f32_e32 v81, 0x2f800000, v80
	v_floor_f32_e32 v81, v81
	v_fmac_f32_e32 v80, 0xcf800000, v81
	v_cvt_u32_f32_e32 v80, v80
	v_cvt_u32_f32_e32 v81, v81
	v_lshl_add_u64 v[82:83], v[112:113], 3, s[12:13]
	global_atomic_add_x2 v[82:83], v[80:81], off
; __device__ __forceinline__ unsigned cvt_pk_bf16(float lo, float hi) { unsigned r; asm volatile("v_cvt_pk_bf16_f32 %0, %1, %2" : "=v"(r) : "v"(lo), "v"(hi)); return r; }
;     __device__ __forceinline__ void operator()(const f32x4 (&acc)[2][2][4][2], const Unit& u, int wr, int wc, int fr, int fq, PG8_LAS unsigned char*) const {
;     ...
;         for (int ri = 0; ri < 8; ++ri) {
;             const int ai = ri >> 2, m = ri & 3;
;             const int row = u.pm * BM + ai * HALF + wr * 64 + m * 16 + fr; float ss = 0.f;
;             if (ri < 7) { const int ai2 = (ri + 1) >> 2, m2 = (ri + 1) & 3; const size_t off2 = (size_t)(u.pm * BM + ai2 * HALF + wr * 64 + m2 * 16 + fr) * 1024 + col0;
; #pragma unroll
;                 for (int bj = 0; bj < 2; ++bj)
; #pragma unroll
;                     for (int n = 0; n < 2; ++n) nxt[bj][n] = *(const u32x2*)(xb + off2 + bj * HALF + n * 16); }
; #pragma unroll
;             for (int bj = 0; bj < 2; ++bj)
; #pragma unroll
;                 for (int n = 0; n < 2; ++n) { const u32x2 bb = cur[bj][n]; const f32x4 av = acc[ai][bj][m][n];
;                     const float o0 = __uint_as_float(bb.x << 16) + av[0], o1 = __uint_as_float(bb.x & 0xffff0000u) + av[1], o2 = __uint_as_float(bb.y << 16) + av[2], o3 = __uint_as_float(bb.y & 0xffff0000u) + av[3];
;                     ss += (o0 * o0 + o1 * o1) + (o2 * o2 + o3 * o3);
;                     cur[bj][n].x = cvt_pk_bf16(o0, o1); cur[bj][n].y = cvt_pk_bf16(o2, o3); }
; #pragma unroll
;             for (int bj = 0; bj < 2; ++bj) { unsigned a0 = cur[bj][0].x, a1 = cur[bj][0].y, b0 = cur[bj][1].x, b1 = cur[bj][1].y;
;                 { auto r = __builtin_amdgcn_permlane16_swap(a0, b0, false, false); a0 = r[0]; b0 = r[1]; }
;                 { auto r = __builtin_amdgcn_permlane16_swap(a1, b1, false, false); a1 = r[0]; b1 = r[1]; }
;                 u32x4 w; w.x = a0; w.y = a1; w.z = b0; w.w = b1; *(u32x4*)(xb + (size_t)row * 1024 + u.pn * BM + wc * 32 + bj * HALF + ((fq & 1) << 4) + ((fq >> 1) << 3)) = w; }
;             ss += __shfl_xor(ss, 16); ss += __shfl_xor(ss, 32);
;             if (fq == 0) atomicAdd(rss_next + row, (unsigned long long)(ss * 4294967296.0f));
.LBB0_442:
	s_or_b64 exec, exec, s[68:69]
	v_add_u32_e32 v80, 0x80, v146
	s_waitcnt lgkmcnt(0)
	v_ashrrev_i32_e32 v81, 31, v80
	v_lshlrev_b64 v[82:83], 11, v[80:81]
	v_lshl_add_u64 v[82:83], s[26:27], 0, v[82:83]
	v_lshl_add_u64 v[84:85], v[144:145], 1, v[82:83]
	s_waitcnt vmcnt(22)
	v_mov_b64_e32 v[106:107], v[194:195]
	v_mov_b64_e32 v[104:105], v[196:197]
	v_mov_b64_e32 v[102:103], v[198:199]
	v_mov_b64_e32 v[100:101], v[200:201]
	v_lshlrev_b32_e32 v92, 16, v106
	v_add_f32_e32 v76, v76, v92
	v_and_b32_e32 v92, 0xffff0000, v106
	v_add_f32_e32 v77, v77, v92
	v_lshlrev_b32_e32 v92, 16, v107
	v_add_f32_e32 v78, v78, v92
	v_and_b32_e32 v92, 0xffff0000, v107
	v_add_f32_e32 v79, v79, v92
	v_mul_f32_e32 v92, v77, v77
	v_mul_f32_e32 v93, v79, v79
	v_fmac_f32_e32 v92, v76, v76
	v_fmac_f32_e32 v93, v78, v78
	v_cvt_pk_bf16_f32 v76, v76, v77
	v_cvt_pk_bf16_f32 v77, v78, v79
	v_lshlrev_b32_e32 v78, 16, v104
	v_add_f32_e32 v72, v72, v78
	v_and_b32_e32 v78, 0xffff0000, v104
	v_add_f32_e32 v73, v73, v78
	v_lshlrev_b32_e32 v78, 16, v105
	v_add_f32_e32 v74, v74, v78
	v_and_b32_e32 v78, 0xffff0000, v105
	v_add_f32_e32 v75, v75, v78
	v_mul_f32_e32 v78, v73, v73
	v_mul_f32_e32 v79, v75, v75
	v_fmac_f32_e32 v78, v72, v72
	v_fmac_f32_e32 v79, v74, v74
	v_add_f32_e32 v92, v92, v93
	v_add_f32_e32 v78, v78, v79
	v_add_f32_e32 v92, v92, v78
	v_cvt_pk_bf16_f32 v78, v72, v73
	v_lshlrev_b32_e32 v72, 16, v102
	v_add_f32_e32 v68, v68, v72
	v_and_b32_e32 v72, 0xffff0000, v102
	v_add_f32_e32 v69, v69, v72
	v_lshlrev_b32_e32 v72, 16, v103
	v_add_f32_e32 v70, v70, v72
	v_and_b32_e32 v72, 0xffff0000, v103
	v_add_f32_e32 v71, v71, v72
	v_mul_f32_e32 v72, v69, v69
	v_mul_f32_e32 v73, v71, v71
	v_cvt_pk_bf16_f32 v79, v74, v75
	v_fmac_f32_e32 v72, v68, v68
	v_fmac_f32_e32 v73, v70, v70
	v_cvt_pk_bf16_f32 v68, v68, v69
	v_cvt_pk_bf16_f32 v69, v70, v71
	v_lshlrev_b32_e32 v70, 16, v100
	v_add_f32_e32 v64, v64, v70
	v_and_b32_e32 v70, 0xffff0000, v100
	v_add_f32_e32 v65, v65, v70
	v_lshlrev_b32_e32 v70, 16, v101
	v_add_f32_e32 v66, v66, v70
	v_and_b32_e32 v70, 0xffff0000, v101
	v_add_f32_e32 v67, v67, v70
	v_mul_f32_e32 v70, v65, v65
	v_mul_f32_e32 v71, v67, v67
	v_add_f32_e32 v72, v72, v73
	v_fmac_f32_e32 v70, v64, v64
	v_fmac_f32_e32 v71, v66, v66
	v_add_f32_e32 v73, v70, v71
	v_cvt_pk_bf16_f32 v70, v64, v65
	v_cvt_pk_bf16_f32 v71, v66, v67
	v_add_f32_e32 v66, v92, v72
	v_add_f32_e32 v72, v66, v73
	ds_bpermute_b32 v73, v124, v72
	v_lshl_add_u64 v[64:65], s[70:71], 1, v[98:99]
	v_lshl_add_u64 v[64:65], v[64:65], 0, s[8:9]
	v_lshl_add_u64 v[64:65], v[64:65], 0, v[132:133]
	v_lshl_add_u64 v[66:67], v[64:65], 0, v[142:143]
	s_waitcnt lgkmcnt(0)
	v_add_f32_e32 v64, v72, v73
	ds_bpermute_b32 v65, v125, v64
	v_permlane16_swap_b32_e32 v76, v78
	v_permlane16_swap_b32_e32 v77, v79
	v_permlane16_swap_b32_e32 v68, v70
	v_permlane16_swap_b32_e32 v69, v71
	global_store_dwordx4 v[66:67], v[76:79], off
	global_store_dwordx4 v[66:67], v[68:71], off offset:256
	s_and_saveexec_b64 s[68:69], s[4:5]
	s_cbranch_execz .LBB0_444
	s_waitcnt lgkmcnt(0)
	v_add_f32_e32 v64, v64, v65
	v_mul_f32_e32 v64, 0x4f800000, v64
	v_trunc_f32_e32 v64, v64
	v_mul_f32_e32 v65, 0x2f800000, v64
	v_floor_f32_e32 v65, v65
	v_fmac_f32_e32 v64, 0xcf800000, v65
	v_cvt_u32_f32_e32 v64, v64
	v_cvt_u32_f32_e32 v65, v65
	v_lshl_add_u64 v[66:67], v[96:97], 3, s[12:13]
	global_atomic_add_x2 v[66:67], v[64:65], off
.LBB0_444:
	s_or_b64 exec, exec, s[68:69]
	v_or_b32_e32 v64, 16, v80
	s_waitcnt lgkmcnt(0)
	v_ashrrev_i32_e32 v65, 31, v64
	v_lshlrev_b64 v[66:67], 11, v[64:65]
	v_lshl_add_u64 v[66:67], s[26:27], 0, v[66:67]
	v_lshl_add_u64 v[68:69], v[144:145], 1, v[66:67]
	s_waitcnt vmcnt(20)
	v_mov_b64_e32 v[90:91], v[202:203]
	v_mov_b64_e32 v[88:89], v[204:205]
	v_mov_b64_e32 v[86:87], v[206:207]
	v_mov_b64_e32 v[84:85], v[208:209]
	v_lshlrev_b32_e32 v76, 16, v90
	v_add_f32_e32 v60, v60, v76
	v_and_b32_e32 v76, 0xffff0000, v90
	v_add_f32_e32 v61, v61, v76
	v_lshlrev_b32_e32 v76, 16, v91
	v_add_f32_e32 v62, v62, v76
	v_and_b32_e32 v76, 0xffff0000, v91
	v_add_f32_e32 v63, v63, v76
	v_mul_f32_e32 v76, v61, v61
	v_mul_f32_e32 v77, v63, v63
	v_fmac_f32_e32 v76, v60, v60
	v_fmac_f32_e32 v77, v62, v62
	v_cvt_pk_bf16_f32 v60, v60, v61
	v_cvt_pk_bf16_f32 v61, v62, v63
	v_lshlrev_b32_e32 v62, 16, v88
	v_add_f32_e32 v56, v56, v62
	v_and_b32_e32 v62, 0xffff0000, v88
	v_add_f32_e32 v57, v57, v62
	v_lshlrev_b32_e32 v62, 16, v89
	v_add_f32_e32 v58, v58, v62
	v_and_b32_e32 v62, 0xffff0000, v89
	v_add_f32_e32 v59, v59, v62
	v_mul_f32_e32 v62, v57, v57
	v_mul_f32_e32 v63, v59, v59
	v_fmac_f32_e32 v62, v56, v56
	v_fmac_f32_e32 v63, v58, v58
	v_add_f32_e32 v76, v76, v77
	v_add_f32_e32 v62, v62, v63
	v_add_f32_e32 v76, v76, v62
	v_cvt_pk_bf16_f32 v62, v56, v57
	v_lshlrev_b32_e32 v56, 16, v86
	v_add_f32_e32 v52, v52, v56
	v_and_b32_e32 v56, 0xffff0000, v86
	v_add_f32_e32 v53, v53, v56
	v_lshlrev_b32_e32 v56, 16, v87
	v_add_f32_e32 v54, v54, v56
	v_and_b32_e32 v56, 0xffff0000, v87
	v_add_f32_e32 v55, v55, v56
	v_mul_f32_e32 v56, v53, v53
	v_mul_f32_e32 v57, v55, v55
	v_cvt_pk_bf16_f32 v63, v58, v59
	v_fmac_f32_e32 v56, v52, v52
	v_fmac_f32_e32 v57, v54, v54
	v_cvt_pk_bf16_f32 v52, v52, v53
	v_cvt_pk_bf16_f32 v53, v54, v55
	v_lshlrev_b32_e32 v54, 16, v84
	v_add_f32_e32 v48, v48, v54
	v_and_b32_e32 v54, 0xffff0000, v84
	v_add_f32_e32 v49, v49, v54
	v_lshlrev_b32_e32 v54, 16, v85
	v_add_f32_e32 v50, v50, v54
	v_and_b32_e32 v54, 0xffff0000, v85
	v_add_f32_e32 v51, v51, v54
	v_mul_f32_e32 v54, v49, v49
	v_mul_f32_e32 v55, v51, v51
	v_add_f32_e32 v56, v56, v57
	v_fmac_f32_e32 v54, v48, v48
	v_fmac_f32_e32 v55, v50, v50
	v_add_f32_e32 v57, v54, v55
	v_cvt_pk_bf16_f32 v54, v48, v49
	v_cvt_pk_bf16_f32 v55, v50, v51
	v_add_f32_e32 v50, v76, v56
	v_add_f32_e32 v56, v50, v57
	ds_bpermute_b32 v57, v124, v56
	v_lshl_add_u64 v[48:49], s[70:71], 1, v[82:83]
	v_lshl_add_u64 v[48:49], v[48:49], 0, s[8:9]
	v_lshl_add_u64 v[48:49], v[48:49], 0, v[132:133]
	v_mov_b32_e32 v143, v133
	v_lshl_add_u64 v[50:51], v[48:49], 0, v[142:143]
	s_waitcnt lgkmcnt(0)
	v_add_f32_e32 v48, v56, v57
	ds_bpermute_b32 v49, v125, v48
	v_permlane16_swap_b32_e32 v60, v62
	v_permlane16_swap_b32_e32 v61, v63
	v_permlane16_swap_b32_e32 v52, v54
	v_permlane16_swap_b32_e32 v53, v55
	global_store_dwordx4 v[50:51], v[60:63], off
	global_store_dwordx4 v[50:51], v[52:55], off offset:256
	s_and_saveexec_b64 s[68:69], s[4:5]
	s_cbranch_execz .LBB0_446
	s_waitcnt lgkmcnt(0)
	v_add_f32_e32 v48, v48, v49
	v_mul_f32_e32 v48, 0x4f800000, v48
	v_trunc_f32_e32 v48, v48
	v_mul_f32_e32 v49, 0x2f800000, v48
	v_floor_f32_e32 v49, v49
	v_fmac_f32_e32 v48, 0xcf800000, v49
	v_cvt_u32_f32_e32 v48, v48
	v_cvt_u32_f32_e32 v49, v49
	v_lshl_add_u64 v[50:51], v[80:81], 3, s[12:13]
	global_atomic_add_x2 v[50:51], v[48:49], off
; __device__ __forceinline__ unsigned cvt_pk_bf16(float lo, float hi) { unsigned r; asm volatile("v_cvt_pk_bf16_f32 %0, %1, %2" : "=v"(r) : "v"(lo), "v"(hi)); return r; }
;     __device__ __forceinline__ void operator()(const f32x4 (&acc)[2][2][4][2], const Unit& u, int wr, int wc, int fr, int fq, PG8_LAS unsigned char*) const {
;     ...
;         for (int ri = 0; ri < 8; ++ri) {
;             const int ai = ri >> 2, m = ri & 3;
;             const int row = u.pm * BM + ai * HALF + wr * 64 + m * 16 + fr; float ss = 0.f;
;             if (ri < 7) { const int ai2 = (ri + 1) >> 2, m2 = (ri + 1) & 3; const size_t off2 = (size_t)(u.pm * BM + ai2 * HALF + wr * 64 + m2 * 16 + fr) * 1024 + col0;
; #pragma unroll
;                 for (int bj = 0; bj < 2; ++bj)
; #pragma unroll
;                     for (int n = 0; n < 2; ++n) nxt[bj][n] = *(const u32x2*)(xb + off2 + bj * HALF + n * 16); }
; #pragma unroll
;             for (int bj = 0; bj < 2; ++bj)
; #pragma unroll
;                 for (int n = 0; n < 2; ++n) { const u32x2 bb = cur[bj][n]; const f32x4 av = acc[ai][bj][m][n];
;                     const float o0 = __uint_as_float(bb.x << 16) + av[0], o1 = __uint_as_float(bb.x & 0xffff0000u) + av[1], o2 = __uint_as_float(bb.y << 16) + av[2], o3 = __uint_as_float(bb.y & 0xffff0000u) + av[3];
;                     ss += (o0 * o0 + o1 * o1) + (o2 * o2 + o3 * o3);
;                     cur[bj][n].x = cvt_pk_bf16(o0, o1); cur[bj][n].y = cvt_pk_bf16(o2, o3); }
; #pragma unroll
;             for (int bj = 0; bj < 2; ++bj) { unsigned a0 = cur[bj][0].x, a1 = cur[bj][0].y, b0 = cur[bj][1].x, b1 = cur[bj][1].y;
;                 { auto r = __builtin_amdgcn_permlane16_swap(a0, b0, false, false); a0 = r[0]; b0 = r[1]; }
;                 { auto r = __builtin_amdgcn_permlane16_swap(a1, b1, false, false); a1 = r[0]; b1 = r[1]; }
;                 u32x4 w; w.x = a0; w.y = a1; w.z = b0; w.w = b1; *(u32x4*)(xb + (size_t)row * 1024 + u.pn * BM + wc * 32 + bj * HALF + ((fq & 1) << 4) + ((fq >> 1) << 3)) = w; }
;             ss += __shfl_xor(ss, 16); ss += __shfl_xor(ss, 32);
;             if (fq == 0) atomicAdd(rss_next + row, (unsigned long long)(ss * 4294967296.0f));
.LBB0_446:
	s_or_b64 exec, exec, s[68:69]
	v_or_b32_e32 v48, 32, v80
	s_waitcnt lgkmcnt(0)
	v_ashrrev_i32_e32 v49, 31, v48
	v_lshlrev_b64 v[50:51], 11, v[48:49]
	v_lshl_add_u64 v[50:51], s[26:27], 0, v[50:51]
	v_lshl_add_u64 v[52:53], v[144:145], 1, v[50:51]
	s_waitcnt vmcnt(18)
	v_mov_b64_e32 v[74:75], v[210:211]
	v_mov_b64_e32 v[72:73], v[212:213]
	v_mov_b64_e32 v[70:71], v[216:217]
	v_mov_b64_e32 v[68:69], v[218:219]
	v_lshlrev_b32_e32 v60, 16, v74
	v_add_f32_e32 v44, v44, v60
	v_and_b32_e32 v60, 0xffff0000, v74
	v_add_f32_e32 v45, v45, v60
	v_lshlrev_b32_e32 v60, 16, v75
	v_add_f32_e32 v46, v46, v60
	v_and_b32_e32 v60, 0xffff0000, v75
	v_add_f32_e32 v47, v47, v60
	v_mul_f32_e32 v60, v45, v45
	v_mul_f32_e32 v61, v47, v47
	v_fmac_f32_e32 v60, v44, v44
	v_fmac_f32_e32 v61, v46, v46
	v_cvt_pk_bf16_f32 v44, v44, v45
	v_cvt_pk_bf16_f32 v45, v46, v47
	v_lshlrev_b32_e32 v46, 16, v72
	v_add_f32_e32 v40, v40, v46
	v_and_b32_e32 v46, 0xffff0000, v72
	v_add_f32_e32 v41, v41, v46
	v_lshlrev_b32_e32 v46, 16, v73
	v_add_f32_e32 v42, v42, v46
	v_and_b32_e32 v46, 0xffff0000, v73
	v_add_f32_e32 v43, v43, v46
	v_mul_f32_e32 v46, v41, v41
	v_mul_f32_e32 v47, v43, v43
	v_fmac_f32_e32 v46, v40, v40
	v_fmac_f32_e32 v47, v42, v42
	v_add_f32_e32 v60, v60, v61
	v_add_f32_e32 v46, v46, v47
	v_add_f32_e32 v60, v60, v46
	v_cvt_pk_bf16_f32 v46, v40, v41
	v_lshlrev_b32_e32 v40, 16, v70
	v_add_f32_e32 v36, v36, v40
	v_and_b32_e32 v40, 0xffff0000, v70
	v_add_f32_e32 v37, v37, v40
	v_lshlrev_b32_e32 v40, 16, v71
	v_add_f32_e32 v38, v38, v40
	v_and_b32_e32 v40, 0xffff0000, v71
	v_add_f32_e32 v39, v39, v40
	v_mul_f32_e32 v40, v37, v37
	v_mul_f32_e32 v41, v39, v39
	v_cvt_pk_bf16_f32 v47, v42, v43
	v_fmac_f32_e32 v40, v36, v36
	v_fmac_f32_e32 v41, v38, v38
	v_cvt_pk_bf16_f32 v36, v36, v37
	v_cvt_pk_bf16_f32 v37, v38, v39
	v_lshlrev_b32_e32 v38, 16, v68
	v_add_f32_e32 v32, v32, v38
	v_and_b32_e32 v38, 0xffff0000, v68
	v_add_f32_e32 v33, v33, v38
	v_lshlrev_b32_e32 v38, 16, v69
	v_add_f32_e32 v34, v34, v38
	v_and_b32_e32 v38, 0xffff0000, v69
	v_add_f32_e32 v35, v35, v38
	v_mul_f32_e32 v38, v33, v33
	v_mul_f32_e32 v39, v35, v35
	v_add_f32_e32 v40, v40, v41
	v_fmac_f32_e32 v38, v32, v32
	v_fmac_f32_e32 v39, v34, v34
	v_add_f32_e32 v41, v38, v39
	v_cvt_pk_bf16_f32 v38, v32, v33
	v_cvt_pk_bf16_f32 v39, v34, v35
	v_add_f32_e32 v34, v60, v40
	v_add_f32_e32 v40, v34, v41
	ds_bpermute_b32 v41, v124, v40
	v_lshl_add_u64 v[32:33], s[70:71], 1, v[66:67]
	v_lshl_add_u64 v[32:33], v[32:33], 0, s[8:9]
	v_lshl_add_u64 v[32:33], v[32:33], 0, v[132:133]
	v_lshl_add_u64 v[34:35], v[32:33], 0, v[142:143]
	s_waitcnt lgkmcnt(0)
	v_add_f32_e32 v32, v40, v41
	ds_bpermute_b32 v33, v125, v32
	v_permlane16_swap_b32_e32 v44, v46
	v_permlane16_swap_b32_e32 v45, v47
	v_permlane16_swap_b32_e32 v36, v38
	v_permlane16_swap_b32_e32 v37, v39
	global_store_dwordx4 v[34:35], v[44:47], off
	global_store_dwordx4 v[34:35], v[36:39], off offset:256
	s_and_saveexec_b64 s[68:69], s[4:5]
	s_cbranch_execz .LBB0_448
	s_waitcnt lgkmcnt(0)
	v_add_f32_e32 v32, v32, v33
	v_mul_f32_e32 v32, 0x4f800000, v32
	v_trunc_f32_e32 v32, v32
	v_mul_f32_e32 v33, 0x2f800000, v32
	v_floor_f32_e32 v33, v33
	v_fmac_f32_e32 v32, 0xcf800000, v33
	v_cvt_u32_f32_e32 v32, v32
	v_cvt_u32_f32_e32 v33, v33
	v_lshl_add_u64 v[34:35], v[64:65], 3, s[12:13]
	global_atomic_add_x2 v[34:35], v[32:33], off
; __device__ __forceinline__ unsigned cvt_pk_bf16(float lo, float hi) { unsigned r; asm volatile("v_cvt_pk_bf16_f32 %0, %1, %2" : "=v"(r) : "v"(lo), "v"(hi)); return r; }
;     __device__ __forceinline__ void operator()(const f32x4 (&acc)[2][2][4][2], const Unit& u, int wr, int wc, int fr, int fq, PG8_LAS unsigned char*) const {
;     ...
;         for (int ri = 0; ri < 8; ++ri) {
;             const int ai = ri >> 2, m = ri & 3;
;             const int row = u.pm * BM + ai * HALF + wr * 64 + m * 16 + fr; float ss = 0.f;
;             if (ri < 7) { const int ai2 = (ri + 1) >> 2, m2 = (ri + 1) & 3; const size_t off2 = (size_t)(u.pm * BM + ai2 * HALF + wr * 64 + m2 * 16 + fr) * 1024 + col0;
; #pragma unroll
;                 for (int bj = 0; bj < 2; ++bj)
; #pragma unroll
;                     for (int n = 0; n < 2; ++n) nxt[bj][n] = *(const u32x2*)(xb + off2 + bj * HALF + n * 16); }
; #pragma unroll
;             for (int bj = 0; bj < 2; ++bj)
; #pragma unroll
;                 for (int n = 0; n < 2; ++n) { const u32x2 bb = cur[bj][n]; const f32x4 av = acc[ai][bj][m][n];
;                     const float o0 = __uint_as_float(bb.x << 16) + av[0], o1 = __uint_as_float(bb.x & 0xffff0000u) + av[1], o2 = __uint_as_float(bb.y << 16) + av[2], o3 = __uint_as_float(bb.y & 0xffff0000u) + av[3];
;                     ss += (o0 * o0 + o1 * o1) + (o2 * o2 + o3 * o3);
;                     cur[bj][n].x = cvt_pk_bf16(o0, o1); cur[bj][n].y = cvt_pk_bf16(o2, o3); }
; #pragma unroll
;             for (int bj = 0; bj < 2; ++bj) { unsigned a0 = cur[bj][0].x, a1 = cur[bj][0].y, b0 = cur[bj][1].x, b1 = cur[bj][1].y;
;                 { auto r = __builtin_amdgcn_permlane16_swap(a0, b0, false, false); a0 = r[0]; b0 = r[1]; }
;                 { auto r = __builtin_amdgcn_permlane16_swap(a1, b1, false, false); a1 = r[0]; b1 = r[1]; }
;                 u32x4 w; w.x = a0; w.y = a1; w.z = b0; w.w = b1; *(u32x4*)(xb + (size_t)row * 1024 + u.pn * BM + wc * 32 + bj * HALF + ((fq & 1) << 4) + ((fq >> 1) << 3)) = w; }
;             ss += __shfl_xor(ss, 16); ss += __shfl_xor(ss, 32);
;             if (fq == 0) atomicAdd(rss_next + row, (unsigned long long)(ss * 4294967296.0f));
.LBB0_448:
	s_or_b64 exec, exec, s[68:69]
	v_or_b32_e32 v32, 48, v80
	s_waitcnt lgkmcnt(0)
	v_ashrrev_i32_e32 v33, 31, v32
	v_lshlrev_b64 v[34:35], 11, v[32:33]
	v_lshl_add_u64 v[34:35], s[26:27], 0, v[34:35]
	v_lshl_add_u64 v[36:37], v[144:145], 1, v[34:35]
	s_waitcnt vmcnt(16)
	v_mov_b64_e32 v[58:59], v[220:221]
	v_mov_b64_e32 v[56:57], v[222:223]
	v_mov_b64_e32 v[54:55], v[224:225]
	v_mov_b64_e32 v[52:53], v[226:227]
	v_lshlrev_b32_e32 v44, 16, v58
	v_add_f32_e32 v28, v28, v44
	v_and_b32_e32 v44, 0xffff0000, v58
	v_add_f32_e32 v29, v29, v44
	v_lshlrev_b32_e32 v44, 16, v59
	v_add_f32_e32 v30, v30, v44
	v_and_b32_e32 v44, 0xffff0000, v59
	v_add_f32_e32 v31, v31, v44
	v_mul_f32_e32 v44, v29, v29
	v_mul_f32_e32 v45, v31, v31
	v_fmac_f32_e32 v44, v28, v28
	v_fmac_f32_e32 v45, v30, v30
	v_cvt_pk_bf16_f32 v28, v28, v29
	v_cvt_pk_bf16_f32 v29, v30, v31
	v_lshlrev_b32_e32 v30, 16, v56
	v_add_f32_e32 v24, v24, v30
	v_and_b32_e32 v30, 0xffff0000, v56
	v_add_f32_e32 v25, v25, v30
	v_lshlrev_b32_e32 v30, 16, v57
	v_add_f32_e32 v26, v26, v30
	v_and_b32_e32 v30, 0xffff0000, v57
	v_add_f32_e32 v27, v27, v30
	v_mul_f32_e32 v30, v25, v25
	v_mul_f32_e32 v31, v27, v27
	v_fmac_f32_e32 v30, v24, v24
	v_fmac_f32_e32 v31, v26, v26
	v_add_f32_e32 v44, v44, v45
	v_add_f32_e32 v30, v30, v31
	v_add_f32_e32 v44, v44, v30
	v_cvt_pk_bf16_f32 v30, v24, v25
	v_lshlrev_b32_e32 v24, 16, v54
	v_add_f32_e32 v20, v20, v24
	v_and_b32_e32 v24, 0xffff0000, v54
	v_add_f32_e32 v21, v21, v24
	v_lshlrev_b32_e32 v24, 16, v55
	v_add_f32_e32 v22, v22, v24
	v_and_b32_e32 v24, 0xffff0000, v55
	v_add_f32_e32 v23, v23, v24
	v_mul_f32_e32 v24, v21, v21
	v_mul_f32_e32 v25, v23, v23
	v_cvt_pk_bf16_f32 v31, v26, v27
	v_fmac_f32_e32 v24, v20, v20
	v_fmac_f32_e32 v25, v22, v22
	v_cvt_pk_bf16_f32 v20, v20, v21
	v_cvt_pk_bf16_f32 v21, v22, v23
	v_lshlrev_b32_e32 v22, 16, v52
	v_add_f32_e32 v16, v16, v22
	v_and_b32_e32 v22, 0xffff0000, v52
	v_add_f32_e32 v17, v17, v22
	v_lshlrev_b32_e32 v22, 16, v53
	v_add_f32_e32 v18, v18, v22
	v_and_b32_e32 v22, 0xffff0000, v53
	v_add_f32_e32 v19, v19, v22
	v_mul_f32_e32 v22, v17, v17
	v_mul_f32_e32 v23, v19, v19
	v_add_f32_e32 v24, v24, v25
	v_fmac_f32_e32 v22, v16, v16
	v_fmac_f32_e32 v23, v18, v18
	v_add_f32_e32 v25, v22, v23
	v_cvt_pk_bf16_f32 v22, v16, v17
	v_cvt_pk_bf16_f32 v23, v18, v19
	v_add_f32_e32 v18, v44, v24
	v_add_f32_e32 v24, v18, v25
	ds_bpermute_b32 v25, v124, v24
	v_lshl_add_u64 v[16:17], s[70:71], 1, v[50:51]
	v_lshl_add_u64 v[16:17], v[16:17], 0, s[8:9]
	v_lshl_add_u64 v[16:17], v[16:17], 0, v[132:133]
	v_mov_b32_e32 v143, v133
	v_lshl_add_u64 v[18:19], v[16:17], 0, v[142:143]
	s_waitcnt lgkmcnt(0)
	v_add_f32_e32 v16, v24, v25
	ds_bpermute_b32 v17, v125, v16
	v_permlane16_swap_b32_e32 v28, v30
	v_permlane16_swap_b32_e32 v29, v31
	v_permlane16_swap_b32_e32 v20, v22
	v_permlane16_swap_b32_e32 v21, v23
	global_store_dwordx4 v[18:19], v[28:31], off
	global_store_dwordx4 v[18:19], v[20:23], off offset:256
	s_and_saveexec_b64 s[68:69], s[4:5]
	s_cbranch_execz .LBB0_450
	s_waitcnt lgkmcnt(0)
	v_add_f32_e32 v16, v16, v17
	v_mul_f32_e32 v16, 0x4f800000, v16
	v_trunc_f32_e32 v16, v16
	v_mul_f32_e32 v17, 0x2f800000, v16
	v_floor_f32_e32 v17, v17
	v_fmac_f32_e32 v16, 0xcf800000, v17
	v_cvt_u32_f32_e32 v16, v16
	v_cvt_u32_f32_e32 v17, v17
	v_lshl_add_u64 v[18:19], v[48:49], 3, s[12:13]
	global_atomic_add_x2 v[18:19], v[16:17], off
.LBB0_450:
	s_or_b64 exec, exec, s[68:69]
	s_waitcnt vmcnt(14)
	v_mov_b64_e32 v[42:43], v[228:229]
	v_mov_b64_e32 v[40:41], v[230:231]
	v_mov_b64_e32 v[38:39], v[232:233]
	v_mov_b64_e32 v[36:37], v[234:235]
	v_lshlrev_b32_e32 v16, 16, v42
	v_add_f32_e32 v12, v12, v16
	v_and_b32_e32 v16, 0xffff0000, v42
	v_add_f32_e32 v13, v13, v16
	v_lshlrev_b32_e32 v16, 16, v43
	v_add_f32_e32 v14, v14, v16
	v_and_b32_e32 v16, 0xffff0000, v43
	v_add_f32_e32 v15, v15, v16
	v_mul_f32_e32 v16, v13, v13
	s_waitcnt lgkmcnt(0)
	v_mul_f32_e32 v17, v15, v15
	v_fmac_f32_e32 v16, v12, v12
	v_fmac_f32_e32 v17, v14, v14
	v_cvt_pk_bf16_f32 v12, v12, v13
	v_cvt_pk_bf16_f32 v13, v14, v15
	v_lshlrev_b32_e32 v14, 16, v40
	v_add_f32_e32 v8, v8, v14
	v_and_b32_e32 v14, 0xffff0000, v40
	v_add_f32_e32 v9, v9, v14
	v_lshlrev_b32_e32 v14, 16, v41
	v_add_f32_e32 v10, v10, v14
	v_and_b32_e32 v14, 0xffff0000, v41
	v_add_f32_e32 v11, v11, v14
	v_mul_f32_e32 v14, v9, v9
	v_mul_f32_e32 v15, v11, v11
	v_fmac_f32_e32 v14, v8, v8
	v_fmac_f32_e32 v15, v10, v10
	v_add_f32_e32 v16, v16, v17
	v_add_f32_e32 v14, v14, v15
	v_add_f32_e32 v16, v16, v14
	v_cvt_pk_bf16_f32 v14, v8, v9
	v_lshlrev_b32_e32 v8, 16, v38
	v_add_f32_e32 v4, v4, v8
	v_and_b32_e32 v8, 0xffff0000, v38
	v_add_f32_e32 v5, v5, v8
	v_lshlrev_b32_e32 v8, 16, v39
	v_add_f32_e32 v6, v6, v8
	v_and_b32_e32 v8, 0xffff0000, v39
	v_add_f32_e32 v7, v7, v8
	v_mul_f32_e32 v8, v5, v5
	v_mul_f32_e32 v9, v7, v7
	v_cvt_pk_bf16_f32 v15, v10, v11
	v_fmac_f32_e32 v8, v4, v4
	v_fmac_f32_e32 v9, v6, v6
	v_cvt_pk_bf16_f32 v4, v4, v5
	v_cvt_pk_bf16_f32 v5, v6, v7
	v_lshlrev_b32_e32 v6, 16, v36
	v_add_f32_e32 v0, v0, v6
	v_and_b32_e32 v6, 0xffff0000, v36
	v_add_f32_e32 v1, v1, v6
	v_lshlrev_b32_e32 v6, 16, v37
	v_add_f32_e32 v2, v2, v6
	v_and_b32_e32 v6, 0xffff0000, v37
	v_add_f32_e32 v3, v3, v6
	v_mul_f32_e32 v6, v1, v1
	v_mul_f32_e32 v7, v3, v3
	v_add_f32_e32 v8, v8, v9
	v_fmac_f32_e32 v6, v0, v0
	v_fmac_f32_e32 v7, v2, v2
	v_add_f32_e32 v9, v6, v7
	v_cvt_pk_bf16_f32 v6, v0, v1
	v_cvt_pk_bf16_f32 v7, v2, v3
	v_add_f32_e32 v2, v16, v8
	v_add_f32_e32 v8, v2, v9
	ds_bpermute_b32 v9, v124, v8
	v_lshl_add_u64 v[0:1], s[70:71], 1, v[34:35]
	v_lshl_add_u64 v[0:1], v[0:1], 0, s[8:9]
	v_lshl_add_u64 v[0:1], v[0:1], 0, v[132:133]
	v_lshl_add_u64 v[2:3], v[0:1], 0, v[142:143]
	s_waitcnt lgkmcnt(0)
	v_add_f32_e32 v0, v8, v9
	ds_bpermute_b32 v1, v125, v0
	v_permlane16_swap_b32_e32 v12, v14
	v_permlane16_swap_b32_e32 v13, v15
	v_permlane16_swap_b32_e32 v4, v6
	v_permlane16_swap_b32_e32 v5, v7
	global_store_dwordx4 v[2:3], v[12:15], off
	global_store_dwordx4 v[2:3], v[4:7], off offset:256
	s_and_saveexec_b64 s[68:69], s[4:5]
	s_cbranch_execz .LBB0_452
	s_waitcnt lgkmcnt(0)
	v_add_f32_e32 v0, v0, v1
	v_mul_f32_e32 v0, 0x4f800000, v0
	v_trunc_f32_e32 v0, v0
	v_mul_f32_e32 v1, 0x2f800000, v0
	v_floor_f32_e32 v1, v1
	v_fmac_f32_e32 v0, 0xcf800000, v1
	v_cvt_u32_f32_e32 v0, v0
	v_cvt_u32_f32_e32 v1, v1
	v_lshl_add_u64 v[2:3], v[32:33], 3, s[12:13]
	global_atomic_add_x2 v[2:3], v[0:1], off

;     __device__ __forceinline__ void operator()(const f32x4 (&acc)[2][2][4][2], const Unit& u, int wr, int wc, int fr, int fq, PG8_LAS unsigned char*) const {
;         const int col0 = u.pn * BM + wc * 32 + 4 * fq;
;         u32x2 cur[2][2], nxt[2][2];
;         { const size_t off = (size_t)(u.pm * BM + wr * 64 + fr) * 1024 + col0;
; #pragma unroll
;           for (int bj = 0; bj < 2; ++bj)
; #pragma unroll
;             for (int n = 0; n < 2; ++n) cur[bj][n] = *(const u32x2*)(xb + off + bj * HALF + n * 16); }
; #pragma unroll
;         for (int ri = 0; ri < 8; ++ri) {
;             const int ai = ri >> 2, m = ri & 3;
;             const int row = u.pm * BM + ai * HALF + wr * 64 + m * 16 + fr; float ss = 0.f;
;             if (ri < 7) { const int ai2 = (ri + 1) >> 2, m2 = (ri + 1) & 3; const size_t off2 = (size_t)(u.pm * BM + ai2 * HALF + wr * 64 + m2 * 16 + fr) * 1024 + col0;
; #pragma unroll
;                 for (int bj = 0; bj < 2; ++bj)
; #pragma unroll
;                     for (int n = 0; n < 2; ++n) nxt[bj][n] = *(const u32x2*)(xb + off2 + bj * HALF + n * 16); }
; #pragma unroll
;             for (int bj = 0; bj < 2; ++bj)
; #pragma unroll
;                 for (int n = 0; n < 2; ++n) { const u32x2 bb = cur[bj][n]; const f32x4 av = acc[ai][bj][m][n];
;                     const float o0 = __uint_as_float(bb.x << 16) + av[0], o1 = __uint_as_float(bb.x & 0xffff0000u) + av[1], o2 = __uint_as_float(bb.y << 16) + av[2], o3 = __uint_as_float(bb.y & 0xffff0000u) + av[3];
;                     ss += (o0 * o0 + o1 * o1) + (o2 * o2 + o3 * o3);
;                     cur[bj][n].x = cvt_pk_bf16(o0, o1); cur[bj][n].y = cvt_pk_bf16(o2, o3); }
; #pragma unroll
;             for (int bj = 0; bj < 2; ++bj) { unsigned a0 = cur[bj][0].x, a1 = cur[bj][0].y, b0 = cur[bj][1].x, b1 = cur[bj][1].y;
;                 { auto r = __builtin_amdgcn_permlane16_swap(a0, b0, false, false); a0 = r[0]; b0 = r[1]; }
;                 { auto r = __builtin_amdgcn_permlane16_swap(a1, b1, false, false); a1 = r[0]; b1 = r[1]; }
;                 u32x4 w; w.x = a0; w.y = a1; w.z = b0; w.w = b1; *(u32x4*)(xb + (size_t)row * 1024 + u.pn * BM + wc * 32 + bj * HALF + ((fq & 1) << 4) + ((fq >> 1) << 3)) = w; }
;             ss += __shfl_xor(ss, 16); ss += __shfl_xor(ss, 32);
;             if (fq == 0) atomicAdd(rss_next + row, (unsigned long long)(ss * 4294967296.0f));
.LBB0_602:
	s_lshl_b32 s64, s72, 8
	v_lshl_add_u32 v146, s63, 8, v160
	v_or_b32_e32 v144, s64, v162
	v_ashrrev_i32_e32 v147, 31, v146
	v_ashrrev_i32_e32 v145, 31, v144
	v_lshlrev_b64 v[148:149], 11, v[146:147]
	v_lshl_add_u64 v[152:153], s[26:27], 0, v[148:149]
	v_lshlrev_b64 v[154:155], 1, v[144:145]
	v_lshl_add_u64 v[148:149], v[152:153], 0, v[154:155]
	global_load_dwordx2 v[168:169], v[148:149], off
	global_load_dwordx2 v[170:171], v[148:149], off offset:32
	global_load_dwordx2 v[172:173], v[148:149], off offset:256
	global_load_dwordx2 v[174:175], v[148:149], off offset:288
	v_or_b32_e32 v148, 16, v146
	v_ashrrev_i32_e32 v149, 31, v148
	v_lshlrev_b64 v[150:151], 11, v[148:149]
	s_ashr_i32 s65, s64, 31
	v_lshl_add_u64 v[150:151], s[26:27], 0, v[150:151]
	v_lshl_add_u64 v[152:153], s[64:65], 1, v[152:153]
	v_lshl_add_u64 v[176:177], v[150:151], 0, v[154:155]
	v_lshl_add_u64 v[178:179], v[152:153], 0, s[10:11]
	global_load_dwordx2 v[158:159], v[176:177], off
	global_load_dwordx2 v[156:157], v[176:177], off offset:32
	global_load_dwordx2 v[154:155], v[176:177], off offset:256
	global_load_dwordx2 v[152:153], v[176:177], off offset:288
	s_mov_b64 s[98:99], 0x8000
	v_lshl_add_u64 v[252:253], v[176:177], 0, s[98:99]
	global_load_dwordx2 v[186:187], v[252:253], off
	global_load_dwordx2 v[188:189], v[252:253], off offset:32
	global_load_dwordx2 v[190:191], v[252:253], off offset:256
	global_load_dwordx2 v[192:193], v[252:253], off offset:288
	s_mov_b64 s[98:99], 0x10000
	v_lshl_add_u64 v[252:253], v[176:177], 0, s[98:99]
	global_load_dwordx2 v[194:195], v[252:253], off
	global_load_dwordx2 v[196:197], v[252:253], off offset:32
	global_load_dwordx2 v[198:199], v[252:253], off offset:256
	global_load_dwordx2 v[200:201], v[252:253], off offset:288
	s_mov_b64 s[98:99], 0x38000
	v_lshl_add_u64 v[252:253], v[176:177], 0, s[98:99]
	global_load_dwordx2 v[202:203], v[252:253], off
	global_load_dwordx2 v[204:205], v[252:253], off offset:32
	global_load_dwordx2 v[206:207], v[252:253], off offset:256
	global_load_dwordx2 v[208:209], v[252:253], off offset:288
	s_mov_b64 s[98:99], 0x40000
	v_lshl_add_u64 v[252:253], v[176:177], 0, s[98:99]
	global_load_dwordx2 v[210:211], v[252:253], off
	global_load_dwordx2 v[212:213], v[252:253], off offset:32
	global_load_dwordx2 v[216:217], v[252:253], off offset:256
	global_load_dwordx2 v[218:219], v[252:253], off offset:288
	s_mov_b64 s[98:99], 0x48000
	v_lshl_add_u64 v[252:253], v[176:177], 0, s[98:99]
	global_load_dwordx2 v[220:221], v[252:253], off
	global_load_dwordx2 v[222:223], v[252:253], off offset:32
	global_load_dwordx2 v[224:225], v[252:253], off offset:256
	global_load_dwordx2 v[226:227], v[252:253], off offset:288
	s_mov_b64 s[98:99], 0x50000
	v_lshl_add_u64 v[252:253], v[176:177], 0, s[98:99]
	global_load_dwordx2 v[228:229], v[252:253], off
	global_load_dwordx2 v[230:231], v[252:253], off offset:32
	global_load_dwordx2 v[232:233], v[252:253], off offset:256
	global_load_dwordx2 v[234:235], v[252:253], off offset:288
	v_xor_b32_e32 v143, 16, v166
	s_waitcnt vmcnt(24)
	v_lshlrev_b32_e32 v167, 16, v168
	v_and_b32_e32 v168, 0xffff0000, v168
	v_lshlrev_b32_e32 v176, 16, v169
	v_and_b32_e32 v169, 0xffff0000, v169
	v_lshlrev_b32_e32 v177, 16, v170
	v_and_b32_e32 v170, 0xffff0000, v170
	v_lshlrev_b32_e32 v180, 16, v171
	v_and_b32_e32 v171, 0xffff0000, v171
	v_lshlrev_b32_e32 v181, 16, v172
	v_and_b32_e32 v172, 0xffff0000, v172
	v_lshlrev_b32_e32 v182, 16, v173
	v_and_b32_e32 v173, 0xffff0000, v173
	v_lshlrev_b32_e32 v183, 16, v174
	v_and_b32_e32 v174, 0xffff0000, v174
	v_add_f32_e32 v125, v125, v168
	v_add_f32_e32 v127, v127, v169
	v_add_f32_e32 v121, v121, v170
	v_add_f32_e32 v123, v123, v171
	v_lshlrev_b32_e32 v184, 16, v175
	v_and_b32_e32 v175, 0xffff0000, v175
	v_add_f32_e32 v124, v124, v167
	v_add_f32_e32 v126, v126, v176
	v_add_f32_e32 v120, v120, v177
	v_add_f32_e32 v122, v122, v180
	v_add_f32_e32 v167, v116, v181
	v_add_f32_e32 v116, v117, v172
	v_add_f32_e32 v168, v118, v182
	v_add_f32_e32 v117, v119, v173
	v_add_f32_e32 v169, v112, v183
	v_add_f32_e32 v118, v113, v174
	v_mul_f32_e32 v171, v125, v125
	v_mul_f32_e32 v172, v127, v127
	v_cvt_pk_bf16_f32 v112, v124, v125
	v_cvt_pk_bf16_f32 v113, v126, v127
	v_mul_f32_e32 v125, v121, v121
	v_mul_f32_e32 v127, v123, v123
	v_add_f32_e32 v170, v114, v184
	v_add_f32_e32 v119, v115, v175
	v_cvt_pk_bf16_f32 v114, v120, v121
	v_cvt_pk_bf16_f32 v115, v122, v123
	v_mul_f32_e32 v121, v116, v116
	v_mul_f32_e32 v123, v117, v117
	v_fmac_f32_e32 v171, v124, v124
	v_fmac_f32_e32 v172, v126, v126
	v_fmac_f32_e32 v125, v120, v120
	v_fmac_f32_e32 v127, v122, v122
	v_mul_f32_e32 v173, v118, v118
	v_mul_f32_e32 v174, v119, v119
	v_fmac_f32_e32 v121, v167, v167
	v_fmac_f32_e32 v123, v168, v168
	v_add_f32_e32 v120, v171, v172
	v_add_f32_e32 v122, v125, v127
	v_fmac_f32_e32 v173, v169, v169
	v_fmac_f32_e32 v174, v170, v170
	v_add_f32_e32 v121, v121, v123
	v_add_f32_e32 v120, v120, v122
	v_add_f32_e32 v123, v173, v174
	v_add_f32_e32 v120, v120, v121
	v_add_f32_e32 v122, v120, v123
	v_and_b32_e32 v120, 64, v166
	v_add_u32_e32 v123, 64, v120
	v_cmp_lt_i32_e32 vcc, v143, v123
	v_permlane16_swap_b32_e32 v112, v114
	s_nop 0
	v_cndmask_b32_e32 v120, v166, v143, vcc
	v_lshlrev_b32_e32 v124, 2, v120
	ds_bpermute_b32 v125, v124, v122
	v_lshl_add_u64 v[120:121], v[178:179], 0, v[132:133]
	v_mov_b32_e32 v143, v133
	v_permlane16_swap_b32_e32 v113, v115
	v_lshl_add_u64 v[120:121], v[120:121], 0, v[142:143]
	v_cvt_pk_bf16_f32 v116, v167, v116
	v_cvt_pk_bf16_f32 v117, v168, v117
	v_cvt_pk_bf16_f32 v118, v169, v118
	v_cvt_pk_bf16_f32 v119, v170, v119
	global_store_dwordx4 v[120:121], v[112:115], off
	v_permlane16_swap_b32_e32 v116, v118
	s_nop 0
	v_xor_b32_e32 v113, 32, v166
	v_cmp_lt_i32_e32 vcc, v113, v123
	s_waitcnt lgkmcnt(0)
	v_add_f32_e32 v112, v122, v125
	v_permlane16_swap_b32_e32 v117, v119
	v_cndmask_b32_e32 v113, v166, v113, vcc
	v_lshlrev_b32_e32 v125, 2, v113
	ds_bpermute_b32 v113, v125, v112
	global_store_dwordx4 v[120:121], v[116:119], off offset:256
	s_and_saveexec_b64 s[66:67], s[4:5]
	s_cbranch_execz .LBB0_604
	s_waitcnt lgkmcnt(0)
	v_add_f32_e32 v112, v112, v113
	v_mul_f32_e32 v112, 0x4f800000, v112
	v_trunc_f32_e32 v112, v112
	v_mul_f32_e32 v113, 0x2f800000, v112
	v_floor_f32_e32 v113, v113
	v_fmac_f32_e32 v112, 0xcf800000, v113
	v_cvt_u32_f32_e32 v112, v112
	v_cvt_u32_f32_e32 v113, v113
	v_lshl_add_u64 v[114:115], v[146:147], 3, s[38:39]
	global_atomic_add_x2 v[114:115], v[112:113], off
; __device__ __forceinline__ unsigned cvt_pk_bf16(float lo, float hi) { unsigned r; asm volatile("v_cvt_pk_bf16_f32 %0, %1, %2" : "=v"(r) : "v"(lo), "v"(hi)); return r; }
;     __device__ __forceinline__ void operator()(const f32x4 (&acc)[2][2][4][2], const Unit& u, int wr, int wc, int fr, int fq, PG8_LAS unsigned char*) const {
;     ...
;         for (int ri = 0; ri < 8; ++ri) {
;             const int ai = ri >> 2, m = ri & 3;
;             const int row = u.pm * BM + ai * HALF + wr * 64 + m * 16 + fr; float ss = 0.f;
;             if (ri < 7) { const int ai2 = (ri + 1) >> 2, m2 = (ri + 1) & 3; const size_t off2 = (size_t)(u.pm * BM + ai2 * HALF + wr * 64 + m2 * 16 + fr) * 1024 + col0;
; #pragma unroll
;                 for (int bj = 0; bj < 2; ++bj)
; #pragma unroll
;                     for (int n = 0; n < 2; ++n) nxt[bj][n] = *(const u32x2*)(xb + off2 + bj * HALF + n * 16); }
; #pragma unroll
;             for (int bj = 0; bj < 2; ++bj)
; #pragma unroll
;                 for (int n = 0; n < 2; ++n) { const u32x2 bb = cur[bj][n]; const f32x4 av = acc[ai][bj][m][n];
;                     const float o0 = __uint_as_float(bb.x << 16) + av[0], o1 = __uint_as_float(bb.x & 0xffff0000u) + av[1], o2 = __uint_as_float(bb.y << 16) + av[2], o3 = __uint_as_float(bb.y & 0xffff0000u) + av[3];
;                     ss += (o0 * o0 + o1 * o1) + (o2 * o2 + o3 * o3);
;                     cur[bj][n].x = cvt_pk_bf16(o0, o1); cur[bj][n].y = cvt_pk_bf16(o2, o3); }
; #pragma unroll
;             for (int bj = 0; bj < 2; ++bj) { unsigned a0 = cur[bj][0].x, a1 = cur[bj][0].y, b0 = cur[bj][1].x, b1 = cur[bj][1].y;
;                 { auto r = __builtin_amdgcn_permlane16_swap(a0, b0, false, false); a0 = r[0]; b0 = r[1]; }
;                 { auto r = __builtin_amdgcn_permlane16_swap(a1, b1, false, false); a1 = r[0]; b1 = r[1]; }
;                 u32x4 w; w.x = a0; w.y = a1; w.z = b0; w.w = b1; *(u32x4*)(xb + (size_t)row * 1024 + u.pn * BM + wc * 32 + bj * HALF + ((fq & 1) << 4) + ((fq >> 1) << 3)) = w; }
;             ss += __shfl_xor(ss, 16); ss += __shfl_xor(ss, 32);
;             if (fq == 0) atomicAdd(rss_next + row, (unsigned long long)(ss * 4294967296.0f));
.LBB0_604:
	s_or_b64 exec, exec, s[66:67]
	v_or_b32_e32 v112, 32, v146
	s_waitcnt lgkmcnt(0)
	v_ashrrev_i32_e32 v113, 31, v112
	v_lshlrev_b64 v[114:115], 11, v[112:113]
	v_lshl_add_u64 v[114:115], s[26:27], 0, v[114:115]
	v_lshl_add_u64 v[116:117], v[144:145], 1, v[114:115]
	v_lshlrev_b32_e32 v126, 16, v158
	v_add_f32_e32 v108, v108, v126
	v_and_b32_e32 v126, 0xffff0000, v158
	v_add_f32_e32 v109, v109, v126
	v_lshlrev_b32_e32 v126, 16, v159
	v_add_f32_e32 v110, v110, v126
	v_and_b32_e32 v126, 0xffff0000, v159
	v_add_f32_e32 v111, v111, v126
	v_mul_f32_e32 v126, v109, v109
	v_mul_f32_e32 v127, v111, v111
	v_fmac_f32_e32 v126, v108, v108
	v_fmac_f32_e32 v127, v110, v110
	v_cvt_pk_bf16_f32 v108, v108, v109
	v_cvt_pk_bf16_f32 v109, v110, v111
	v_lshlrev_b32_e32 v110, 16, v156
	v_add_f32_e32 v104, v104, v110
	v_and_b32_e32 v110, 0xffff0000, v156
	v_add_f32_e32 v105, v105, v110
	v_lshlrev_b32_e32 v110, 16, v157
	v_add_f32_e32 v106, v106, v110
	v_and_b32_e32 v110, 0xffff0000, v157
	v_add_f32_e32 v107, v107, v110
	v_mul_f32_e32 v110, v105, v105
	v_mul_f32_e32 v111, v107, v107
	v_fmac_f32_e32 v110, v104, v104
	v_fmac_f32_e32 v111, v106, v106
	v_add_f32_e32 v126, v126, v127
	v_add_f32_e32 v110, v110, v111
	v_add_f32_e32 v126, v126, v110
	v_cvt_pk_bf16_f32 v110, v104, v105
	v_lshlrev_b32_e32 v104, 16, v154
	v_add_f32_e32 v100, v100, v104
	v_and_b32_e32 v104, 0xffff0000, v154
	v_add_f32_e32 v101, v101, v104
	v_lshlrev_b32_e32 v104, 16, v155
	v_add_f32_e32 v102, v102, v104
	v_and_b32_e32 v104, 0xffff0000, v155
	v_add_f32_e32 v103, v103, v104
	v_mul_f32_e32 v104, v101, v101
	v_mul_f32_e32 v105, v103, v103
	v_cvt_pk_bf16_f32 v111, v106, v107
	v_fmac_f32_e32 v104, v100, v100
	v_fmac_f32_e32 v105, v102, v102
	v_cvt_pk_bf16_f32 v100, v100, v101
	v_cvt_pk_bf16_f32 v101, v102, v103
	v_lshlrev_b32_e32 v102, 16, v152
	v_add_f32_e32 v96, v96, v102
	v_and_b32_e32 v102, 0xffff0000, v152
	v_add_f32_e32 v97, v97, v102
	v_lshlrev_b32_e32 v102, 16, v153
	v_add_f32_e32 v98, v98, v102
	v_and_b32_e32 v102, 0xffff0000, v153
	v_add_f32_e32 v99, v99, v102
	v_mul_f32_e32 v102, v97, v97
	v_mul_f32_e32 v103, v99, v99
	v_add_f32_e32 v104, v104, v105
	v_fmac_f32_e32 v102, v96, v96
	v_fmac_f32_e32 v103, v98, v98
	v_add_f32_e32 v105, v102, v103
	v_cvt_pk_bf16_f32 v102, v96, v97
	v_cvt_pk_bf16_f32 v103, v98, v99
	v_add_f32_e32 v98, v126, v104
	v_add_f32_e32 v104, v98, v105
	ds_bpermute_b32 v105, v124, v104
	v_lshl_add_u64 v[96:97], s[64:65], 1, v[150:151]
	v_lshl_add_u64 v[96:97], v[96:97], 0, s[10:11]
	v_lshl_add_u64 v[96:97], v[96:97], 0, v[132:133]
	v_lshl_add_u64 v[98:99], v[96:97], 0, v[142:143]
	s_waitcnt lgkmcnt(0)
	v_add_f32_e32 v96, v104, v105
	ds_bpermute_b32 v97, v125, v96
	v_permlane16_swap_b32_e32 v108, v110
	v_permlane16_swap_b32_e32 v109, v111
	v_permlane16_swap_b32_e32 v100, v102
	v_permlane16_swap_b32_e32 v101, v103
	global_store_dwordx4 v[98:99], v[108:111], off
	global_store_dwordx4 v[98:99], v[100:103], off offset:256
	s_and_saveexec_b64 s[66:67], s[4:5]
	s_cbranch_execz .LBB0_606
	s_waitcnt lgkmcnt(0)
	v_add_f32_e32 v96, v96, v97
	v_mul_f32_e32 v96, 0x4f800000, v96
	v_trunc_f32_e32 v96, v96
	v_mul_f32_e32 v97, 0x2f800000, v96
	v_floor_f32_e32 v97, v97
	v_fmac_f32_e32 v96, 0xcf800000, v97
	v_cvt_u32_f32_e32 v96, v96
	v_cvt_u32_f32_e32 v97, v97
	v_lshl_add_u64 v[98:99], v[148:149], 3, s[38:39]
	global_atomic_add_x2 v[98:99], v[96:97], off
.LBB0_606:
	s_or_b64 exec, exec, s[66:67]
	v_or_b32_e32 v96, 48, v146
	s_waitcnt lgkmcnt(0)
	v_ashrrev_i32_e32 v97, 31, v96
	v_lshlrev_b64 v[98:99], 11, v[96:97]
	v_lshl_add_u64 v[98:99], s[26:27], 0, v[98:99]
	v_lshl_add_u64 v[100:101], v[144:145], 1, v[98:99]
	s_waitcnt vmcnt(24)
	v_mov_b64_e32 v[122:123], v[186:187]
	v_mov_b64_e32 v[120:121], v[188:189]
	v_mov_b64_e32 v[118:119], v[190:191]
	v_mov_b64_e32 v[116:117], v[192:193]
	v_lshlrev_b32_e32 v108, 16, v122
	v_add_f32_e32 v92, v92, v108
	v_and_b32_e32 v108, 0xffff0000, v122
	v_add_f32_e32 v93, v93, v108
	v_lshlrev_b32_e32 v108, 16, v123
	v_add_f32_e32 v94, v94, v108
	v_and_b32_e32 v108, 0xffff0000, v123
	v_add_f32_e32 v95, v95, v108
	v_mul_f32_e32 v108, v93, v93
	v_mul_f32_e32 v109, v95, v95
	v_fmac_f32_e32 v108, v92, v92
	v_fmac_f32_e32 v109, v94, v94
	v_cvt_pk_bf16_f32 v92, v92, v93
	v_cvt_pk_bf16_f32 v93, v94, v95
	v_lshlrev_b32_e32 v94, 16, v120
	v_add_f32_e32 v88, v88, v94
	v_and_b32_e32 v94, 0xffff0000, v120
	v_add_f32_e32 v89, v89, v94
	v_lshlrev_b32_e32 v94, 16, v121
	v_add_f32_e32 v90, v90, v94
	v_and_b32_e32 v94, 0xffff0000, v121
	v_add_f32_e32 v91, v91, v94
	v_mul_f32_e32 v94, v89, v89
	v_mul_f32_e32 v95, v91, v91
	v_fmac_f32_e32 v94, v88, v88
	v_fmac_f32_e32 v95, v90, v90
	v_add_f32_e32 v108, v108, v109
	v_add_f32_e32 v94, v94, v95
	v_add_f32_e32 v108, v108, v94
	v_cvt_pk_bf16_f32 v94, v88, v89
	v_lshlrev_b32_e32 v88, 16, v118
	v_add_f32_e32 v84, v84, v88
	v_and_b32_e32 v88, 0xffff0000, v118
	v_add_f32_e32 v85, v85, v88
	v_lshlrev_b32_e32 v88, 16, v119
	v_add_f32_e32 v86, v86, v88
	v_and_b32_e32 v88, 0xffff0000, v119
	v_add_f32_e32 v87, v87, v88
	v_mul_f32_e32 v88, v85, v85
	v_mul_f32_e32 v89, v87, v87
	v_cvt_pk_bf16_f32 v95, v90, v91
	v_fmac_f32_e32 v88, v84, v84
	v_fmac_f32_e32 v89, v86, v86
	v_cvt_pk_bf16_f32 v84, v84, v85
	v_cvt_pk_bf16_f32 v85, v86, v87
	v_lshlrev_b32_e32 v86, 16, v116
	v_add_f32_e32 v80, v80, v86
	v_and_b32_e32 v86, 0xffff0000, v116
	v_add_f32_e32 v81, v81, v86
	v_lshlrev_b32_e32 v86, 16, v117
	v_add_f32_e32 v82, v82, v86
	v_and_b32_e32 v86, 0xffff0000, v117
	v_add_f32_e32 v83, v83, v86
	v_mul_f32_e32 v86, v81, v81
	v_mul_f32_e32 v87, v83, v83
	v_add_f32_e32 v88, v88, v89
	v_fmac_f32_e32 v86, v80, v80
	v_fmac_f32_e32 v87, v82, v82
	v_add_f32_e32 v89, v86, v87
	v_cvt_pk_bf16_f32 v86, v80, v81
	v_cvt_pk_bf16_f32 v87, v82, v83
	v_add_f32_e32 v82, v108, v88
	v_add_f32_e32 v88, v82, v89
	ds_bpermute_b32 v89, v124, v88
	v_lshl_add_u64 v[80:81], s[64:65], 1, v[114:115]
	v_lshl_add_u64 v[80:81], v[80:81], 0, s[10:11]
	v_lshl_add_u64 v[80:81], v[80:81], 0, v[132:133]
	v_mov_b32_e32 v143, v133
	v_lshl_add_u64 v[82:83], v[80:81], 0, v[142:143]
	s_waitcnt lgkmcnt(0)
	v_add_f32_e32 v80, v88, v89
	ds_bpermute_b32 v81, v125, v80
	v_permlane16_swap_b32_e32 v92, v94
	v_permlane16_swap_b32_e32 v93, v95
	v_permlane16_swap_b32_e32 v84, v86
	v_permlane16_swap_b32_e32 v85, v87
	global_store_dwordx4 v[82:83], v[92:95], off
	global_store_dwordx4 v[82:83], v[84:87], off offset:256
	s_and_saveexec_b64 s[66:67], s[4:5]
	s_cbranch_execz .LBB0_608
	s_waitcnt lgkmcnt(0)
	v_add_f32_e32 v80, v80, v81
	v_mul_f32_e32 v80, 0x4f800000, v80
	v_trunc_f32_e32 v80, v80
	v_mul_f32_e32 v81, 0x2f800000, v80
	v_floor_f32_e32 v81, v81
	v_fmac_f32_e32 v80, 0xcf800000, v81
	v_cvt_u32_f32_e32 v80, v80
	v_cvt_u32_f32_e32 v81, v81
	v_lshl_add_u64 v[82:83], v[112:113], 3, s[38:39]
	global_atomic_add_x2 v[82:83], v[80:81], off
; __device__ __forceinline__ unsigned cvt_pk_bf16(float lo, float hi) { unsigned r; asm volatile("v_cvt_pk_bf16_f32 %0, %1, %2" : "=v"(r) : "v"(lo), "v"(hi)); return r; }
;     __device__ __forceinline__ void operator()(const f32x4 (&acc)[2][2][4][2], const Unit& u, int wr, int wc, int fr, int fq, PG8_LAS unsigned char*) const {
;     ...
;         for (int ri = 0; ri < 8; ++ri) {
;             const int ai = ri >> 2, m = ri & 3;
;             const int row = u.pm * BM + ai * HALF + wr * 64 + m * 16 + fr; float ss = 0.f;
;             if (ri < 7) { const int ai2 = (ri + 1) >> 2, m2 = (ri + 1) & 3; const size_t off2 = (size_t)(u.pm * BM + ai2 * HALF + wr * 64 + m2 * 16 + fr) * 1024 + col0;
; #pragma unroll
;                 for (int bj = 0; bj < 2; ++bj)
; #pragma unroll
;                     for (int n = 0; n < 2; ++n) nxt[bj][n] = *(const u32x2*)(xb + off2 + bj * HALF + n * 16); }
; #pragma unroll
;             for (int bj = 0; bj < 2; ++bj)
; #pragma unroll
;                 for (int n = 0; n < 2; ++n) { const u32x2 bb = cur[bj][n]; const f32x4 av = acc[ai][bj][m][n];
;                     const float o0 = __uint_as_float(bb.x << 16) + av[0], o1 = __uint_as_float(bb.x & 0xffff0000u) + av[1], o2 = __uint_as_float(bb.y << 16) + av[2], o3 = __uint_as_float(bb.y & 0xffff0000u) + av[3];
;                     ss += (o0 * o0 + o1 * o1) + (o2 * o2 + o3 * o3);
;                     cur[bj][n].x = cvt_pk_bf16(o0, o1); cur[bj][n].y = cvt_pk_bf16(o2, o3); }
; #pragma unroll
;             for (int bj = 0; bj < 2; ++bj) { unsigned a0 = cur[bj][0].x, a1 = cur[bj][0].y, b0 = cur[bj][1].x, b1 = cur[bj][1].y;
;                 { auto r = __builtin_amdgcn_permlane16_swap(a0, b0, false, false); a0 = r[0]; b0 = r[1]; }
;                 { auto r = __builtin_amdgcn_permlane16_swap(a1, b1, false, false); a1 = r[0]; b1 = r[1]; }
;                 u32x4 w; w.x = a0; w.y = a1; w.z = b0; w.w = b1; *(u32x4*)(xb + (size_t)row * 1024 + u.pn * BM + wc * 32 + bj * HALF + ((fq & 1) << 4) + ((fq >> 1) << 3)) = w; }
;             ss += __shfl_xor(ss, 16); ss += __shfl_xor(ss, 32);
;             if (fq == 0) atomicAdd(rss_next + row, (unsigned long long)(ss * 4294967296.0f));
.LBB0_608:
	s_or_b64 exec, exec, s[66:67]
	v_add_u32_e32 v80, 0x80, v146
	s_waitcnt lgkmcnt(0)
	v_ashrrev_i32_e32 v81, 31, v80
	v_lshlrev_b64 v[82:83], 11, v[80:81]
	v_lshl_add_u64 v[82:83], s[26:27], 0, v[82:83]
	v_lshl_add_u64 v[84:85], v[144:145], 1, v[82:83]
	s_waitcnt vmcnt(22)
	v_mov_b64_e32 v[106:107], v[194:195]
	v_mov_b64_e32 v[104:105], v[196:197]
	v_mov_b64_e32 v[102:103], v[198:199]
	v_mov_b64_e32 v[100:101], v[200:201]
	v_lshlrev_b32_e32 v92, 16, v106
	v_add_f32_e32 v76, v76, v92
	v_and_b32_e32 v92, 0xffff0000, v106
	v_add_f32_e32 v77, v77, v92
	v_lshlrev_b32_e32 v92, 16, v107
	v_add_f32_e32 v78, v78, v92
	v_and_b32_e32 v92, 0xffff0000, v107
	v_add_f32_e32 v79, v79, v92
	v_mul_f32_e32 v92, v77, v77
	v_mul_f32_e32 v93, v79, v79
	v_fmac_f32_e32 v92, v76, v76
	v_fmac_f32_e32 v93, v78, v78
	v_cvt_pk_bf16_f32 v76, v76, v77
	v_cvt_pk_bf16_f32 v77, v78, v79
	v_lshlrev_b32_e32 v78, 16, v104
	v_add_f32_e32 v72, v72, v78
	v_and_b32_e32 v78, 0xffff0000, v104
	v_add_f32_e32 v73, v73, v78
	v_lshlrev_b32_e32 v78, 16, v105
	v_add_f32_e32 v74, v74, v78
	v_and_b32_e32 v78, 0xffff0000, v105
	v_add_f32_e32 v75, v75, v78
	v_mul_f32_e32 v78, v73, v73
	v_mul_f32_e32 v79, v75, v75
	v_fmac_f32_e32 v78, v72, v72
	v_fmac_f32_e32 v79, v74, v74
	v_add_f32_e32 v92, v92, v93
	v_add_f32_e32 v78, v78, v79
	v_add_f32_e32 v92, v92, v78
	v_cvt_pk_bf16_f32 v78, v72, v73
	v_lshlrev_b32_e32 v72, 16, v102
	v_add_f32_e32 v68, v68, v72
	v_and_b32_e32 v72, 0xffff0000, v102
	v_add_f32_e32 v69, v69, v72
	v_lshlrev_b32_e32 v72, 16, v103
	v_add_f32_e32 v70, v70, v72
	v_and_b32_e32 v72, 0xffff0000, v103
	v_add_f32_e32 v71, v71, v72
	v_mul_f32_e32 v72, v69, v69
	v_mul_f32_e32 v73, v71, v71
	v_cvt_pk_bf16_f32 v79, v74, v75
	v_fmac_f32_e32 v72, v68, v68
	v_fmac_f32_e32 v73, v70, v70
	v_cvt_pk_bf16_f32 v68, v68, v69
	v_cvt_pk_bf16_f32 v69, v70, v71
	v_lshlrev_b32_e32 v70, 16, v100
	v_add_f32_e32 v64, v64, v70
	v_and_b32_e32 v70, 0xffff0000, v100
	v_add_f32_e32 v65, v65, v70
	v_lshlrev_b32_e32 v70, 16, v101
	v_add_f32_e32 v66, v66, v70
	v_and_b32_e32 v70, 0xffff0000, v101
	v_add_f32_e32 v67, v67, v70
	v_mul_f32_e32 v70, v65, v65
	v_mul_f32_e32 v71, v67, v67
	v_add_f32_e32 v72, v72, v73
	v_fmac_f32_e32 v70, v64, v64
	v_fmac_f32_e32 v71, v66, v66
	v_add_f32_e32 v73, v70, v71
	v_cvt_pk_bf16_f32 v70, v64, v65
	v_cvt_pk_bf16_f32 v71, v66, v67
	v_add_f32_e32 v66, v92, v72
	v_add_f32_e32 v72, v66, v73
	ds_bpermute_b32 v73, v124, v72
	v_lshl_add_u64 v[64:65], s[64:65], 1, v[98:99]
	v_lshl_add_u64 v[64:65], v[64:65], 0, s[10:11]
	v_lshl_add_u64 v[64:65], v[64:65], 0, v[132:133]
	v_lshl_add_u64 v[66:67], v[64:65], 0, v[142:143]
	s_waitcnt lgkmcnt(0)
	v_add_f32_e32 v64, v72, v73
	ds_bpermute_b32 v65, v125, v64
	v_permlane16_swap_b32_e32 v76, v78
	v_permlane16_swap_b32_e32 v77, v79
	v_permlane16_swap_b32_e32 v68, v70
	v_permlane16_swap_b32_e32 v69, v71
	global_store_dwordx4 v[66:67], v[76:79], off
	global_store_dwordx4 v[66:67], v[68:71], off offset:256
	s_and_saveexec_b64 s[66:67], s[4:5]
	s_cbranch_execz .LBB0_610
	s_waitcnt lgkmcnt(0)
	v_add_f32_e32 v64, v64, v65
	v_mul_f32_e32 v64, 0x4f800000, v64
	v_trunc_f32_e32 v64, v64
	v_mul_f32_e32 v65, 0x2f800000, v64
	v_floor_f32_e32 v65, v65
	v_fmac_f32_e32 v64, 0xcf800000, v65
	v_cvt_u32_f32_e32 v64, v64
	v_cvt_u32_f32_e32 v65, v65
	v_lshl_add_u64 v[66:67], v[96:97], 3, s[38:39]
	global_atomic_add_x2 v[66:67], v[64:65], off
.LBB0_610:
	s_or_b64 exec, exec, s[66:67]
	v_or_b32_e32 v64, 16, v80
	s_waitcnt lgkmcnt(0)
	v_ashrrev_i32_e32 v65, 31, v64
	v_lshlrev_b64 v[66:67], 11, v[64:65]
	v_lshl_add_u64 v[66:67], s[26:27], 0, v[66:67]
	v_lshl_add_u64 v[68:69], v[144:145], 1, v[66:67]
	s_waitcnt vmcnt(20)
	v_mov_b64_e32 v[90:91], v[202:203]
	v_mov_b64_e32 v[88:89], v[204:205]
	v_mov_b64_e32 v[86:87], v[206:207]
	v_mov_b64_e32 v[84:85], v[208:209]
	v_lshlrev_b32_e32 v76, 16, v90
	v_add_f32_e32 v60, v60, v76
	v_and_b32_e32 v76, 0xffff0000, v90
	v_add_f32_e32 v61, v61, v76
	v_lshlrev_b32_e32 v76, 16, v91
	v_add_f32_e32 v62, v62, v76
	v_and_b32_e32 v76, 0xffff0000, v91
	v_add_f32_e32 v63, v63, v76
	v_mul_f32_e32 v76, v61, v61
	v_mul_f32_e32 v77, v63, v63
	v_fmac_f32_e32 v76, v60, v60
	v_fmac_f32_e32 v77, v62, v62
	v_cvt_pk_bf16_f32 v60, v60, v61
	v_cvt_pk_bf16_f32 v61, v62, v63
	v_lshlrev_b32_e32 v62, 16, v88
	v_add_f32_e32 v56, v56, v62
	v_and_b32_e32 v62, 0xffff0000, v88
	v_add_f32_e32 v57, v57, v62
	v_lshlrev_b32_e32 v62, 16, v89
	v_add_f32_e32 v58, v58, v62
	v_and_b32_e32 v62, 0xffff0000, v89
	v_add_f32_e32 v59, v59, v62
	v_mul_f32_e32 v62, v57, v57
	v_mul_f32_e32 v63, v59, v59
	v_fmac_f32_e32 v62, v56, v56
	v_fmac_f32_e32 v63, v58, v58
	v_add_f32_e32 v76, v76, v77
	v_add_f32_e32 v62, v62, v63
	v_add_f32_e32 v76, v76, v62
	v_cvt_pk_bf16_f32 v62, v56, v57
	v_lshlrev_b32_e32 v56, 16, v86
	v_add_f32_e32 v52, v52, v56
	v_and_b32_e32 v56, 0xffff0000, v86
	v_add_f32_e32 v53, v53, v56
	v_lshlrev_b32_e32 v56, 16, v87
	v_add_f32_e32 v54, v54, v56
	v_and_b32_e32 v56, 0xffff0000, v87
	v_add_f32_e32 v55, v55, v56
	v_mul_f32_e32 v56, v53, v53
	v_mul_f32_e32 v57, v55, v55
	v_cvt_pk_bf16_f32 v63, v58, v59
	v_fmac_f32_e32 v56, v52, v52
	v_fmac_f32_e32 v57, v54, v54
	v_cvt_pk_bf16_f32 v52, v52, v53
	v_cvt_pk_bf16_f32 v53, v54, v55
	v_lshlrev_b32_e32 v54, 16, v84
	v_add_f32_e32 v48, v48, v54
	v_and_b32_e32 v54, 0xffff0000, v84
	v_add_f32_e32 v49, v49, v54
	v_lshlrev_b32_e32 v54, 16, v85
	v_add_f32_e32 v50, v50, v54
	v_and_b32_e32 v54, 0xffff0000, v85
	v_add_f32_e32 v51, v51, v54
	v_mul_f32_e32 v54, v49, v49
	v_mul_f32_e32 v55, v51, v51
	v_add_f32_e32 v56, v56, v57
	v_fmac_f32_e32 v54, v48, v48
	v_fmac_f32_e32 v55, v50, v50
	v_add_f32_e32 v57, v54, v55
	v_cvt_pk_bf16_f32 v54, v48, v49
	v_cvt_pk_bf16_f32 v55, v50, v51
	v_add_f32_e32 v50, v76, v56
	v_add_f32_e32 v56, v50, v57
	ds_bpermute_b32 v57, v124, v56
	v_lshl_add_u64 v[48:49], s[64:65], 1, v[82:83]
	v_lshl_add_u64 v[48:49], v[48:49], 0, s[10:11]
	v_lshl_add_u64 v[48:49], v[48:49], 0, v[132:133]
	v_mov_b32_e32 v143, v133
	v_lshl_add_u64 v[50:51], v[48:49], 0, v[142:143]
	s_waitcnt lgkmcnt(0)
	v_add_f32_e32 v48, v56, v57
	ds_bpermute_b32 v49, v125, v48
	v_permlane16_swap_b32_e32 v60, v62
	v_permlane16_swap_b32_e32 v61, v63
	v_permlane16_swap_b32_e32 v52, v54
	v_permlane16_swap_b32_e32 v53, v55
	global_store_dwordx4 v[50:51], v[60:63], off
	global_store_dwordx4 v[50:51], v[52:55], off offset:256
	s_and_saveexec_b64 s[66:67], s[4:5]
	s_cbranch_execz .LBB0_612
	s_waitcnt lgkmcnt(0)
	v_add_f32_e32 v48, v48, v49
	v_mul_f32_e32 v48, 0x4f800000, v48
	v_trunc_f32_e32 v48, v48
	v_mul_f32_e32 v49, 0x2f800000, v48
	v_floor_f32_e32 v49, v49
	v_fmac_f32_e32 v48, 0xcf800000, v49
	v_cvt_u32_f32_e32 v48, v48
	v_cvt_u32_f32_e32 v49, v49
	v_lshl_add_u64 v[50:51], v[80:81], 3, s[38:39]
	global_atomic_add_x2 v[50:51], v[48:49], off
; __device__ __forceinline__ unsigned cvt_pk_bf16(float lo, float hi) { unsigned r; asm volatile("v_cvt_pk_bf16_f32 %0, %1, %2" : "=v"(r) : "v"(lo), "v"(hi)); return r; }
;     __device__ __forceinline__ void operator()(const f32x4 (&acc)[2][2][4][2], const Unit& u, int wr, int wc, int fr, int fq, PG8_LAS unsigned char*) const {
;     ...
;         for (int ri = 0; ri < 8; ++ri) {
;             const int ai = ri >> 2, m = ri & 3;
;             const int row = u.pm * BM + ai * HALF + wr * 64 + m * 16 + fr; float ss = 0.f;
;             if (ri < 7) { const int ai2 = (ri + 1) >> 2, m2 = (ri + 1) & 3; const size_t off2 = (size_t)(u.pm * BM + ai2 * HALF + wr * 64 + m2 * 16 + fr) * 1024 + col0;
; #pragma unroll
;                 for (int bj = 0; bj < 2; ++bj)
; #pragma unroll
;                     for (int n = 0; n < 2; ++n) nxt[bj][n] = *(const u32x2*)(xb + off2 + bj * HALF + n * 16); }
; #pragma unroll
;             for (int bj = 0; bj < 2; ++bj)
; #pragma unroll
;                 for (int n = 0; n < 2; ++n) { const u32x2 bb = cur[bj][n]; const f32x4 av = acc[ai][bj][m][n];
;                     const float o0 = __uint_as_float(bb.x << 16) + av[0], o1 = __uint_as_float(bb.x & 0xffff0000u) + av[1], o2 = __uint_as_float(bb.y << 16) + av[2], o3 = __uint_as_float(bb.y & 0xffff0000u) + av[3];
;                     ss += (o0 * o0 + o1 * o1) + (o2 * o2 + o3 * o3);
;                     cur[bj][n].x = cvt_pk_bf16(o0, o1); cur[bj][n].y = cvt_pk_bf16(o2, o3); }
; #pragma unroll
;             for (int bj = 0; bj < 2; ++bj) { unsigned a0 = cur[bj][0].x, a1 = cur[bj][0].y, b0 = cur[bj][1].x, b1 = cur[bj][1].y;
;                 { auto r = __builtin_amdgcn_permlane16_swap(a0, b0, false, false); a0 = r[0]; b0 = r[1]; }
;                 { auto r = __builtin_amdgcn_permlane16_swap(a1, b1, false, false); a1 = r[0]; b1 = r[1]; }
;                 u32x4 w; w.x = a0; w.y = a1; w.z = b0; w.w = b1; *(u32x4*)(xb + (size_t)row * 1024 + u.pn * BM + wc * 32 + bj * HALF + ((fq & 1) << 4) + ((fq >> 1) << 3)) = w; }
;             ss += __shfl_xor(ss, 16); ss += __shfl_xor(ss, 32);
;             if (fq == 0) atomicAdd(rss_next + row, (unsigned long long)(ss * 4294967296.0f));
.LBB0_612:
	s_or_b64 exec, exec, s[66:67]
	v_or_b32_e32 v48, 32, v80
	s_waitcnt lgkmcnt(0)
	v_ashrrev_i32_e32 v49, 31, v48
	v_lshlrev_b64 v[50:51], 11, v[48:49]
	v_lshl_add_u64 v[50:51], s[26:27], 0, v[50:51]
	v_lshl_add_u64 v[52:53], v[144:145], 1, v[50:51]
	s_waitcnt vmcnt(18)
	v_mov_b64_e32 v[74:75], v[210:211]
	v_mov_b64_e32 v[72:73], v[212:213]
	v_mov_b64_e32 v[70:71], v[216:217]
	v_mov_b64_e32 v[68:69], v[218:219]
	v_lshlrev_b32_e32 v60, 16, v74
	v_add_f32_e32 v44, v44, v60
	v_and_b32_e32 v60, 0xffff0000, v74
	v_add_f32_e32 v45, v45, v60
	v_lshlrev_b32_e32 v60, 16, v75
	v_add_f32_e32 v46, v46, v60
	v_and_b32_e32 v60, 0xffff0000, v75
	v_add_f32_e32 v47, v47, v60
	v_mul_f32_e32 v60, v45, v45
	v_mul_f32_e32 v61, v47, v47
	v_fmac_f32_e32 v60, v44, v44
	v_fmac_f32_e32 v61, v46, v46
	v_cvt_pk_bf16_f32 v44, v44, v45
	v_cvt_pk_bf16_f32 v45, v46, v47
	v_lshlrev_b32_e32 v46, 16, v72
	v_add_f32_e32 v40, v40, v46
	v_and_b32_e32 v46, 0xffff0000, v72
	v_add_f32_e32 v41, v41, v46
	v_lshlrev_b32_e32 v46, 16, v73
	v_add_f32_e32 v42, v42, v46
	v_and_b32_e32 v46, 0xffff0000, v73
	v_add_f32_e32 v43, v43, v46
	v_mul_f32_e32 v46, v41, v41
	v_mul_f32_e32 v47, v43, v43
	v_fmac_f32_e32 v46, v40, v40
	v_fmac_f32_e32 v47, v42, v42
	v_add_f32_e32 v60, v60, v61
	v_add_f32_e32 v46, v46, v47
	v_add_f32_e32 v60, v60, v46
	v_cvt_pk_bf16_f32 v46, v40, v41
	v_lshlrev_b32_e32 v40, 16, v70
	v_add_f32_e32 v36, v36, v40
	v_and_b32_e32 v40, 0xffff0000, v70
	v_add_f32_e32 v37, v37, v40
	v_lshlrev_b32_e32 v40, 16, v71
	v_add_f32_e32 v38, v38, v40
	v_and_b32_e32 v40, 0xffff0000, v71
	v_add_f32_e32 v39, v39, v40
	v_mul_f32_e32 v40, v37, v37
	v_mul_f32_e32 v41, v39, v39
	v_cvt_pk_bf16_f32 v47, v42, v43
	v_fmac_f32_e32 v40, v36, v36
	v_fmac_f32_e32 v41, v38, v38
	v_cvt_pk_bf16_f32 v36, v36, v37
	v_cvt_pk_bf16_f32 v37, v38, v39
	v_lshlrev_b32_e32 v38, 16, v68
	v_add_f32_e32 v32, v32, v38
	v_and_b32_e32 v38, 0xffff0000, v68
	v_add_f32_e32 v33, v33, v38
	v_lshlrev_b32_e32 v38, 16, v69
	v_add_f32_e32 v34, v34, v38
	v_and_b32_e32 v38, 0xffff0000, v69
	v_add_f32_e32 v35, v35, v38
	v_mul_f32_e32 v38, v33, v33
	v_mul_f32_e32 v39, v35, v35
	v_add_f32_e32 v40, v40, v41
	v_fmac_f32_e32 v38, v32, v32
	v_fmac_f32_e32 v39, v34, v34
	v_add_f32_e32 v41, v38, v39
	v_cvt_pk_bf16_f32 v38, v32, v33
	v_cvt_pk_bf16_f32 v39, v34, v35
	v_add_f32_e32 v34, v60, v40
	v_add_f32_e32 v40, v34, v41
	ds_bpermute_b32 v41, v124, v40
	v_lshl_add_u64 v[32:33], s[64:65], 1, v[66:67]
	v_lshl_add_u64 v[32:33], v[32:33], 0, s[10:11]
	v_lshl_add_u64 v[32:33], v[32:33], 0, v[132:133]
	v_lshl_add_u64 v[34:35], v[32:33], 0, v[142:143]
	s_waitcnt lgkmcnt(0)
	v_add_f32_e32 v32, v40, v41
	ds_bpermute_b32 v33, v125, v32
	v_permlane16_swap_b32_e32 v44, v46
	v_permlane16_swap_b32_e32 v45, v47
	v_permlane16_swap_b32_e32 v36, v38
	v_permlane16_swap_b32_e32 v37, v39
	global_store_dwordx4 v[34:35], v[44:47], off
	global_store_dwordx4 v[34:35], v[36:39], off offset:256
	s_and_saveexec_b64 s[66:67], s[4:5]
	s_cbranch_execz .LBB0_614
	s_waitcnt lgkmcnt(0)
	v_add_f32_e32 v32, v32, v33
	v_mul_f32_e32 v32, 0x4f800000, v32
	v_trunc_f32_e32 v32, v32
	v_mul_f32_e32 v33, 0x2f800000, v32
	v_floor_f32_e32 v33, v33
	v_fmac_f32_e32 v32, 0xcf800000, v33
	v_cvt_u32_f32_e32 v32, v32
	v_cvt_u32_f32_e32 v33, v33
	v_lshl_add_u64 v[34:35], v[64:65], 3, s[38:39]
	global_atomic_add_x2 v[34:35], v[32:33], off
; __device__ __forceinline__ unsigned cvt_pk_bf16(float lo, float hi) { unsigned r; asm volatile("v_cvt_pk_bf16_f32 %0, %1, %2" : "=v"(r) : "v"(lo), "v"(hi)); return r; }
;     __device__ __forceinline__ void operator()(const f32x4 (&acc)[2][2][4][2], const Unit& u, int wr, int wc, int fr, int fq, PG8_LAS unsigned char*) const {
;     ...
;         for (int ri = 0; ri < 8; ++ri) {
;             const int ai = ri >> 2, m = ri & 3;
;             const int row = u.pm * BM + ai * HALF + wr * 64 + m * 16 + fr; float ss = 0.f;
;             if (ri < 7) { const int ai2 = (ri + 1) >> 2, m2 = (ri + 1) & 3; const size_t off2 = (size_t)(u.pm * BM + ai2 * HALF + wr * 64 + m2 * 16 + fr) * 1024 + col0;
; #pragma unroll
;                 for (int bj = 0; bj < 2; ++bj)
; #pragma unroll
;                     for (int n = 0; n < 2; ++n) nxt[bj][n] = *(const u32x2*)(xb + off2 + bj * HALF + n * 16); }
; #pragma unroll
;             for (int bj = 0; bj < 2; ++bj)
; #pragma unroll
;                 for (int n = 0; n < 2; ++n) { const u32x2 bb = cur[bj][n]; const f32x4 av = acc[ai][bj][m][n];
;                     const float o0 = __uint_as_float(bb.x << 16) + av[0], o1 = __uint_as_float(bb.x & 0xffff0000u) + av[1], o2 = __uint_as_float(bb.y << 16) + av[2], o3 = __uint_as_float(bb.y & 0xffff0000u) + av[3];
;                     ss += (o0 * o0 + o1 * o1) + (o2 * o2 + o3 * o3);
;                     cur[bj][n].x = cvt_pk_bf16(o0, o1); cur[bj][n].y = cvt_pk_bf16(o2, o3); }
; #pragma unroll
;             for (int bj = 0; bj < 2; ++bj) { unsigned a0 = cur[bj][0].x, a1 = cur[bj][0].y, b0 = cur[bj][1].x, b1 = cur[bj][1].y;
;                 { auto r = __builtin_amdgcn_permlane16_swap(a0, b0, false, false); a0 = r[0]; b0 = r[1]; }
;                 { auto r = __builtin_amdgcn_permlane16_swap(a1, b1, false, false); a1 = r[0]; b1 = r[1]; }
;                 u32x4 w; w.x = a0; w.y = a1; w.z = b0; w.w = b1; *(u32x4*)(xb + (size_t)row * 1024 + u.pn * BM + wc * 32 + bj * HALF + ((fq & 1) << 4) + ((fq >> 1) << 3)) = w; }
;             ss += __shfl_xor(ss, 16); ss += __shfl_xor(ss, 32);
;             if (fq == 0) atomicAdd(rss_next + row, (unsigned long long)(ss * 4294967296.0f));
.LBB0_614:
	s_or_b64 exec, exec, s[66:67]
	v_or_b32_e32 v32, 48, v80
	s_waitcnt lgkmcnt(0)
	v_ashrrev_i32_e32 v33, 31, v32
	v_lshlrev_b64 v[34:35], 11, v[32:33]
	v_lshl_add_u64 v[34:35], s[26:27], 0, v[34:35]
	v_lshl_add_u64 v[36:37], v[144:145], 1, v[34:35]
	s_waitcnt vmcnt(16)
	v_mov_b64_e32 v[58:59], v[220:221]
	v_mov_b64_e32 v[56:57], v[222:223]
	v_mov_b64_e32 v[54:55], v[224:225]
	v_mov_b64_e32 v[52:53], v[226:227]
	v_lshlrev_b32_e32 v44, 16, v58
	v_add_f32_e32 v28, v28, v44
	v_and_b32_e32 v44, 0xffff0000, v58
	v_add_f32_e32 v29, v29, v44
	v_lshlrev_b32_e32 v44, 16, v59
	v_add_f32_e32 v30, v30, v44
	v_and_b32_e32 v44, 0xffff0000, v59
	v_add_f32_e32 v31, v31, v44
	v_mul_f32_e32 v44, v29, v29
	v_mul_f32_e32 v45, v31, v31
	v_fmac_f32_e32 v44, v28, v28
	v_fmac_f32_e32 v45, v30, v30
	v_cvt_pk_bf16_f32 v28, v28, v29
	v_cvt_pk_bf16_f32 v29, v30, v31
	v_lshlrev_b32_e32 v30, 16, v56
	v_add_f32_e32 v24, v24, v30
	v_and_b32_e32 v30, 0xffff0000, v56
	v_add_f32_e32 v25, v25, v30
	v_lshlrev_b32_e32 v30, 16, v57
	v_add_f32_e32 v26, v26, v30
	v_and_b32_e32 v30, 0xffff0000, v57
	v_add_f32_e32 v27, v27, v30
	v_mul_f32_e32 v30, v25, v25
	v_mul_f32_e32 v31, v27, v27
	v_fmac_f32_e32 v30, v24, v24
	v_fmac_f32_e32 v31, v26, v26
	v_add_f32_e32 v44, v44, v45
	v_add_f32_e32 v30, v30, v31
	v_add_f32_e32 v44, v44, v30
	v_cvt_pk_bf16_f32 v30, v24, v25
	v_lshlrev_b32_e32 v24, 16, v54
	v_add_f32_e32 v20, v20, v24
	v_and_b32_e32 v24, 0xffff0000, v54
	v_add_f32_e32 v21, v21, v24
	v_lshlrev_b32_e32 v24, 16, v55
	v_add_f32_e32 v22, v22, v24
	v_and_b32_e32 v24, 0xffff0000, v55
	v_add_f32_e32 v23, v23, v24
	v_mul_f32_e32 v24, v21, v21
	v_mul_f32_e32 v25, v23, v23
	v_cvt_pk_bf16_f32 v31, v26, v27
	v_fmac_f32_e32 v24, v20, v20
	v_fmac_f32_e32 v25, v22, v22
	v_cvt_pk_bf16_f32 v20, v20, v21
	v_cvt_pk_bf16_f32 v21, v22, v23
	v_lshlrev_b32_e32 v22, 16, v52
	v_add_f32_e32 v16, v16, v22
	v_and_b32_e32 v22, 0xffff0000, v52
	v_add_f32_e32 v17, v17, v22
	v_lshlrev_b32_e32 v22, 16, v53
	v_add_f32_e32 v18, v18, v22
	v_and_b32_e32 v22, 0xffff0000, v53
	v_add_f32_e32 v19, v19, v22
	v_mul_f32_e32 v22, v17, v17
	v_mul_f32_e32 v23, v19, v19
	v_add_f32_e32 v24, v24, v25
	v_fmac_f32_e32 v22, v16, v16
	v_fmac_f32_e32 v23, v18, v18
	v_add_f32_e32 v25, v22, v23
	v_cvt_pk_bf16_f32 v22, v16, v17
	v_cvt_pk_bf16_f32 v23, v18, v19
	v_add_f32_e32 v18, v44, v24
	v_add_f32_e32 v24, v18, v25
	ds_bpermute_b32 v25, v124, v24
	v_lshl_add_u64 v[16:17], s[64:65], 1, v[50:51]
	v_lshl_add_u64 v[16:17], v[16:17], 0, s[10:11]
	v_lshl_add_u64 v[16:17], v[16:17], 0, v[132:133]
	v_mov_b32_e32 v143, v133
	v_lshl_add_u64 v[18:19], v[16:17], 0, v[142:143]
	s_waitcnt lgkmcnt(0)
	v_add_f32_e32 v16, v24, v25
	ds_bpermute_b32 v17, v125, v16
	v_permlane16_swap_b32_e32 v28, v30
	v_permlane16_swap_b32_e32 v29, v31
	v_permlane16_swap_b32_e32 v20, v22
	v_permlane16_swap_b32_e32 v21, v23
	global_store_dwordx4 v[18:19], v[28:31], off
	global_store_dwordx4 v[18:19], v[20:23], off offset:256
	s_and_saveexec_b64 s[66:67], s[4:5]
	s_cbranch_execz .LBB0_616
	s_waitcnt lgkmcnt(0)
	v_add_f32_e32 v16, v16, v17
	v_mul_f32_e32 v16, 0x4f800000, v16
	v_trunc_f32_e32 v16, v16
	v_mul_f32_e32 v17, 0x2f800000, v16
	v_floor_f32_e32 v17, v17
	v_fmac_f32_e32 v16, 0xcf800000, v17
	v_cvt_u32_f32_e32 v16, v16
	v_cvt_u32_f32_e32 v17, v17
	v_lshl_add_u64 v[18:19], v[48:49], 3, s[38:39]
	global_atomic_add_x2 v[18:19], v[16:17], off
.LBB0_616:
	s_or_b64 exec, exec, s[66:67]
	s_waitcnt vmcnt(14)
	v_mov_b64_e32 v[42:43], v[228:229]
	v_mov_b64_e32 v[40:41], v[230:231]
	v_mov_b64_e32 v[38:39], v[232:233]
	v_mov_b64_e32 v[36:37], v[234:235]
	v_lshlrev_b32_e32 v16, 16, v42
	v_add_f32_e32 v12, v12, v16
	v_and_b32_e32 v16, 0xffff0000, v42
	v_add_f32_e32 v13, v13, v16
	v_lshlrev_b32_e32 v16, 16, v43
	v_add_f32_e32 v14, v14, v16
	v_and_b32_e32 v16, 0xffff0000, v43
	v_add_f32_e32 v15, v15, v16
	v_mul_f32_e32 v16, v13, v13
	s_waitcnt lgkmcnt(0)
	v_mul_f32_e32 v17, v15, v15
	v_fmac_f32_e32 v16, v12, v12
	v_fmac_f32_e32 v17, v14, v14
	v_cvt_pk_bf16_f32 v12, v12, v13
	v_cvt_pk_bf16_f32 v13, v14, v15
	v_lshlrev_b32_e32 v14, 16, v40
	v_add_f32_e32 v8, v8, v14
	v_and_b32_e32 v14, 0xffff0000, v40
	v_add_f32_e32 v9, v9, v14
	v_lshlrev_b32_e32 v14, 16, v41
	v_add_f32_e32 v10, v10, v14
	v_and_b32_e32 v14, 0xffff0000, v41
	v_add_f32_e32 v11, v11, v14
	v_mul_f32_e32 v14, v9, v9
	v_mul_f32_e32 v15, v11, v11
	v_fmac_f32_e32 v14, v8, v8
	v_fmac_f32_e32 v15, v10, v10
	v_add_f32_e32 v16, v16, v17
	v_add_f32_e32 v14, v14, v15
	v_add_f32_e32 v16, v16, v14
	v_cvt_pk_bf16_f32 v14, v8, v9
	v_lshlrev_b32_e32 v8, 16, v38
	v_add_f32_e32 v4, v4, v8
	v_and_b32_e32 v8, 0xffff0000, v38
	v_add_f32_e32 v5, v5, v8
	v_lshlrev_b32_e32 v8, 16, v39
	v_add_f32_e32 v6, v6, v8
	v_and_b32_e32 v8, 0xffff0000, v39
	v_add_f32_e32 v7, v7, v8
	v_mul_f32_e32 v8, v5, v5
	v_mul_f32_e32 v9, v7, v7
	v_cvt_pk_bf16_f32 v15, v10, v11
	v_fmac_f32_e32 v8, v4, v4
	v_fmac_f32_e32 v9, v6, v6
	v_cvt_pk_bf16_f32 v4, v4, v5
	v_cvt_pk_bf16_f32 v5, v6, v7
	v_lshlrev_b32_e32 v6, 16, v36
	v_add_f32_e32 v0, v0, v6
	v_and_b32_e32 v6, 0xffff0000, v36
	v_add_f32_e32 v1, v1, v6
	v_lshlrev_b32_e32 v6, 16, v37
	v_add_f32_e32 v2, v2, v6
	v_and_b32_e32 v6, 0xffff0000, v37
	v_add_f32_e32 v3, v3, v6
	v_mul_f32_e32 v6, v1, v1
	v_mul_f32_e32 v7, v3, v3
	v_add_f32_e32 v8, v8, v9
	v_fmac_f32_e32 v6, v0, v0
	v_fmac_f32_e32 v7, v2, v2
	v_add_f32_e32 v9, v6, v7
	v_cvt_pk_bf16_f32 v6, v0, v1
	v_cvt_pk_bf16_f32 v7, v2, v3
	v_add_f32_e32 v2, v16, v8
	v_add_f32_e32 v8, v2, v9
	ds_bpermute_b32 v9, v124, v8
	v_lshl_add_u64 v[0:1], s[64:65], 1, v[34:35]
	v_lshl_add_u64 v[0:1], v[0:1], 0, s[10:11]
	v_lshl_add_u64 v[0:1], v[0:1], 0, v[132:133]
	v_lshl_add_u64 v[2:3], v[0:1], 0, v[142:143]
	s_waitcnt lgkmcnt(0)
	v_add_f32_e32 v0, v8, v9
	ds_bpermute_b32 v1, v125, v0
	v_permlane16_swap_b32_e32 v12, v14
	v_permlane16_swap_b32_e32 v13, v15
	v_permlane16_swap_b32_e32 v4, v6
	v_permlane16_swap_b32_e32 v5, v7
	global_store_dwordx4 v[2:3], v[12:15], off
	global_store_dwordx4 v[2:3], v[4:7], off offset:256
	s_and_saveexec_b64 s[64:65], s[4:5]
	s_cbranch_execz .LBB0_618
	s_waitcnt lgkmcnt(0)
	v_add_f32_e32 v0, v0, v1
	v_mul_f32_e32 v0, 0x4f800000, v0
	v_trunc_f32_e32 v0, v0
	v_mul_f32_e32 v1, 0x2f800000, v0
	v_floor_f32_e32 v1, v1
	v_fmac_f32_e32 v0, 0xcf800000, v1
	v_cvt_u32_f32_e32 v0, v0
	v_cvt_u32_f32_e32 v1, v1
	v_lshl_add_u64 v[2:3], v[32:33], 3, s[38:39]
	global_atomic_add_x2 v[2:3], v[0:1], off

;     __device__ __forceinline__ void operator()(const f32x4 (&acc)[2][2][4][2], const Unit& u, int wr, int wc, int fr, int fq, PG8_LAS unsigned char*) const {
;         const int col0 = u.pn * BM + wc * 32 + 4 * fq;
;         u32x2 cur[2][2], nxt[2][2];
;         { const size_t off = (size_t)(u.pm * BM + wr * 64 + fr) * 1024 + col0;
; #pragma unroll
;           for (int bj = 0; bj < 2; ++bj)
; #pragma unroll
;             for (int n = 0; n < 2; ++n) cur[bj][n] = *(const u32x2*)(xb + off + bj * HALF + n * 16); }
; #pragma unroll
;         for (int ri = 0; ri < 8; ++ri) {
;             const int ai = ri >> 2, m = ri & 3;
;             const int row = u.pm * BM + ai * HALF + wr * 64 + m * 16 + fr; float ss = 0.f;
;             if (ri < 7) { const int ai2 = (ri + 1) >> 2, m2 = (ri + 1) & 3; const size_t off2 = (size_t)(u.pm * BM + ai2 * HALF + wr * 64 + m2 * 16 + fr) * 1024 + col0;
; #pragma unroll
;                 for (int bj = 0; bj < 2; ++bj)
; #pragma unroll
;                     for (int n = 0; n < 2; ++n) nxt[bj][n] = *(const u32x2*)(xb + off2 + bj * HALF + n * 16); }
; #pragma unroll
;             for (int bj = 0; bj < 2; ++bj)
; #pragma unroll
;                 for (int n = 0; n < 2; ++n) { const u32x2 bb = cur[bj][n]; const f32x4 av = acc[ai][bj][m][n];
;                     const float o0 = __uint_as_float(bb.x << 16) + av[0], o1 = __uint_as_float(bb.x & 0xffff0000u) + av[1], o2 = __uint_as_float(bb.y << 16) + av[2], o3 = __uint_as_float(bb.y & 0xffff0000u) + av[3];
;                     ss += (o0 * o0 + o1 * o1) + (o2 * o2 + o3 * o3);
;                     cur[bj][n].x = cvt_pk_bf16(o0, o1); cur[bj][n].y = cvt_pk_bf16(o2, o3); }
; #pragma unroll
;             for (int bj = 0; bj < 2; ++bj) { unsigned a0 = cur[bj][0].x, a1 = cur[bj][0].y, b0 = cur[bj][1].x, b1 = cur[bj][1].y;
;                 { auto r = __builtin_amdgcn_permlane16_swap(a0, b0, false, false); a0 = r[0]; b0 = r[1]; }
;                 { auto r = __builtin_amdgcn_permlane16_swap(a1, b1, false, false); a1 = r[0]; b1 = r[1]; }
;                 u32x4 w; w.x = a0; w.y = a1; w.z = b0; w.w = b1; *(u32x4*)(xb + (size_t)row * 1024 + u.pn * BM + wc * 32 + bj * HALF + ((fq & 1) << 4) + ((fq >> 1) << 3)) = w; }
;             ss += __shfl_xor(ss, 16); ss += __shfl_xor(ss, 32);
;             if (fq == 0) atomicAdd(rss_next + row, (unsigned long long)(ss * 4294967296.0f));
.LBB0_988:
	s_lshl_b32 s44, s44, 8
	v_lshl_add_u32 v146, s42, 8, v160
	v_or_b32_e32 v144, s44, v162
	v_ashrrev_i32_e32 v147, 31, v146
	v_ashrrev_i32_e32 v145, 31, v144
	v_lshlrev_b64 v[148:149], 11, v[146:147]
	v_lshl_add_u64 v[152:153], s[26:27], 0, v[148:149]
	v_lshlrev_b64 v[154:155], 1, v[144:145]
	v_lshl_add_u64 v[148:149], v[152:153], 0, v[154:155]
	global_load_dwordx2 v[168:169], v[148:149], off
	global_load_dwordx2 v[170:171], v[148:149], off offset:32
	global_load_dwordx2 v[172:173], v[148:149], off offset:256
	global_load_dwordx2 v[174:175], v[148:149], off offset:288
	v_or_b32_e32 v148, 16, v146
	v_ashrrev_i32_e32 v149, 31, v148
	v_lshlrev_b64 v[150:151], 11, v[148:149]
	s_ashr_i32 s45, s44, 31
	v_lshl_add_u64 v[150:151], s[26:27], 0, v[150:151]
	v_lshl_add_u64 v[152:153], s[44:45], 1, v[152:153]
	v_lshl_add_u64 v[176:177], v[150:151], 0, v[154:155]
	v_lshl_add_u64 v[178:179], v[152:153], 0, s[8:9]
	global_load_dwordx2 v[158:159], v[176:177], off
	global_load_dwordx2 v[156:157], v[176:177], off offset:32
	global_load_dwordx2 v[154:155], v[176:177], off offset:256
	global_load_dwordx2 v[152:153], v[176:177], off offset:288
	s_mov_b64 s[98:99], 0x8000
	v_lshl_add_u64 v[252:253], v[176:177], 0, s[98:99]
	global_load_dwordx2 v[186:187], v[252:253], off
	global_load_dwordx2 v[188:189], v[252:253], off offset:32
	global_load_dwordx2 v[190:191], v[252:253], off offset:256
	global_load_dwordx2 v[192:193], v[252:253], off offset:288
	s_mov_b64 s[98:99], 0x10000
	v_lshl_add_u64 v[252:253], v[176:177], 0, s[98:99]
	global_load_dwordx2 v[194:195], v[252:253], off
	global_load_dwordx2 v[196:197], v[252:253], off offset:32
	global_load_dwordx2 v[198:199], v[252:253], off offset:256
	global_load_dwordx2 v[200:201], v[252:253], off offset:288
	s_mov_b64 s[98:99], 0x38000
	v_lshl_add_u64 v[252:253], v[176:177], 0, s[98:99]
	global_load_dwordx2 v[202:203], v[252:253], off
	global_load_dwordx2 v[204:205], v[252:253], off offset:32
	global_load_dwordx2 v[206:207], v[252:253], off offset:256
	global_load_dwordx2 v[208:209], v[252:253], off offset:288
	s_mov_b64 s[98:99], 0x40000
	v_lshl_add_u64 v[252:253], v[176:177], 0, s[98:99]
	global_load_dwordx2 v[210:211], v[252:253], off
	global_load_dwordx2 v[212:213], v[252:253], off offset:32
	global_load_dwordx2 v[216:217], v[252:253], off offset:256
	global_load_dwordx2 v[218:219], v[252:253], off offset:288
	s_mov_b64 s[98:99], 0x48000
	v_lshl_add_u64 v[252:253], v[176:177], 0, s[98:99]
	global_load_dwordx2 v[220:221], v[252:253], off
	global_load_dwordx2 v[222:223], v[252:253], off offset:32
	global_load_dwordx2 v[224:225], v[252:253], off offset:256
	global_load_dwordx2 v[226:227], v[252:253], off offset:288
	s_mov_b64 s[98:99], 0x50000
	v_lshl_add_u64 v[252:253], v[176:177], 0, s[98:99]
	global_load_dwordx2 v[228:229], v[252:253], off
	global_load_dwordx2 v[230:231], v[252:253], off offset:32
	global_load_dwordx2 v[232:233], v[252:253], off offset:256
	global_load_dwordx2 v[234:235], v[252:253], off offset:288
	v_xor_b32_e32 v143, 16, v166
	s_waitcnt vmcnt(24)
	v_lshlrev_b32_e32 v167, 16, v168
	v_and_b32_e32 v168, 0xffff0000, v168
	v_lshlrev_b32_e32 v176, 16, v169
	v_and_b32_e32 v169, 0xffff0000, v169
	v_lshlrev_b32_e32 v177, 16, v170
	v_and_b32_e32 v170, 0xffff0000, v170
	v_lshlrev_b32_e32 v180, 16, v171
	v_and_b32_e32 v171, 0xffff0000, v171
	v_lshlrev_b32_e32 v181, 16, v172
	v_and_b32_e32 v172, 0xffff0000, v172
	v_lshlrev_b32_e32 v182, 16, v173
	v_and_b32_e32 v173, 0xffff0000, v173
	v_lshlrev_b32_e32 v183, 16, v174
	v_and_b32_e32 v174, 0xffff0000, v174
	v_add_f32_e32 v125, v125, v168
	v_add_f32_e32 v127, v127, v169
	v_add_f32_e32 v121, v121, v170
	v_add_f32_e32 v123, v123, v171
	v_lshlrev_b32_e32 v184, 16, v175
	v_and_b32_e32 v175, 0xffff0000, v175
	v_add_f32_e32 v124, v124, v167
	v_add_f32_e32 v126, v126, v176
	v_add_f32_e32 v120, v120, v177
	v_add_f32_e32 v122, v122, v180
	v_add_f32_e32 v167, v116, v181
	v_add_f32_e32 v116, v117, v172
	v_add_f32_e32 v168, v118, v182
	v_add_f32_e32 v117, v119, v173
	v_add_f32_e32 v169, v112, v183
	v_add_f32_e32 v118, v113, v174
	v_mul_f32_e32 v171, v125, v125
	v_mul_f32_e32 v172, v127, v127
	v_cvt_pk_bf16_f32 v112, v124, v125
	v_cvt_pk_bf16_f32 v113, v126, v127
	v_mul_f32_e32 v125, v121, v121
	v_mul_f32_e32 v127, v123, v123
	v_add_f32_e32 v170, v114, v184
	v_add_f32_e32 v119, v115, v175
	v_cvt_pk_bf16_f32 v114, v120, v121
	v_cvt_pk_bf16_f32 v115, v122, v123
	v_mul_f32_e32 v121, v116, v116
	v_mul_f32_e32 v123, v117, v117
	v_fmac_f32_e32 v171, v124, v124
	v_fmac_f32_e32 v172, v126, v126
	v_fmac_f32_e32 v125, v120, v120
	v_fmac_f32_e32 v127, v122, v122
	v_mul_f32_e32 v173, v118, v118
	v_mul_f32_e32 v174, v119, v119
	v_fmac_f32_e32 v121, v167, v167
	v_fmac_f32_e32 v123, v168, v168
	v_add_f32_e32 v120, v171, v172
	v_add_f32_e32 v122, v125, v127
	v_fmac_f32_e32 v173, v169, v169
	v_fmac_f32_e32 v174, v170, v170
	v_add_f32_e32 v121, v121, v123
	v_add_f32_e32 v120, v120, v122
	v_add_f32_e32 v123, v173, v174
	v_add_f32_e32 v120, v120, v121
	v_add_f32_e32 v122, v120, v123
	v_and_b32_e32 v120, 64, v166
	v_add_u32_e32 v123, 64, v120
	v_cmp_lt_i32_e32 vcc, v143, v123
	v_permlane16_swap_b32_e32 v112, v114
	s_nop 0
	v_cndmask_b32_e32 v120, v166, v143, vcc
	v_lshlrev_b32_e32 v124, 2, v120
	ds_bpermute_b32 v125, v124, v122
	v_lshl_add_u64 v[120:121], v[178:179], 0, v[132:133]
	v_mov_b32_e32 v143, v133
	v_permlane16_swap_b32_e32 v113, v115
	v_lshl_add_u64 v[120:121], v[120:121], 0, v[142:143]
	v_cvt_pk_bf16_f32 v116, v167, v116
	v_cvt_pk_bf16_f32 v117, v168, v117
	v_cvt_pk_bf16_f32 v118, v169, v118
	v_cvt_pk_bf16_f32 v119, v170, v119
	global_store_dwordx4 v[120:121], v[112:115], off
	v_permlane16_swap_b32_e32 v116, v118
	s_nop 0
	v_xor_b32_e32 v113, 32, v166
	v_cmp_lt_i32_e32 vcc, v113, v123
	s_waitcnt lgkmcnt(0)
	v_add_f32_e32 v112, v122, v125
	v_permlane16_swap_b32_e32 v117, v119
	v_cndmask_b32_e32 v113, v166, v113, vcc
	v_lshlrev_b32_e32 v125, 2, v113
	ds_bpermute_b32 v113, v125, v112
	global_store_dwordx4 v[120:121], v[116:119], off offset:256
	s_and_saveexec_b64 s[42:43], s[4:5]
	s_cbranch_execz .LBB0_990
	s_waitcnt lgkmcnt(0)
	v_add_f32_e32 v112, v112, v113
	v_mul_f32_e32 v112, 0x4f800000, v112
	v_trunc_f32_e32 v112, v112
	v_mul_f32_e32 v113, 0x2f800000, v112
	v_floor_f32_e32 v113, v113
	v_fmac_f32_e32 v112, 0xcf800000, v113
	v_cvt_u32_f32_e32 v112, v112
	v_cvt_u32_f32_e32 v113, v113
	v_lshl_add_u64 v[114:115], v[146:147], 3, s[12:13]
	global_atomic_add_x2 v[114:115], v[112:113], off
; __device__ __forceinline__ unsigned cvt_pk_bf16(float lo, float hi) { unsigned r; asm volatile("v_cvt_pk_bf16_f32 %0, %1, %2" : "=v"(r) : "v"(lo), "v"(hi)); return r; }
;     __device__ __forceinline__ void operator()(const f32x4 (&acc)[2][2][4][2], const Unit& u, int wr, int wc, int fr, int fq, PG8_LAS unsigned char*) const {
;     ...
;         for (int ri = 0; ri < 8; ++ri) {
;             const int ai = ri >> 2, m = ri & 3;
;             const int row = u.pm * BM + ai * HALF + wr * 64 + m * 16 + fr; float ss = 0.f;
;             if (ri < 7) { const int ai2 = (ri + 1) >> 2, m2 = (ri + 1) & 3; const size_t off2 = (size_t)(u.pm * BM + ai2 * HALF + wr * 64 + m2 * 16 + fr) * 1024 + col0;
; #pragma unroll
;                 for (int bj = 0; bj < 2; ++bj)
; #pragma unroll
;                     for (int n = 0; n < 2; ++n) nxt[bj][n] = *(const u32x2*)(xb + off2 + bj * HALF + n * 16); }
; #pragma unroll
;             for (int bj = 0; bj < 2; ++bj)
; #pragma unroll
;                 for (int n = 0; n < 2; ++n) { const u32x2 bb = cur[bj][n]; const f32x4 av = acc[ai][bj][m][n];
;                     const float o0 = __uint_as_float(bb.x << 16) + av[0], o1 = __uint_as_float(bb.x & 0xffff0000u) + av[1], o2 = __uint_as_float(bb.y << 16) + av[2], o3 = __uint_as_float(bb.y & 0xffff0000u) + av[3];
;                     ss += (o0 * o0 + o1 * o1) + (o2 * o2 + o3 * o3);
;                     cur[bj][n].x = cvt_pk_bf16(o0, o1); cur[bj][n].y = cvt_pk_bf16(o2, o3); }
; #pragma unroll
;             for (int bj = 0; bj < 2; ++bj) { unsigned a0 = cur[bj][0].x, a1 = cur[bj][0].y, b0 = cur[bj][1].x, b1 = cur[bj][1].y;
;                 { auto r = __builtin_amdgcn_permlane16_swap(a0, b0, false, false); a0 = r[0]; b0 = r[1]; }
;                 { auto r = __builtin_amdgcn_permlane16_swap(a1, b1, false, false); a1 = r[0]; b1 = r[1]; }
;                 u32x4 w; w.x = a0; w.y = a1; w.z = b0; w.w = b1; *(u32x4*)(xb + (size_t)row * 1024 + u.pn * BM + wc * 32 + bj * HALF + ((fq & 1) << 4) + ((fq >> 1) << 3)) = w; }
;             ss += __shfl_xor(ss, 16); ss += __shfl_xor(ss, 32);
;             if (fq == 0) atomicAdd(rss_next + row, (unsigned long long)(ss * 4294967296.0f));
.LBB0_990:
	s_or_b64 exec, exec, s[42:43]
	v_or_b32_e32 v112, 32, v146
	s_waitcnt lgkmcnt(0)
	v_ashrrev_i32_e32 v113, 31, v112
	v_lshlrev_b64 v[114:115], 11, v[112:113]
	v_lshl_add_u64 v[114:115], s[26:27], 0, v[114:115]
	v_lshl_add_u64 v[116:117], v[144:145], 1, v[114:115]
	v_lshlrev_b32_e32 v126, 16, v158
	v_add_f32_e32 v108, v108, v126
	v_and_b32_e32 v126, 0xffff0000, v158
	v_add_f32_e32 v109, v109, v126
	v_lshlrev_b32_e32 v126, 16, v159
	v_add_f32_e32 v110, v110, v126
	v_and_b32_e32 v126, 0xffff0000, v159
	v_add_f32_e32 v111, v111, v126
	v_mul_f32_e32 v126, v109, v109
	v_mul_f32_e32 v127, v111, v111
	v_fmac_f32_e32 v126, v108, v108
	v_fmac_f32_e32 v127, v110, v110
	v_cvt_pk_bf16_f32 v108, v108, v109
	v_cvt_pk_bf16_f32 v109, v110, v111
	v_lshlrev_b32_e32 v110, 16, v156
	v_add_f32_e32 v104, v104, v110
	v_and_b32_e32 v110, 0xffff0000, v156
	v_add_f32_e32 v105, v105, v110
	v_lshlrev_b32_e32 v110, 16, v157
	v_add_f32_e32 v106, v106, v110
	v_and_b32_e32 v110, 0xffff0000, v157
	v_add_f32_e32 v107, v107, v110
	v_mul_f32_e32 v110, v105, v105
	v_mul_f32_e32 v111, v107, v107
	v_fmac_f32_e32 v110, v104, v104
	v_fmac_f32_e32 v111, v106, v106
	v_add_f32_e32 v126, v126, v127
	v_add_f32_e32 v110, v110, v111
	v_add_f32_e32 v126, v126, v110
	v_cvt_pk_bf16_f32 v110, v104, v105
	v_lshlrev_b32_e32 v104, 16, v154
	v_add_f32_e32 v100, v100, v104
	v_and_b32_e32 v104, 0xffff0000, v154
	v_add_f32_e32 v101, v101, v104
	v_lshlrev_b32_e32 v104, 16, v155
	v_add_f32_e32 v102, v102, v104
	v_and_b32_e32 v104, 0xffff0000, v155
	v_add_f32_e32 v103, v103, v104
	v_mul_f32_e32 v104, v101, v101
	v_mul_f32_e32 v105, v103, v103
	v_cvt_pk_bf16_f32 v111, v106, v107
	v_fmac_f32_e32 v104, v100, v100
	v_fmac_f32_e32 v105, v102, v102
	v_cvt_pk_bf16_f32 v100, v100, v101
	v_cvt_pk_bf16_f32 v101, v102, v103
	v_lshlrev_b32_e32 v102, 16, v152
	v_add_f32_e32 v96, v96, v102
	v_and_b32_e32 v102, 0xffff0000, v152
	v_add_f32_e32 v97, v97, v102
	v_lshlrev_b32_e32 v102, 16, v153
	v_add_f32_e32 v98, v98, v102
	v_and_b32_e32 v102, 0xffff0000, v153
	v_add_f32_e32 v99, v99, v102
	v_mul_f32_e32 v102, v97, v97
	v_mul_f32_e32 v103, v99, v99
	v_add_f32_e32 v104, v104, v105
	v_fmac_f32_e32 v102, v96, v96
	v_fmac_f32_e32 v103, v98, v98
	v_add_f32_e32 v105, v102, v103
	v_cvt_pk_bf16_f32 v102, v96, v97
	v_cvt_pk_bf16_f32 v103, v98, v99
	v_add_f32_e32 v98, v126, v104
	v_add_f32_e32 v104, v98, v105
	ds_bpermute_b32 v105, v124, v104
	v_lshl_add_u64 v[96:97], s[44:45], 1, v[150:151]
	v_lshl_add_u64 v[96:97], v[96:97], 0, s[8:9]
	v_lshl_add_u64 v[96:97], v[96:97], 0, v[132:133]
	v_lshl_add_u64 v[98:99], v[96:97], 0, v[142:143]
	s_waitcnt lgkmcnt(0)
	v_add_f32_e32 v96, v104, v105
	ds_bpermute_b32 v97, v125, v96
	v_permlane16_swap_b32_e32 v108, v110
	v_permlane16_swap_b32_e32 v109, v111
	v_permlane16_swap_b32_e32 v100, v102
	v_permlane16_swap_b32_e32 v101, v103
	global_store_dwordx4 v[98:99], v[108:111], off
	global_store_dwordx4 v[98:99], v[100:103], off offset:256
	s_and_saveexec_b64 s[42:43], s[4:5]
	s_cbranch_execz .LBB0_992
	s_waitcnt lgkmcnt(0)
	v_add_f32_e32 v96, v96, v97
	v_mul_f32_e32 v96, 0x4f800000, v96
	v_trunc_f32_e32 v96, v96
	v_mul_f32_e32 v97, 0x2f800000, v96
	v_floor_f32_e32 v97, v97
	v_fmac_f32_e32 v96, 0xcf800000, v97
	v_cvt_u32_f32_e32 v96, v96
	v_cvt_u32_f32_e32 v97, v97
	v_lshl_add_u64 v[98:99], v[148:149], 3, s[12:13]
	global_atomic_add_x2 v[98:99], v[96:97], off
.LBB0_992:
	s_or_b64 exec, exec, s[42:43]
	v_or_b32_e32 v96, 48, v146
	s_waitcnt lgkmcnt(0)
	v_ashrrev_i32_e32 v97, 31, v96
	v_lshlrev_b64 v[98:99], 11, v[96:97]
	v_lshl_add_u64 v[98:99], s[26:27], 0, v[98:99]
	v_lshl_add_u64 v[100:101], v[144:145], 1, v[98:99]
	s_waitcnt vmcnt(24)
	v_mov_b64_e32 v[122:123], v[186:187]
	v_mov_b64_e32 v[120:121], v[188:189]
	v_mov_b64_e32 v[118:119], v[190:191]
	v_mov_b64_e32 v[116:117], v[192:193]
	v_lshlrev_b32_e32 v108, 16, v122
	v_add_f32_e32 v92, v92, v108
	v_and_b32_e32 v108, 0xffff0000, v122
	v_add_f32_e32 v93, v93, v108
	v_lshlrev_b32_e32 v108, 16, v123
	v_add_f32_e32 v94, v94, v108
	v_and_b32_e32 v108, 0xffff0000, v123
	v_add_f32_e32 v95, v95, v108
	v_mul_f32_e32 v108, v93, v93
	v_mul_f32_e32 v109, v95, v95
	v_fmac_f32_e32 v108, v92, v92
	v_fmac_f32_e32 v109, v94, v94
	v_cvt_pk_bf16_f32 v92, v92, v93
	v_cvt_pk_bf16_f32 v93, v94, v95
	v_lshlrev_b32_e32 v94, 16, v120
	v_add_f32_e32 v88, v88, v94
	v_and_b32_e32 v94, 0xffff0000, v120
	v_add_f32_e32 v89, v89, v94
	v_lshlrev_b32_e32 v94, 16, v121
	v_add_f32_e32 v90, v90, v94
	v_and_b32_e32 v94, 0xffff0000, v121
	v_add_f32_e32 v91, v91, v94
	v_mul_f32_e32 v94, v89, v89
	v_mul_f32_e32 v95, v91, v91
	v_fmac_f32_e32 v94, v88, v88
	v_fmac_f32_e32 v95, v90, v90
	v_add_f32_e32 v108, v108, v109
	v_add_f32_e32 v94, v94, v95
	v_add_f32_e32 v108, v108, v94
	v_cvt_pk_bf16_f32 v94, v88, v89
	v_lshlrev_b32_e32 v88, 16, v118
	v_add_f32_e32 v84, v84, v88
	v_and_b32_e32 v88, 0xffff0000, v118
	v_add_f32_e32 v85, v85, v88
	v_lshlrev_b32_e32 v88, 16, v119
	v_add_f32_e32 v86, v86, v88
	v_and_b32_e32 v88, 0xffff0000, v119
	v_add_f32_e32 v87, v87, v88
	v_mul_f32_e32 v88, v85, v85
	v_mul_f32_e32 v89, v87, v87
	v_cvt_pk_bf16_f32 v95, v90, v91
	v_fmac_f32_e32 v88, v84, v84
	v_fmac_f32_e32 v89, v86, v86
	v_cvt_pk_bf16_f32 v84, v84, v85
	v_cvt_pk_bf16_f32 v85, v86, v87
	v_lshlrev_b32_e32 v86, 16, v116
	v_add_f32_e32 v80, v80, v86
	v_and_b32_e32 v86, 0xffff0000, v116
	v_add_f32_e32 v81, v81, v86
	v_lshlrev_b32_e32 v86, 16, v117
	v_add_f32_e32 v82, v82, v86
	v_and_b32_e32 v86, 0xffff0000, v117
	v_add_f32_e32 v83, v83, v86
	v_mul_f32_e32 v86, v81, v81
	v_mul_f32_e32 v87, v83, v83
	v_add_f32_e32 v88, v88, v89
	v_fmac_f32_e32 v86, v80, v80
	v_fmac_f32_e32 v87, v82, v82
	v_add_f32_e32 v89, v86, v87
	v_cvt_pk_bf16_f32 v86, v80, v81
	v_cvt_pk_bf16_f32 v87, v82, v83
	v_add_f32_e32 v82, v108, v88
	v_add_f32_e32 v88, v82, v89
	ds_bpermute_b32 v89, v124, v88
	v_lshl_add_u64 v[80:81], s[44:45], 1, v[114:115]
	v_lshl_add_u64 v[80:81], v[80:81], 0, s[8:9]
	v_lshl_add_u64 v[80:81], v[80:81], 0, v[132:133]
	v_mov_b32_e32 v143, v133
	v_lshl_add_u64 v[82:83], v[80:81], 0, v[142:143]
	s_waitcnt lgkmcnt(0)
	v_add_f32_e32 v80, v88, v89
	ds_bpermute_b32 v81, v125, v80
	v_permlane16_swap_b32_e32 v92, v94
	v_permlane16_swap_b32_e32 v93, v95
	v_permlane16_swap_b32_e32 v84, v86
	v_permlane16_swap_b32_e32 v85, v87
	global_store_dwordx4 v[82:83], v[92:95], off
	global_store_dwordx4 v[82:83], v[84:87], off offset:256
	s_and_saveexec_b64 s[42:43], s[4:5]
	s_cbranch_execz .LBB0_994
	s_waitcnt lgkmcnt(0)
	v_add_f32_e32 v80, v80, v81
	v_mul_f32_e32 v80, 0x4f800000, v80
	v_trunc_f32_e32 v80, v80
	v_mul_f32_e32 v81, 0x2f800000, v80
	v_floor_f32_e32 v81, v81
	v_fmac_f32_e32 v80, 0xcf800000, v81
	v_cvt_u32_f32_e32 v80, v80
	v_cvt_u32_f32_e32 v81, v81
	v_lshl_add_u64 v[82:83], v[112:113], 3, s[12:13]
	global_atomic_add_x2 v[82:83], v[80:81], off
; __device__ __forceinline__ unsigned cvt_pk_bf16(float lo, float hi) { unsigned r; asm volatile("v_cvt_pk_bf16_f32 %0, %1, %2" : "=v"(r) : "v"(lo), "v"(hi)); return r; }
;     __device__ __forceinline__ void operator()(const f32x4 (&acc)[2][2][4][2], const Unit& u, int wr, int wc, int fr, int fq, PG8_LAS unsigned char*) const {
;     ...
;         for (int ri = 0; ri < 8; ++ri) {
;             const int ai = ri >> 2, m = ri & 3;
;             const int row = u.pm * BM + ai * HALF + wr * 64 + m * 16 + fr; float ss = 0.f;
;             if (ri < 7) { const int ai2 = (ri + 1) >> 2, m2 = (ri + 1) & 3; const size_t off2 = (size_t)(u.pm * BM + ai2 * HALF + wr * 64 + m2 * 16 + fr) * 1024 + col0;
; #pragma unroll
;                 for (int bj = 0; bj < 2; ++bj)
; #pragma unroll
;                     for (int n = 0; n < 2; ++n) nxt[bj][n] = *(const u32x2*)(xb + off2 + bj * HALF + n * 16); }
; #pragma unroll
;             for (int bj = 0; bj < 2; ++bj)
; #pragma unroll
;                 for (int n = 0; n < 2; ++n) { const u32x2 bb = cur[bj][n]; const f32x4 av = acc[ai][bj][m][n];
;                     const float o0 = __uint_as_float(bb.x << 16) + av[0], o1 = __uint_as_float(bb.x & 0xffff0000u) + av[1], o2 = __uint_as_float(bb.y << 16) + av[2], o3 = __uint_as_float(bb.y & 0xffff0000u) + av[3];
;                     ss += (o0 * o0 + o1 * o1) + (o2 * o2 + o3 * o3);
;                     cur[bj][n].x = cvt_pk_bf16(o0, o1); cur[bj][n].y = cvt_pk_bf16(o2, o3); }
; #pragma unroll
;             for (int bj = 0; bj < 2; ++bj) { unsigned a0 = cur[bj][0].x, a1 = cur[bj][0].y, b0 = cur[bj][1].x, b1 = cur[bj][1].y;
;                 { auto r = __builtin_amdgcn_permlane16_swap(a0, b0, false, false); a0 = r[0]; b0 = r[1]; }
;                 { auto r = __builtin_amdgcn_permlane16_swap(a1, b1, false, false); a1 = r[0]; b1 = r[1]; }
;                 u32x4 w; w.x = a0; w.y = a1; w.z = b0; w.w = b1; *(u32x4*)(xb + (size_t)row * 1024 + u.pn * BM + wc * 32 + bj * HALF + ((fq & 1) << 4) + ((fq >> 1) << 3)) = w; }
;             ss += __shfl_xor(ss, 16); ss += __shfl_xor(ss, 32);
;             if (fq == 0) atomicAdd(rss_next + row, (unsigned long long)(ss * 4294967296.0f));
.LBB0_994:
	s_or_b64 exec, exec, s[42:43]
	v_add_u32_e32 v80, 0x80, v146
	s_waitcnt lgkmcnt(0)
	v_ashrrev_i32_e32 v81, 31, v80
	v_lshlrev_b64 v[82:83], 11, v[80:81]
	v_lshl_add_u64 v[82:83], s[26:27], 0, v[82:83]
	v_lshl_add_u64 v[84:85], v[144:145], 1, v[82:83]
	s_waitcnt vmcnt(22)
	v_mov_b64_e32 v[106:107], v[194:195]
	v_mov_b64_e32 v[104:105], v[196:197]
	v_mov_b64_e32 v[102:103], v[198:199]
	v_mov_b64_e32 v[100:101], v[200:201]
	v_lshlrev_b32_e32 v92, 16, v106
	v_add_f32_e32 v76, v76, v92
	v_and_b32_e32 v92, 0xffff0000, v106
	v_add_f32_e32 v77, v77, v92
	v_lshlrev_b32_e32 v92, 16, v107
	v_add_f32_e32 v78, v78, v92
	v_and_b32_e32 v92, 0xffff0000, v107
	v_add_f32_e32 v79, v79, v92
	v_mul_f32_e32 v92, v77, v77
	v_mul_f32_e32 v93, v79, v79
	v_fmac_f32_e32 v92, v76, v76
	v_fmac_f32_e32 v93, v78, v78
	v_cvt_pk_bf16_f32 v76, v76, v77
	v_cvt_pk_bf16_f32 v77, v78, v79
	v_lshlrev_b32_e32 v78, 16, v104
	v_add_f32_e32 v72, v72, v78
	v_and_b32_e32 v78, 0xffff0000, v104
	v_add_f32_e32 v73, v73, v78
	v_lshlrev_b32_e32 v78, 16, v105
	v_add_f32_e32 v74, v74, v78
	v_and_b32_e32 v78, 0xffff0000, v105
	v_add_f32_e32 v75, v75, v78
	v_mul_f32_e32 v78, v73, v73
	v_mul_f32_e32 v79, v75, v75
	v_fmac_f32_e32 v78, v72, v72
	v_fmac_f32_e32 v79, v74, v74
	v_add_f32_e32 v92, v92, v93
	v_add_f32_e32 v78, v78, v79
	v_add_f32_e32 v92, v92, v78
	v_cvt_pk_bf16_f32 v78, v72, v73
	v_lshlrev_b32_e32 v72, 16, v102
	v_add_f32_e32 v68, v68, v72
	v_and_b32_e32 v72, 0xffff0000, v102
	v_add_f32_e32 v69, v69, v72
	v_lshlrev_b32_e32 v72, 16, v103
	v_add_f32_e32 v70, v70, v72
	v_and_b32_e32 v72, 0xffff0000, v103
	v_add_f32_e32 v71, v71, v72
	v_mul_f32_e32 v72, v69, v69
	v_mul_f32_e32 v73, v71, v71
	v_cvt_pk_bf16_f32 v79, v74, v75
	v_fmac_f32_e32 v72, v68, v68
	v_fmac_f32_e32 v73, v70, v70
	v_cvt_pk_bf16_f32 v68, v68, v69
	v_cvt_pk_bf16_f32 v69, v70, v71
	v_lshlrev_b32_e32 v70, 16, v100
	v_add_f32_e32 v64, v64, v70
	v_and_b32_e32 v70, 0xffff0000, v100
	v_add_f32_e32 v65, v65, v70
	v_lshlrev_b32_e32 v70, 16, v101
	v_add_f32_e32 v66, v66, v70
	v_and_b32_e32 v70, 0xffff0000, v101
	v_add_f32_e32 v67, v67, v70
	v_mul_f32_e32 v70, v65, v65
	v_mul_f32_e32 v71, v67, v67
	v_add_f32_e32 v72, v72, v73
	v_fmac_f32_e32 v70, v64, v64
	v_fmac_f32_e32 v71, v66, v66
	v_add_f32_e32 v73, v70, v71
	v_cvt_pk_bf16_f32 v70, v64, v65
	v_cvt_pk_bf16_f32 v71, v66, v67
	v_add_f32_e32 v66, v92, v72
	v_add_f32_e32 v72, v66, v73
	ds_bpermute_b32 v73, v124, v72
	v_lshl_add_u64 v[64:65], s[44:45], 1, v[98:99]
	v_lshl_add_u64 v[64:65], v[64:65], 0, s[8:9]
	v_lshl_add_u64 v[64:65], v[64:65], 0, v[132:133]
	v_lshl_add_u64 v[66:67], v[64:65], 0, v[142:143]
	s_waitcnt lgkmcnt(0)
	v_add_f32_e32 v64, v72, v73
	ds_bpermute_b32 v65, v125, v64
	v_permlane16_swap_b32_e32 v76, v78
	v_permlane16_swap_b32_e32 v77, v79
	v_permlane16_swap_b32_e32 v68, v70
	v_permlane16_swap_b32_e32 v69, v71
	global_store_dwordx4 v[66:67], v[76:79], off
	global_store_dwordx4 v[66:67], v[68:71], off offset:256
	s_and_saveexec_b64 s[42:43], s[4:5]
	s_cbranch_execz .LBB0_996
	s_waitcnt lgkmcnt(0)
	v_add_f32_e32 v64, v64, v65
	v_mul_f32_e32 v64, 0x4f800000, v64
	v_trunc_f32_e32 v64, v64
	v_mul_f32_e32 v65, 0x2f800000, v64
	v_floor_f32_e32 v65, v65
	v_fmac_f32_e32 v64, 0xcf800000, v65
	v_cvt_u32_f32_e32 v64, v64
	v_cvt_u32_f32_e32 v65, v65
	v_lshl_add_u64 v[66:67], v[96:97], 3, s[12:13]
	global_atomic_add_x2 v[66:67], v[64:65], off
.LBB0_996:
	s_or_b64 exec, exec, s[42:43]
	v_or_b32_e32 v64, 16, v80
	s_waitcnt lgkmcnt(0)
	v_ashrrev_i32_e32 v65, 31, v64
	v_lshlrev_b64 v[66:67], 11, v[64:65]
	v_lshl_add_u64 v[66:67], s[26:27], 0, v[66:67]
	v_lshl_add_u64 v[68:69], v[144:145], 1, v[66:67]
	s_waitcnt vmcnt(20)
	v_mov_b64_e32 v[90:91], v[202:203]
	v_mov_b64_e32 v[88:89], v[204:205]
	v_mov_b64_e32 v[86:87], v[206:207]
	v_mov_b64_e32 v[84:85], v[208:209]
	v_lshlrev_b32_e32 v76, 16, v90
	v_add_f32_e32 v60, v60, v76
	v_and_b32_e32 v76, 0xffff0000, v90
	v_add_f32_e32 v61, v61, v76
	v_lshlrev_b32_e32 v76, 16, v91
	v_add_f32_e32 v62, v62, v76
	v_and_b32_e32 v76, 0xffff0000, v91
	v_add_f32_e32 v63, v63, v76
	v_mul_f32_e32 v76, v61, v61
	v_mul_f32_e32 v77, v63, v63
	v_fmac_f32_e32 v76, v60, v60
	v_fmac_f32_e32 v77, v62, v62
	v_cvt_pk_bf16_f32 v60, v60, v61
	v_cvt_pk_bf16_f32 v61, v62, v63
	v_lshlrev_b32_e32 v62, 16, v88
	v_add_f32_e32 v56, v56, v62
	v_and_b32_e32 v62, 0xffff0000, v88
	v_add_f32_e32 v57, v57, v62
	v_lshlrev_b32_e32 v62, 16, v89
	v_add_f32_e32 v58, v58, v62
	v_and_b32_e32 v62, 0xffff0000, v89
	v_add_f32_e32 v59, v59, v62
	v_mul_f32_e32 v62, v57, v57
	v_mul_f32_e32 v63, v59, v59
	v_fmac_f32_e32 v62, v56, v56
	v_fmac_f32_e32 v63, v58, v58
	v_add_f32_e32 v76, v76, v77
	v_add_f32_e32 v62, v62, v63
	v_add_f32_e32 v76, v76, v62
	v_cvt_pk_bf16_f32 v62, v56, v57
	v_lshlrev_b32_e32 v56, 16, v86
	v_add_f32_e32 v52, v52, v56
	v_and_b32_e32 v56, 0xffff0000, v86
	v_add_f32_e32 v53, v53, v56
	v_lshlrev_b32_e32 v56, 16, v87
	v_add_f32_e32 v54, v54, v56
	v_and_b32_e32 v56, 0xffff0000, v87
	v_add_f32_e32 v55, v55, v56
	v_mul_f32_e32 v56, v53, v53
	v_mul_f32_e32 v57, v55, v55
	v_cvt_pk_bf16_f32 v63, v58, v59
	v_fmac_f32_e32 v56, v52, v52
	v_fmac_f32_e32 v57, v54, v54
	v_cvt_pk_bf16_f32 v52, v52, v53
	v_cvt_pk_bf16_f32 v53, v54, v55
	v_lshlrev_b32_e32 v54, 16, v84
	v_add_f32_e32 v48, v48, v54
	v_and_b32_e32 v54, 0xffff0000, v84
	v_add_f32_e32 v49, v49, v54
	v_lshlrev_b32_e32 v54, 16, v85
	v_add_f32_e32 v50, v50, v54
	v_and_b32_e32 v54, 0xffff0000, v85
	v_add_f32_e32 v51, v51, v54
	v_mul_f32_e32 v54, v49, v49
	v_mul_f32_e32 v55, v51, v51
	v_add_f32_e32 v56, v56, v57
	v_fmac_f32_e32 v54, v48, v48
	v_fmac_f32_e32 v55, v50, v50
	v_add_f32_e32 v57, v54, v55
	v_cvt_pk_bf16_f32 v54, v48, v49
	v_cvt_pk_bf16_f32 v55, v50, v51
	v_add_f32_e32 v50, v76, v56
	v_add_f32_e32 v56, v50, v57
	ds_bpermute_b32 v57, v124, v56
	v_lshl_add_u64 v[48:49], s[44:45], 1, v[82:83]
	v_lshl_add_u64 v[48:49], v[48:49], 0, s[8:9]
	v_lshl_add_u64 v[48:49], v[48:49], 0, v[132:133]
	v_mov_b32_e32 v143, v133
	v_lshl_add_u64 v[50:51], v[48:49], 0, v[142:143]
	s_waitcnt lgkmcnt(0)
	v_add_f32_e32 v48, v56, v57
	ds_bpermute_b32 v49, v125, v48
	v_permlane16_swap_b32_e32 v60, v62
	v_permlane16_swap_b32_e32 v61, v63
	v_permlane16_swap_b32_e32 v52, v54
	v_permlane16_swap_b32_e32 v53, v55
	global_store_dwordx4 v[50:51], v[60:63], off
	global_store_dwordx4 v[50:51], v[52:55], off offset:256
	s_and_saveexec_b64 s[42:43], s[4:5]
	s_cbranch_execz .LBB0_998
	s_waitcnt lgkmcnt(0)
	v_add_f32_e32 v48, v48, v49
	v_mul_f32_e32 v48, 0x4f800000, v48
	v_trunc_f32_e32 v48, v48
	v_mul_f32_e32 v49, 0x2f800000, v48
	v_floor_f32_e32 v49, v49
	v_fmac_f32_e32 v48, 0xcf800000, v49
	v_cvt_u32_f32_e32 v48, v48
	v_cvt_u32_f32_e32 v49, v49
	v_lshl_add_u64 v[50:51], v[80:81], 3, s[12:13]
	global_atomic_add_x2 v[50:51], v[48:49], off
; __device__ __forceinline__ unsigned cvt_pk_bf16(float lo, float hi) { unsigned r; asm volatile("v_cvt_pk_bf16_f32 %0, %1, %2" : "=v"(r) : "v"(lo), "v"(hi)); return r; }
;     __device__ __forceinline__ void operator()(const f32x4 (&acc)[2][2][4][2], const Unit& u, int wr, int wc, int fr, int fq, PG8_LAS unsigned char*) const {
;     ...
;         for (int ri = 0; ri < 8; ++ri) {
;             const int ai = ri >> 2, m = ri & 3;
;             const int row = u.pm * BM + ai * HALF + wr * 64 + m * 16 + fr; float ss = 0.f;
;             if (ri < 7) { const int ai2 = (ri + 1) >> 2, m2 = (ri + 1) & 3; const size_t off2 = (size_t)(u.pm * BM + ai2 * HALF + wr * 64 + m2 * 16 + fr) * 1024 + col0;
; #pragma unroll
;                 for (int bj = 0; bj < 2; ++bj)
; #pragma unroll
;                     for (int n = 0; n < 2; ++n) nxt[bj][n] = *(const u32x2*)(xb + off2 + bj * HALF + n * 16); }
; #pragma unroll
;             for (int bj = 0; bj < 2; ++bj)
; #pragma unroll
;                 for (int n = 0; n < 2; ++n) { const u32x2 bb = cur[bj][n]; const f32x4 av = acc[ai][bj][m][n];
;                     const float o0 = __uint_as_float(bb.x << 16) + av[0], o1 = __uint_as_float(bb.x & 0xffff0000u) + av[1], o2 = __uint_as_float(bb.y << 16) + av[2], o3 = __uint_as_float(bb.y & 0xffff0000u) + av[3];
;                     ss += (o0 * o0 + o1 * o1) + (o2 * o2 + o3 * o3);
;                     cur[bj][n].x = cvt_pk_bf16(o0, o1); cur[bj][n].y = cvt_pk_bf16(o2, o3); }
; #pragma unroll
;             for (int bj = 0; bj < 2; ++bj) { unsigned a0 = cur[bj][0].x, a1 = cur[bj][0].y, b0 = cur[bj][1].x, b1 = cur[bj][1].y;
;                 { auto r = __builtin_amdgcn_permlane16_swap(a0, b0, false, false); a0 = r[0]; b0 = r[1]; }
;                 { auto r = __builtin_amdgcn_permlane16_swap(a1, b1, false, false); a1 = r[0]; b1 = r[1]; }
;                 u32x4 w; w.x = a0; w.y = a1; w.z = b0; w.w = b1; *(u32x4*)(xb + (size_t)row * 1024 + u.pn * BM + wc * 32 + bj * HALF + ((fq & 1) << 4) + ((fq >> 1) << 3)) = w; }
;             ss += __shfl_xor(ss, 16); ss += __shfl_xor(ss, 32);
;             if (fq == 0) atomicAdd(rss_next + row, (unsigned long long)(ss * 4294967296.0f));
.LBB0_998:
	s_or_b64 exec, exec, s[42:43]
	v_or_b32_e32 v48, 32, v80
	s_waitcnt lgkmcnt(0)
	v_ashrrev_i32_e32 v49, 31, v48
	v_lshlrev_b64 v[50:51], 11, v[48:49]
	v_lshl_add_u64 v[50:51], s[26:27], 0, v[50:51]
	v_lshl_add_u64 v[52:53], v[144:145], 1, v[50:51]
	s_waitcnt vmcnt(18)
	v_mov_b64_e32 v[74:75], v[210:211]
	v_mov_b64_e32 v[72:73], v[212:213]
	v_mov_b64_e32 v[70:71], v[216:217]
	v_mov_b64_e32 v[68:69], v[218:219]
	v_lshlrev_b32_e32 v60, 16, v74
	v_add_f32_e32 v44, v44, v60
	v_and_b32_e32 v60, 0xffff0000, v74
	v_add_f32_e32 v45, v45, v60
	v_lshlrev_b32_e32 v60, 16, v75
	v_add_f32_e32 v46, v46, v60
	v_and_b32_e32 v60, 0xffff0000, v75
	v_add_f32_e32 v47, v47, v60
	v_mul_f32_e32 v60, v45, v45
	v_mul_f32_e32 v61, v47, v47
	v_fmac_f32_e32 v60, v44, v44
	v_fmac_f32_e32 v61, v46, v46
	v_cvt_pk_bf16_f32 v44, v44, v45
	v_cvt_pk_bf16_f32 v45, v46, v47
	v_lshlrev_b32_e32 v46, 16, v72
	v_add_f32_e32 v40, v40, v46
	v_and_b32_e32 v46, 0xffff0000, v72
	v_add_f32_e32 v41, v41, v46
	v_lshlrev_b32_e32 v46, 16, v73
	v_add_f32_e32 v42, v42, v46
	v_and_b32_e32 v46, 0xffff0000, v73
	v_add_f32_e32 v43, v43, v46
	v_mul_f32_e32 v46, v41, v41
	v_mul_f32_e32 v47, v43, v43
	v_fmac_f32_e32 v46, v40, v40
	v_fmac_f32_e32 v47, v42, v42
	v_add_f32_e32 v60, v60, v61
	v_add_f32_e32 v46, v46, v47
	v_add_f32_e32 v60, v60, v46
	v_cvt_pk_bf16_f32 v46, v40, v41
	v_lshlrev_b32_e32 v40, 16, v70
	v_add_f32_e32 v36, v36, v40
	v_and_b32_e32 v40, 0xffff0000, v70
	v_add_f32_e32 v37, v37, v40
	v_lshlrev_b32_e32 v40, 16, v71
	v_add_f32_e32 v38, v38, v40
	v_and_b32_e32 v40, 0xffff0000, v71
	v_add_f32_e32 v39, v39, v40
	v_mul_f32_e32 v40, v37, v37
	v_mul_f32_e32 v41, v39, v39
	v_cvt_pk_bf16_f32 v47, v42, v43
	v_fmac_f32_e32 v40, v36, v36
	v_fmac_f32_e32 v41, v38, v38
	v_cvt_pk_bf16_f32 v36, v36, v37
	v_cvt_pk_bf16_f32 v37, v38, v39
	v_lshlrev_b32_e32 v38, 16, v68
	v_add_f32_e32 v32, v32, v38
	v_and_b32_e32 v38, 0xffff0000, v68
	v_add_f32_e32 v33, v33, v38
	v_lshlrev_b32_e32 v38, 16, v69
	v_add_f32_e32 v34, v34, v38
	v_and_b32_e32 v38, 0xffff0000, v69
	v_add_f32_e32 v35, v35, v38
	v_mul_f32_e32 v38, v33, v33
	v_mul_f32_e32 v39, v35, v35
	v_add_f32_e32 v40, v40, v41
	v_fmac_f32_e32 v38, v32, v32
	v_fmac_f32_e32 v39, v34, v34
	v_add_f32_e32 v41, v38, v39
	v_cvt_pk_bf16_f32 v38, v32, v33
	v_cvt_pk_bf16_f32 v39, v34, v35
	v_add_f32_e32 v34, v60, v40
	v_add_f32_e32 v40, v34, v41
	ds_bpermute_b32 v41, v124, v40
	v_lshl_add_u64 v[32:33], s[44:45], 1, v[66:67]
	v_lshl_add_u64 v[32:33], v[32:33], 0, s[8:9]
	v_lshl_add_u64 v[32:33], v[32:33], 0, v[132:133]
	v_lshl_add_u64 v[34:35], v[32:33], 0, v[142:143]
	s_waitcnt lgkmcnt(0)
	v_add_f32_e32 v32, v40, v41
	ds_bpermute_b32 v33, v125, v32
	v_permlane16_swap_b32_e32 v44, v46
	v_permlane16_swap_b32_e32 v45, v47
	v_permlane16_swap_b32_e32 v36, v38
	v_permlane16_swap_b32_e32 v37, v39
	global_store_dwordx4 v[34:35], v[44:47], off
	global_store_dwordx4 v[34:35], v[36:39], off offset:256
	s_and_saveexec_b64 s[42:43], s[4:5]
	s_cbranch_execz .LBB0_1000
	s_waitcnt lgkmcnt(0)
	v_add_f32_e32 v32, v32, v33
	v_mul_f32_e32 v32, 0x4f800000, v32
	v_trunc_f32_e32 v32, v32
	v_mul_f32_e32 v33, 0x2f800000, v32
	v_floor_f32_e32 v33, v33
	v_fmac_f32_e32 v32, 0xcf800000, v33
	v_cvt_u32_f32_e32 v32, v32
	v_cvt_u32_f32_e32 v33, v33
	v_lshl_add_u64 v[34:35], v[64:65], 3, s[12:13]
	global_atomic_add_x2 v[34:35], v[32:33], off
; __device__ __forceinline__ unsigned cvt_pk_bf16(float lo, float hi) { unsigned r; asm volatile("v_cvt_pk_bf16_f32 %0, %1, %2" : "=v"(r) : "v"(lo), "v"(hi)); return r; }
;     __device__ __forceinline__ void operator()(const f32x4 (&acc)[2][2][4][2], const Unit& u, int wr, int wc, int fr, int fq, PG8_LAS unsigned char*) const {
;     ...
;         for (int ri = 0; ri < 8; ++ri) {
;             const int ai = ri >> 2, m = ri & 3;
;             const int row = u.pm * BM + ai * HALF + wr * 64 + m * 16 + fr; float ss = 0.f;
;             if (ri < 7) { const int ai2 = (ri + 1) >> 2, m2 = (ri + 1) & 3; const size_t off2 = (size_t)(u.pm * BM + ai2 * HALF + wr * 64 + m2 * 16 + fr) * 1024 + col0;
; #pragma unroll
;                 for (int bj = 0; bj < 2; ++bj)
; #pragma unroll
;                     for (int n = 0; n < 2; ++n) nxt[bj][n] = *(const u32x2*)(xb + off2 + bj * HALF + n * 16); }
; #pragma unroll
;             for (int bj = 0; bj < 2; ++bj)
; #pragma unroll
;                 for (int n = 0; n < 2; ++n) { const u32x2 bb = cur[bj][n]; const f32x4 av = acc[ai][bj][m][n];
;                     const float o0 = __uint_as_float(bb.x << 16) + av[0], o1 = __uint_as_float(bb.x & 0xffff0000u) + av[1], o2 = __uint_as_float(bb.y << 16) + av[2], o3 = __uint_as_float(bb.y & 0xffff0000u) + av[3];
;                     ss += (o0 * o0 + o1 * o1) + (o2 * o2 + o3 * o3);
;                     cur[bj][n].x = cvt_pk_bf16(o0, o1); cur[bj][n].y = cvt_pk_bf16(o2, o3); }
; #pragma unroll
;             for (int bj = 0; bj < 2; ++bj) { unsigned a0 = cur[bj][0].x, a1 = cur[bj][0].y, b0 = cur[bj][1].x, b1 = cur[bj][1].y;
;                 { auto r = __builtin_amdgcn_permlane16_swap(a0, b0, false, false); a0 = r[0]; b0 = r[1]; }
;                 { auto r = __builtin_amdgcn_permlane16_swap(a1, b1, false, false); a1 = r[0]; b1 = r[1]; }
;                 u32x4 w; w.x = a0; w.y = a1; w.z = b0; w.w = b1; *(u32x4*)(xb + (size_t)row * 1024 + u.pn * BM + wc * 32 + bj * HALF + ((fq & 1) << 4) + ((fq >> 1) << 3)) = w; }
;             ss += __shfl_xor(ss, 16); ss += __shfl_xor(ss, 32);
;             if (fq == 0) atomicAdd(rss_next + row, (unsigned long long)(ss * 4294967296.0f));
.LBB0_1000:
	s_or_b64 exec, exec, s[42:43]
	v_or_b32_e32 v32, 48, v80
	s_waitcnt lgkmcnt(0)
	v_ashrrev_i32_e32 v33, 31, v32
	v_lshlrev_b64 v[34:35], 11, v[32:33]
	v_lshl_add_u64 v[34:35], s[26:27], 0, v[34:35]
	v_lshl_add_u64 v[36:37], v[144:145], 1, v[34:35]
	s_waitcnt vmcnt(16)
	v_mov_b64_e32 v[58:59], v[220:221]
	v_mov_b64_e32 v[56:57], v[222:223]
	v_mov_b64_e32 v[54:55], v[224:225]
	v_mov_b64_e32 v[52:53], v[226:227]
	v_lshlrev_b32_e32 v44, 16, v58
	v_add_f32_e32 v28, v28, v44
	v_and_b32_e32 v44, 0xffff0000, v58
	v_add_f32_e32 v29, v29, v44
	v_lshlrev_b32_e32 v44, 16, v59
	v_add_f32_e32 v30, v30, v44
	v_and_b32_e32 v44, 0xffff0000, v59
	v_add_f32_e32 v31, v31, v44
	v_mul_f32_e32 v44, v29, v29
	v_mul_f32_e32 v45, v31, v31
	v_fmac_f32_e32 v44, v28, v28
	v_fmac_f32_e32 v45, v30, v30
	v_cvt_pk_bf16_f32 v28, v28, v29
	v_cvt_pk_bf16_f32 v29, v30, v31
	v_lshlrev_b32_e32 v30, 16, v56
	v_add_f32_e32 v24, v24, v30
	v_and_b32_e32 v30, 0xffff0000, v56
	v_add_f32_e32 v25, v25, v30
	v_lshlrev_b32_e32 v30, 16, v57
	v_add_f32_e32 v26, v26, v30
	v_and_b32_e32 v30, 0xffff0000, v57
	v_add_f32_e32 v27, v27, v30
	v_mul_f32_e32 v30, v25, v25
	v_mul_f32_e32 v31, v27, v27
	v_fmac_f32_e32 v30, v24, v24
	v_fmac_f32_e32 v31, v26, v26
	v_add_f32_e32 v44, v44, v45
	v_add_f32_e32 v30, v30, v31
	v_add_f32_e32 v44, v44, v30
	v_cvt_pk_bf16_f32 v30, v24, v25
	v_lshlrev_b32_e32 v24, 16, v54
	v_add_f32_e32 v20, v20, v24
	v_and_b32_e32 v24, 0xffff0000, v54
	v_add_f32_e32 v21, v21, v24
	v_lshlrev_b32_e32 v24, 16, v55
	v_add_f32_e32 v22, v22, v24
	v_and_b32_e32 v24, 0xffff0000, v55
	v_add_f32_e32 v23, v23, v24
	v_mul_f32_e32 v24, v21, v21
	v_mul_f32_e32 v25, v23, v23
	v_cvt_pk_bf16_f32 v31, v26, v27
	v_fmac_f32_e32 v24, v20, v20
	v_fmac_f32_e32 v25, v22, v22
	v_cvt_pk_bf16_f32 v20, v20, v21
	v_cvt_pk_bf16_f32 v21, v22, v23
	v_lshlrev_b32_e32 v22, 16, v52
	v_add_f32_e32 v16, v16, v22
	v_and_b32_e32 v22, 0xffff0000, v52
	v_add_f32_e32 v17, v17, v22
	v_lshlrev_b32_e32 v22, 16, v53
	v_add_f32_e32 v18, v18, v22
	v_and_b32_e32 v22, 0xffff0000, v53
	v_add_f32_e32 v19, v19, v22
	v_mul_f32_e32 v22, v17, v17
	v_mul_f32_e32 v23, v19, v19
	v_add_f32_e32 v24, v24, v25
	v_fmac_f32_e32 v22, v16, v16
	v_fmac_f32_e32 v23, v18, v18
	v_add_f32_e32 v25, v22, v23
	v_cvt_pk_bf16_f32 v22, v16, v17
	v_cvt_pk_bf16_f32 v23, v18, v19
	v_add_f32_e32 v18, v44, v24
	v_add_f32_e32 v24, v18, v25
	ds_bpermute_b32 v25, v124, v24
	v_lshl_add_u64 v[16:17], s[44:45], 1, v[50:51]
	v_lshl_add_u64 v[16:17], v[16:17], 0, s[8:9]
	v_lshl_add_u64 v[16:17], v[16:17], 0, v[132:133]
	v_mov_b32_e32 v143, v133
	v_lshl_add_u64 v[18:19], v[16:17], 0, v[142:143]
	s_waitcnt lgkmcnt(0)
	v_add_f32_e32 v16, v24, v25
	ds_bpermute_b32 v17, v125, v16
	v_permlane16_swap_b32_e32 v28, v30
	v_permlane16_swap_b32_e32 v29, v31
	v_permlane16_swap_b32_e32 v20, v22
	v_permlane16_swap_b32_e32 v21, v23
	global_store_dwordx4 v[18:19], v[28:31], off
	global_store_dwordx4 v[18:19], v[20:23], off offset:256
	s_and_saveexec_b64 s[42:43], s[4:5]
	s_cbranch_execz .LBB0_1002
	s_waitcnt lgkmcnt(0)
	v_add_f32_e32 v16, v16, v17
	v_mul_f32_e32 v16, 0x4f800000, v16
	v_trunc_f32_e32 v16, v16
	v_mul_f32_e32 v17, 0x2f800000, v16
	v_floor_f32_e32 v17, v17
	v_fmac_f32_e32 v16, 0xcf800000, v17
	v_cvt_u32_f32_e32 v16, v16
	v_cvt_u32_f32_e32 v17, v17
	v_lshl_add_u64 v[18:19], v[48:49], 3, s[12:13]
	global_atomic_add_x2 v[18:19], v[16:17], off
.LBB0_1002:
	s_or_b64 exec, exec, s[42:43]
	s_waitcnt vmcnt(14)
	v_mov_b64_e32 v[42:43], v[228:229]
	v_mov_b64_e32 v[40:41], v[230:231]
	v_mov_b64_e32 v[38:39], v[232:233]
	v_mov_b64_e32 v[36:37], v[234:235]
	v_lshlrev_b32_e32 v16, 16, v42
	v_add_f32_e32 v12, v12, v16
	v_and_b32_e32 v16, 0xffff0000, v42
	v_add_f32_e32 v13, v13, v16
	v_lshlrev_b32_e32 v16, 16, v43
	v_add_f32_e32 v14, v14, v16
	v_and_b32_e32 v16, 0xffff0000, v43
	v_add_f32_e32 v15, v15, v16
	v_mul_f32_e32 v16, v13, v13
	s_waitcnt lgkmcnt(0)
	v_mul_f32_e32 v17, v15, v15
	v_fmac_f32_e32 v16, v12, v12
	v_fmac_f32_e32 v17, v14, v14
	v_cvt_pk_bf16_f32 v12, v12, v13
	v_cvt_pk_bf16_f32 v13, v14, v15
	v_lshlrev_b32_e32 v14, 16, v40
	v_add_f32_e32 v8, v8, v14
	v_and_b32_e32 v14, 0xffff0000, v40
	v_add_f32_e32 v9, v9, v14
	v_lshlrev_b32_e32 v14, 16, v41
	v_add_f32_e32 v10, v10, v14
	v_and_b32_e32 v14, 0xffff0000, v41
	v_add_f32_e32 v11, v11, v14
	v_mul_f32_e32 v14, v9, v9
	v_mul_f32_e32 v15, v11, v11
	v_fmac_f32_e32 v14, v8, v8
	v_fmac_f32_e32 v15, v10, v10
	v_add_f32_e32 v16, v16, v17
	v_add_f32_e32 v14, v14, v15
	v_add_f32_e32 v16, v16, v14
	v_cvt_pk_bf16_f32 v14, v8, v9
	v_lshlrev_b32_e32 v8, 16, v38
	v_add_f32_e32 v4, v4, v8
	v_and_b32_e32 v8, 0xffff0000, v38
	v_add_f32_e32 v5, v5, v8
	v_lshlrev_b32_e32 v8, 16, v39
	v_add_f32_e32 v6, v6, v8
	v_and_b32_e32 v8, 0xffff0000, v39
	v_add_f32_e32 v7, v7, v8
	v_mul_f32_e32 v8, v5, v5
	v_mul_f32_e32 v9, v7, v7
	v_cvt_pk_bf16_f32 v15, v10, v11
	v_fmac_f32_e32 v8, v4, v4
	v_fmac_f32_e32 v9, v6, v6
	v_cvt_pk_bf16_f32 v4, v4, v5
	v_cvt_pk_bf16_f32 v5, v6, v7
	v_lshlrev_b32_e32 v6, 16, v36
	v_add_f32_e32 v0, v0, v6
	v_and_b32_e32 v6, 0xffff0000, v36
	v_add_f32_e32 v1, v1, v6
	v_lshlrev_b32_e32 v6, 16, v37
	v_add_f32_e32 v2, v2, v6
	v_and_b32_e32 v6, 0xffff0000, v37
	v_add_f32_e32 v3, v3, v6
	v_mul_f32_e32 v6, v1, v1
	v_mul_f32_e32 v7, v3, v3
	v_add_f32_e32 v8, v8, v9
	v_fmac_f32_e32 v6, v0, v0
	v_fmac_f32_e32 v7, v2, v2
	v_add_f32_e32 v9, v6, v7
	v_cvt_pk_bf16_f32 v6, v0, v1
	v_cvt_pk_bf16_f32 v7, v2, v3
	v_add_f32_e32 v2, v16, v8
	v_add_f32_e32 v8, v2, v9
	ds_bpermute_b32 v9, v124, v8
	v_lshl_add_u64 v[0:1], s[44:45], 1, v[34:35]
	v_lshl_add_u64 v[0:1], v[0:1], 0, s[8:9]
	v_lshl_add_u64 v[0:1], v[0:1], 0, v[132:133]
	v_lshl_add_u64 v[2:3], v[0:1], 0, v[142:143]
	s_waitcnt lgkmcnt(0)
	v_add_f32_e32 v0, v8, v9
	ds_bpermute_b32 v1, v125, v0
	v_permlane16_swap_b32_e32 v12, v14
	v_permlane16_swap_b32_e32 v13, v15
	v_permlane16_swap_b32_e32 v4, v6
	v_permlane16_swap_b32_e32 v5, v7
	global_store_dwordx4 v[2:3], v[12:15], off
	global_store_dwordx4 v[2:3], v[4:7], off offset:256
	s_and_saveexec_b64 s[42:43], s[4:5]
	s_cbranch_execz .LBB0_1004
	s_waitcnt lgkmcnt(0)
	v_add_f32_e32 v0, v0, v1
	v_mul_f32_e32 v0, 0x4f800000, v0
	v_trunc_f32_e32 v0, v0
	v_mul_f32_e32 v1, 0x2f800000, v0
	v_floor_f32_e32 v1, v1
	v_fmac_f32_e32 v0, 0xcf800000, v1
	v_cvt_u32_f32_e32 v0, v0
	v_cvt_u32_f32_e32 v1, v1
	v_lshl_add_u64 v[2:3], v[32:33], 3, s[12:13]
	global_atomic_add_x2 v[2:3], v[0:1], off

;     __device__ __forceinline__ void operator()(const f32x4 (&acc)[2][2][4][2], const Unit& u, int wr, int wc, int fr, int fq, PG8_LAS unsigned char*) const {
;         const int col0 = u.pn * BM + wc * 32 + 4 * fq;
;         u32x2 cur[2][2], nxt[2][2];
;         { const size_t off = (size_t)(u.pm * BM + wr * 64 + fr) * 1024 + col0;
; #pragma unroll
;           for (int bj = 0; bj < 2; ++bj)
; #pragma unroll
;             for (int n = 0; n < 2; ++n) cur[bj][n] = *(const u32x2*)(xb + off + bj * HALF + n * 16); }
; #pragma unroll
;         for (int ri = 0; ri < 8; ++ri) {
;             const int ai = ri >> 2, m = ri & 3;
;             const int row = u.pm * BM + ai * HALF + wr * 64 + m * 16 + fr; float ss = 0.f;
;             if (ri < 7) { const int ai2 = (ri + 1) >> 2, m2 = (ri + 1) & 3; const size_t off2 = (size_t)(u.pm * BM + ai2 * HALF + wr * 64 + m2 * 16 + fr) * 1024 + col0;
; #pragma unroll
;                 for (int bj = 0; bj < 2; ++bj)
; #pragma unroll
;                     for (int n = 0; n < 2; ++n) nxt[bj][n] = *(const u32x2*)(xb + off2 + bj * HALF + n * 16); }
; #pragma unroll
;             for (int bj = 0; bj < 2; ++bj)
; #pragma unroll
;                 for (int n = 0; n < 2; ++n) { const u32x2 bb = cur[bj][n]; const f32x4 av = acc[ai][bj][m][n];
;                     const float o0 = __uint_as_float(bb.x << 16) + av[0], o1 = __uint_as_float(bb.x & 0xffff0000u) + av[1], o2 = __uint_as_float(bb.y << 16) + av[2], o3 = __uint_as_float(bb.y & 0xffff0000u) + av[3];
;                     ss += (o0 * o0 + o1 * o1) + (o2 * o2 + o3 * o3);
;                     cur[bj][n].x = cvt_pk_bf16(o0, o1); cur[bj][n].y = cvt_pk_bf16(o2, o3); }
; #pragma unroll
;             for (int bj = 0; bj < 2; ++bj) { unsigned a0 = cur[bj][0].x, a1 = cur[bj][0].y, b0 = cur[bj][1].x, b1 = cur[bj][1].y;
;                 { auto r = __builtin_amdgcn_permlane16_swap(a0, b0, false, false); a0 = r[0]; b0 = r[1]; }
;                 { auto r = __builtin_amdgcn_permlane16_swap(a1, b1, false, false); a1 = r[0]; b1 = r[1]; }
;                 u32x4 w; w.x = a0; w.y = a1; w.z = b0; w.w = b1; *(u32x4*)(xb + (size_t)row * 1024 + u.pn * BM + wc * 32 + bj * HALF + ((fq & 1) << 4) + ((fq >> 1) << 3)) = w; }
;             ss += __shfl_xor(ss, 16); ss += __shfl_xor(ss, 32);
;             if (fq == 0) atomicAdd(rss_next + row, (unsigned long long)(ss * 4294967296.0f));
.LBB0_1154:
	s_lshl_b32 s36, s64, 8
	v_lshl_add_u32 v146, s63, 8, v160
	v_or_b32_e32 v144, s36, v162
	v_ashrrev_i32_e32 v147, 31, v146
	v_ashrrev_i32_e32 v145, 31, v144
	v_lshlrev_b64 v[148:149], 11, v[146:147]
	v_lshl_add_u64 v[152:153], s[26:27], 0, v[148:149]
	v_lshlrev_b64 v[154:155], 1, v[144:145]
	v_lshl_add_u64 v[148:149], v[152:153], 0, v[154:155]
	global_load_dwordx2 v[168:169], v[148:149], off
	global_load_dwordx2 v[170:171], v[148:149], off offset:32
	global_load_dwordx2 v[172:173], v[148:149], off offset:256
	global_load_dwordx2 v[174:175], v[148:149], off offset:288
	v_or_b32_e32 v148, 16, v146
	v_ashrrev_i32_e32 v149, 31, v148
	v_lshlrev_b64 v[150:151], 11, v[148:149]
	s_ashr_i32 s37, s36, 31
	v_lshl_add_u64 v[150:151], s[26:27], 0, v[150:151]
	v_lshl_add_u64 v[152:153], s[36:37], 1, v[152:153]
	v_lshl_add_u64 v[176:177], v[150:151], 0, v[154:155]
	v_lshl_add_u64 v[178:179], v[152:153], 0, s[10:11]
	global_load_dwordx2 v[158:159], v[176:177], off
	global_load_dwordx2 v[156:157], v[176:177], off offset:32
	global_load_dwordx2 v[154:155], v[176:177], off offset:256
	global_load_dwordx2 v[152:153], v[176:177], off offset:288
	s_mov_b64 s[98:99], 0x8000
	v_lshl_add_u64 v[252:253], v[176:177], 0, s[98:99]
	global_load_dwordx2 v[186:187], v[252:253], off
	global_load_dwordx2 v[188:189], v[252:253], off offset:32
	global_load_dwordx2 v[190:191], v[252:253], off offset:256
	global_load_dwordx2 v[192:193], v[252:253], off offset:288
	s_mov_b64 s[98:99], 0x10000
	v_lshl_add_u64 v[252:253], v[176:177], 0, s[98:99]
	global_load_dwordx2 v[194:195], v[252:253], off
	global_load_dwordx2 v[196:197], v[252:253], off offset:32
	global_load_dwordx2 v[198:199], v[252:253], off offset:256
	global_load_dwordx2 v[200:201], v[252:253], off offset:288
	s_mov_b64 s[98:99], 0x38000
	v_lshl_add_u64 v[252:253], v[176:177], 0, s[98:99]
	global_load_dwordx2 v[202:203], v[252:253], off
	global_load_dwordx2 v[204:205], v[252:253], off offset:32
	global_load_dwordx2 v[206:207], v[252:253], off offset:256
	global_load_dwordx2 v[208:209], v[252:253], off offset:288
	s_mov_b64 s[98:99], 0x40000
	v_lshl_add_u64 v[252:253], v[176:177], 0, s[98:99]
	global_load_dwordx2 v[210:211], v[252:253], off
	global_load_dwordx2 v[212:213], v[252:253], off offset:32
	global_load_dwordx2 v[216:217], v[252:253], off offset:256
	global_load_dwordx2 v[218:219], v[252:253], off offset:288
	s_mov_b64 s[98:99], 0x48000
	v_lshl_add_u64 v[252:253], v[176:177], 0, s[98:99]
	global_load_dwordx2 v[220:221], v[252:253], off
	global_load_dwordx2 v[222:223], v[252:253], off offset:32
	global_load_dwordx2 v[224:225], v[252:253], off offset:256
	global_load_dwordx2 v[226:227], v[252:253], off offset:288
	s_mov_b64 s[98:99], 0x50000
	v_lshl_add_u64 v[252:253], v[176:177], 0, s[98:99]
	global_load_dwordx2 v[228:229], v[252:253], off
	global_load_dwordx2 v[230:231], v[252:253], off offset:32
	global_load_dwordx2 v[232:233], v[252:253], off offset:256
	global_load_dwordx2 v[234:235], v[252:253], off offset:288
	v_xor_b32_e32 v143, 16, v166
	s_waitcnt vmcnt(24)
	v_lshlrev_b32_e32 v167, 16, v168
	v_and_b32_e32 v168, 0xffff0000, v168
	v_lshlrev_b32_e32 v176, 16, v169
	v_and_b32_e32 v169, 0xffff0000, v169
	v_lshlrev_b32_e32 v177, 16, v170
	v_and_b32_e32 v170, 0xffff0000, v170
	v_lshlrev_b32_e32 v180, 16, v171
	v_and_b32_e32 v171, 0xffff0000, v171
	v_lshlrev_b32_e32 v181, 16, v172
	v_and_b32_e32 v172, 0xffff0000, v172
	v_lshlrev_b32_e32 v182, 16, v173
	v_and_b32_e32 v173, 0xffff0000, v173
	v_lshlrev_b32_e32 v183, 16, v174
	v_and_b32_e32 v174, 0xffff0000, v174
	v_add_f32_e32 v125, v125, v168
	v_add_f32_e32 v127, v127, v169
	v_add_f32_e32 v121, v121, v170
	v_add_f32_e32 v123, v123, v171
	v_lshlrev_b32_e32 v184, 16, v175
	v_and_b32_e32 v175, 0xffff0000, v175
	v_add_f32_e32 v124, v124, v167
	v_add_f32_e32 v126, v126, v176
	v_add_f32_e32 v120, v120, v177
	v_add_f32_e32 v122, v122, v180
	v_add_f32_e32 v167, v116, v181
	v_add_f32_e32 v116, v117, v172
	v_add_f32_e32 v168, v118, v182
	v_add_f32_e32 v117, v119, v173
	v_add_f32_e32 v169, v112, v183
	v_add_f32_e32 v118, v113, v174
	v_mul_f32_e32 v171, v125, v125
	v_mul_f32_e32 v172, v127, v127
	v_cvt_pk_bf16_f32 v112, v124, v125
	v_cvt_pk_bf16_f32 v113, v126, v127
	v_mul_f32_e32 v125, v121, v121
	v_mul_f32_e32 v127, v123, v123
	v_add_f32_e32 v170, v114, v184
	v_add_f32_e32 v119, v115, v175
	v_cvt_pk_bf16_f32 v114, v120, v121
	v_cvt_pk_bf16_f32 v115, v122, v123
	v_mul_f32_e32 v121, v116, v116
	v_mul_f32_e32 v123, v117, v117
	v_fmac_f32_e32 v171, v124, v124
	v_fmac_f32_e32 v172, v126, v126
	v_fmac_f32_e32 v125, v120, v120
	v_fmac_f32_e32 v127, v122, v122
	v_mul_f32_e32 v173, v118, v118
	v_mul_f32_e32 v174, v119, v119
	v_fmac_f32_e32 v121, v167, v167
	v_fmac_f32_e32 v123, v168, v168
	v_add_f32_e32 v120, v171, v172
	v_add_f32_e32 v122, v125, v127
	v_fmac_f32_e32 v173, v169, v169
	v_fmac_f32_e32 v174, v170, v170
	v_add_f32_e32 v121, v121, v123
	v_add_f32_e32 v120, v120, v122
	v_add_f32_e32 v123, v173, v174
	v_add_f32_e32 v120, v120, v121
	v_add_f32_e32 v122, v120, v123
	v_and_b32_e32 v120, 64, v166
	v_add_u32_e32 v123, 64, v120
	v_cmp_lt_i32_e32 vcc, v143, v123
	v_permlane16_swap_b32_e32 v112, v114
	s_nop 0
	v_cndmask_b32_e32 v120, v166, v143, vcc
	v_lshlrev_b32_e32 v124, 2, v120
	ds_bpermute_b32 v125, v124, v122
	v_lshl_add_u64 v[120:121], v[178:179], 0, v[132:133]
	v_mov_b32_e32 v143, v133
	v_permlane16_swap_b32_e32 v113, v115
	v_lshl_add_u64 v[120:121], v[120:121], 0, v[142:143]
	v_cvt_pk_bf16_f32 v116, v167, v116
	v_cvt_pk_bf16_f32 v117, v168, v117
	v_cvt_pk_bf16_f32 v118, v169, v118
	v_cvt_pk_bf16_f32 v119, v170, v119
	global_store_dwordx4 v[120:121], v[112:115], off
	v_permlane16_swap_b32_e32 v116, v118
	s_nop 0
	v_xor_b32_e32 v113, 32, v166
	v_cmp_lt_i32_e32 vcc, v113, v123
	s_waitcnt lgkmcnt(0)
	v_add_f32_e32 v112, v122, v125
	v_permlane16_swap_b32_e32 v117, v119
	v_cndmask_b32_e32 v113, v166, v113, vcc
	v_lshlrev_b32_e32 v125, 2, v113
	ds_bpermute_b32 v113, v125, v112
	global_store_dwordx4 v[120:121], v[116:119], off offset:256
	s_and_saveexec_b64 s[38:39], s[4:5]
	s_cbranch_execz .LBB0_1156
	s_waitcnt lgkmcnt(0)
	v_add_f32_e32 v112, v112, v113
	v_mul_f32_e32 v112, 0x4f800000, v112
	v_trunc_f32_e32 v112, v112
	v_mul_f32_e32 v113, 0x2f800000, v112
	v_floor_f32_e32 v113, v113
	v_fmac_f32_e32 v112, 0xcf800000, v113
	v_cvt_u32_f32_e32 v112, v112
	v_cvt_u32_f32_e32 v113, v113
	v_lshl_add_u64 v[114:115], v[146:147], 3, s[16:17]
	global_atomic_add_x2 v[114:115], v[112:113], off
; __device__ __forceinline__ unsigned cvt_pk_bf16(float lo, float hi) { unsigned r; asm volatile("v_cvt_pk_bf16_f32 %0, %1, %2" : "=v"(r) : "v"(lo), "v"(hi)); return r; }
;     __device__ __forceinline__ void operator()(const f32x4 (&acc)[2][2][4][2], const Unit& u, int wr, int wc, int fr, int fq, PG8_LAS unsigned char*) const {
;     ...
;         for (int ri = 0; ri < 8; ++ri) {
;             const int ai = ri >> 2, m = ri & 3;
;             const int row = u.pm * BM + ai * HALF + wr * 64 + m * 16 + fr; float ss = 0.f;
;             if (ri < 7) { const int ai2 = (ri + 1) >> 2, m2 = (ri + 1) & 3; const size_t off2 = (size_t)(u.pm * BM + ai2 * HALF + wr * 64 + m2 * 16 + fr) * 1024 + col0;
; #pragma unroll
;                 for (int bj = 0; bj < 2; ++bj)
; #pragma unroll
;                     for (int n = 0; n < 2; ++n) nxt[bj][n] = *(const u32x2*)(xb + off2 + bj * HALF + n * 16); }
; #pragma unroll
;             for (int bj = 0; bj < 2; ++bj)
; #pragma unroll
;                 for (int n = 0; n < 2; ++n) { const u32x2 bb = cur[bj][n]; const f32x4 av = acc[ai][bj][m][n];
;                     const float o0 = __uint_as_float(bb.x << 16) + av[0], o1 = __uint_as_float(bb.x & 0xffff0000u) + av[1], o2 = __uint_as_float(bb.y << 16) + av[2], o3 = __uint_as_float(bb.y & 0xffff0000u) + av[3];
;                     ss += (o0 * o0 + o1 * o1) + (o2 * o2 + o3 * o3);
;                     cur[bj][n].x = cvt_pk_bf16(o0, o1); cur[bj][n].y = cvt_pk_bf16(o2, o3); }
; #pragma unroll
;             for (int bj = 0; bj < 2; ++bj) { unsigned a0 = cur[bj][0].x, a1 = cur[bj][0].y, b0 = cur[bj][1].x, b1 = cur[bj][1].y;
;                 { auto r = __builtin_amdgcn_permlane16_swap(a0, b0, false, false); a0 = r[0]; b0 = r[1]; }
;                 { auto r = __builtin_amdgcn_permlane16_swap(a1, b1, false, false); a1 = r[0]; b1 = r[1]; }
;                 u32x4 w; w.x = a0; w.y = a1; w.z = b0; w.w = b1; *(u32x4*)(xb + (size_t)row * 1024 + u.pn * BM + wc * 32 + bj * HALF + ((fq & 1) << 4) + ((fq >> 1) << 3)) = w; }
;             ss += __shfl_xor(ss, 16); ss += __shfl_xor(ss, 32);
;             if (fq == 0) atomicAdd(rss_next + row, (unsigned long long)(ss * 4294967296.0f));
.LBB0_1156:
	s_or_b64 exec, exec, s[38:39]
	v_or_b32_e32 v112, 32, v146
	s_waitcnt lgkmcnt(0)
	v_ashrrev_i32_e32 v113, 31, v112
	v_lshlrev_b64 v[114:115], 11, v[112:113]
	v_lshl_add_u64 v[114:115], s[26:27], 0, v[114:115]
	v_lshl_add_u64 v[116:117], v[144:145], 1, v[114:115]
	v_lshlrev_b32_e32 v126, 16, v158
	v_add_f32_e32 v108, v108, v126
	v_and_b32_e32 v126, 0xffff0000, v158
	v_add_f32_e32 v109, v109, v126
	v_lshlrev_b32_e32 v126, 16, v159
	v_add_f32_e32 v110, v110, v126
	v_and_b32_e32 v126, 0xffff0000, v159
	v_add_f32_e32 v111, v111, v126
	v_mul_f32_e32 v126, v109, v109
	v_mul_f32_e32 v127, v111, v111
	v_fmac_f32_e32 v126, v108, v108
	v_fmac_f32_e32 v127, v110, v110
	v_cvt_pk_bf16_f32 v108, v108, v109
	v_cvt_pk_bf16_f32 v109, v110, v111
	v_lshlrev_b32_e32 v110, 16, v156
	v_add_f32_e32 v104, v104, v110
	v_and_b32_e32 v110, 0xffff0000, v156
	v_add_f32_e32 v105, v105, v110
	v_lshlrev_b32_e32 v110, 16, v157
	v_add_f32_e32 v106, v106, v110
	v_and_b32_e32 v110, 0xffff0000, v157
	v_add_f32_e32 v107, v107, v110
	v_mul_f32_e32 v110, v105, v105
	v_mul_f32_e32 v111, v107, v107
	v_fmac_f32_e32 v110, v104, v104
	v_fmac_f32_e32 v111, v106, v106
	v_add_f32_e32 v126, v126, v127
	v_add_f32_e32 v110, v110, v111
	v_add_f32_e32 v126, v126, v110
	v_cvt_pk_bf16_f32 v110, v104, v105
	v_lshlrev_b32_e32 v104, 16, v154
	v_add_f32_e32 v100, v100, v104
	v_and_b32_e32 v104, 0xffff0000, v154
	v_add_f32_e32 v101, v101, v104
	v_lshlrev_b32_e32 v104, 16, v155
	v_add_f32_e32 v102, v102, v104
	v_and_b32_e32 v104, 0xffff0000, v155
	v_add_f32_e32 v103, v103, v104
	v_mul_f32_e32 v104, v101, v101
	v_mul_f32_e32 v105, v103, v103
	v_cvt_pk_bf16_f32 v111, v106, v107
	v_fmac_f32_e32 v104, v100, v100
	v_fmac_f32_e32 v105, v102, v102
	v_cvt_pk_bf16_f32 v100, v100, v101
	v_cvt_pk_bf16_f32 v101, v102, v103
	v_lshlrev_b32_e32 v102, 16, v152
	v_add_f32_e32 v96, v96, v102
	v_and_b32_e32 v102, 0xffff0000, v152
	v_add_f32_e32 v97, v97, v102
	v_lshlrev_b32_e32 v102, 16, v153
	v_add_f32_e32 v98, v98, v102
	v_and_b32_e32 v102, 0xffff0000, v153
	v_add_f32_e32 v99, v99, v102
	v_mul_f32_e32 v102, v97, v97
	v_mul_f32_e32 v103, v99, v99
	v_add_f32_e32 v104, v104, v105
	v_fmac_f32_e32 v102, v96, v96
	v_fmac_f32_e32 v103, v98, v98
	v_add_f32_e32 v105, v102, v103
	v_cvt_pk_bf16_f32 v102, v96, v97
	v_cvt_pk_bf16_f32 v103, v98, v99
	v_add_f32_e32 v98, v126, v104
	v_add_f32_e32 v104, v98, v105
	ds_bpermute_b32 v105, v124, v104
	v_lshl_add_u64 v[96:97], s[36:37], 1, v[150:151]
	v_lshl_add_u64 v[96:97], v[96:97], 0, s[10:11]
	v_lshl_add_u64 v[96:97], v[96:97], 0, v[132:133]
	v_lshl_add_u64 v[98:99], v[96:97], 0, v[142:143]
	s_waitcnt lgkmcnt(0)
	v_add_f32_e32 v96, v104, v105
	ds_bpermute_b32 v97, v125, v96
	v_permlane16_swap_b32_e32 v108, v110
	v_permlane16_swap_b32_e32 v109, v111
	v_permlane16_swap_b32_e32 v100, v102
	v_permlane16_swap_b32_e32 v101, v103
	global_store_dwordx4 v[98:99], v[108:111], off
	global_store_dwordx4 v[98:99], v[100:103], off offset:256
	s_and_saveexec_b64 s[38:39], s[4:5]
	s_cbranch_execz .LBB0_1158
	s_waitcnt lgkmcnt(0)
	v_add_f32_e32 v96, v96, v97
	v_mul_f32_e32 v96, 0x4f800000, v96
	v_trunc_f32_e32 v96, v96
	v_mul_f32_e32 v97, 0x2f800000, v96
	v_floor_f32_e32 v97, v97
	v_fmac_f32_e32 v96, 0xcf800000, v97
	v_cvt_u32_f32_e32 v96, v96
	v_cvt_u32_f32_e32 v97, v97
	v_lshl_add_u64 v[98:99], v[148:149], 3, s[16:17]
	global_atomic_add_x2 v[98:99], v[96:97], off
.LBB0_1158:
	s_or_b64 exec, exec, s[38:39]
	v_or_b32_e32 v96, 48, v146
	s_waitcnt lgkmcnt(0)
	v_ashrrev_i32_e32 v97, 31, v96
	v_lshlrev_b64 v[98:99], 11, v[96:97]
	v_lshl_add_u64 v[98:99], s[26:27], 0, v[98:99]
	v_lshl_add_u64 v[100:101], v[144:145], 1, v[98:99]
	s_waitcnt vmcnt(24)
	v_mov_b64_e32 v[122:123], v[186:187]
	v_mov_b64_e32 v[120:121], v[188:189]
	v_mov_b64_e32 v[118:119], v[190:191]
	v_mov_b64_e32 v[116:117], v[192:193]
	v_lshlrev_b32_e32 v108, 16, v122
	v_add_f32_e32 v92, v92, v108
	v_and_b32_e32 v108, 0xffff0000, v122
	v_add_f32_e32 v93, v93, v108
	v_lshlrev_b32_e32 v108, 16, v123
	v_add_f32_e32 v94, v94, v108
	v_and_b32_e32 v108, 0xffff0000, v123
	v_add_f32_e32 v95, v95, v108
	v_mul_f32_e32 v108, v93, v93
	v_mul_f32_e32 v109, v95, v95
	v_fmac_f32_e32 v108, v92, v92
	v_fmac_f32_e32 v109, v94, v94
	v_cvt_pk_bf16_f32 v92, v92, v93
	v_cvt_pk_bf16_f32 v93, v94, v95
	v_lshlrev_b32_e32 v94, 16, v120
	v_add_f32_e32 v88, v88, v94
	v_and_b32_e32 v94, 0xffff0000, v120
	v_add_f32_e32 v89, v89, v94
	v_lshlrev_b32_e32 v94, 16, v121
	v_add_f32_e32 v90, v90, v94
	v_and_b32_e32 v94, 0xffff0000, v121
	v_add_f32_e32 v91, v91, v94
	v_mul_f32_e32 v94, v89, v89
	v_mul_f32_e32 v95, v91, v91
	v_fmac_f32_e32 v94, v88, v88
	v_fmac_f32_e32 v95, v90, v90
	v_add_f32_e32 v108, v108, v109
	v_add_f32_e32 v94, v94, v95
	v_add_f32_e32 v108, v108, v94
	v_cvt_pk_bf16_f32 v94, v88, v89
	v_lshlrev_b32_e32 v88, 16, v118
	v_add_f32_e32 v84, v84, v88
	v_and_b32_e32 v88, 0xffff0000, v118
	v_add_f32_e32 v85, v85, v88
	v_lshlrev_b32_e32 v88, 16, v119
	v_add_f32_e32 v86, v86, v88
	v_and_b32_e32 v88, 0xffff0000, v119
	v_add_f32_e32 v87, v87, v88
	v_mul_f32_e32 v88, v85, v85
	v_mul_f32_e32 v89, v87, v87
	v_cvt_pk_bf16_f32 v95, v90, v91
	v_fmac_f32_e32 v88, v84, v84
	v_fmac_f32_e32 v89, v86, v86
	v_cvt_pk_bf16_f32 v84, v84, v85
	v_cvt_pk_bf16_f32 v85, v86, v87
	v_lshlrev_b32_e32 v86, 16, v116
	v_add_f32_e32 v80, v80, v86
	v_and_b32_e32 v86, 0xffff0000, v116
	v_add_f32_e32 v81, v81, v86
	v_lshlrev_b32_e32 v86, 16, v117
	v_add_f32_e32 v82, v82, v86
	v_and_b32_e32 v86, 0xffff0000, v117
	v_add_f32_e32 v83, v83, v86
	v_mul_f32_e32 v86, v81, v81
	v_mul_f32_e32 v87, v83, v83
	v_add_f32_e32 v88, v88, v89
	v_fmac_f32_e32 v86, v80, v80
	v_fmac_f32_e32 v87, v82, v82
	v_add_f32_e32 v89, v86, v87
	v_cvt_pk_bf16_f32 v86, v80, v81
	v_cvt_pk_bf16_f32 v87, v82, v83
	v_add_f32_e32 v82, v108, v88
	v_add_f32_e32 v88, v82, v89
	ds_bpermute_b32 v89, v124, v88
	v_lshl_add_u64 v[80:81], s[36:37], 1, v[114:115]
	v_lshl_add_u64 v[80:81], v[80:81], 0, s[10:11]
	v_lshl_add_u64 v[80:81], v[80:81], 0, v[132:133]
	v_mov_b32_e32 v143, v133
	v_lshl_add_u64 v[82:83], v[80:81], 0, v[142:143]
	s_waitcnt lgkmcnt(0)
	v_add_f32_e32 v80, v88, v89
	ds_bpermute_b32 v81, v125, v80
	v_permlane16_swap_b32_e32 v92, v94
	v_permlane16_swap_b32_e32 v93, v95
	v_permlane16_swap_b32_e32 v84, v86
	v_permlane16_swap_b32_e32 v85, v87
	global_store_dwordx4 v[82:83], v[92:95], off
	global_store_dwordx4 v[82:83], v[84:87], off offset:256
	s_and_saveexec_b64 s[38:39], s[4:5]
	s_cbranch_execz .LBB0_1160
	s_waitcnt lgkmcnt(0)
	v_add_f32_e32 v80, v80, v81
	v_mul_f32_e32 v80, 0x4f800000, v80
	v_trunc_f32_e32 v80, v80
	v_mul_f32_e32 v81, 0x2f800000, v80
	v_floor_f32_e32 v81, v81
	v_fmac_f32_e32 v80, 0xcf800000, v81
	v_cvt_u32_f32_e32 v80, v80
	v_cvt_u32_f32_e32 v81, v81
	v_lshl_add_u64 v[82:83], v[112:113], 3, s[16:17]
	global_atomic_add_x2 v[82:83], v[80:81], off
; __device__ __forceinline__ unsigned cvt_pk_bf16(float lo, float hi) { unsigned r; asm volatile("v_cvt_pk_bf16_f32 %0, %1, %2" : "=v"(r) : "v"(lo), "v"(hi)); return r; }
;     __device__ __forceinline__ void operator()(const f32x4 (&acc)[2][2][4][2], const Unit& u, int wr, int wc, int fr, int fq, PG8_LAS unsigned char*) const {
;     ...
;         for (int ri = 0; ri < 8; ++ri) {
;             const int ai = ri >> 2, m = ri & 3;
;             const int row = u.pm * BM + ai * HALF + wr * 64 + m * 16 + fr; float ss = 0.f;
;             if (ri < 7) { const int ai2 = (ri + 1) >> 2, m2 = (ri + 1) & 3; const size_t off2 = (size_t)(u.pm * BM + ai2 * HALF + wr * 64 + m2 * 16 + fr) * 1024 + col0;
; #pragma unroll
;                 for (int bj = 0; bj < 2; ++bj)
; #pragma unroll
;                     for (int n = 0; n < 2; ++n) nxt[bj][n] = *(const u32x2*)(xb + off2 + bj * HALF + n * 16); }
; #pragma unroll
;             for (int bj = 0; bj < 2; ++bj)
; #pragma unroll
;                 for (int n = 0; n < 2; ++n) { const u32x2 bb = cur[bj][n]; const f32x4 av = acc[ai][bj][m][n];
;                     const float o0 = __uint_as_float(bb.x << 16) + av[0], o1 = __uint_as_float(bb.x & 0xffff0000u) + av[1], o2 = __uint_as_float(bb.y << 16) + av[2], o3 = __uint_as_float(bb.y & 0xffff0000u) + av[3];
;                     ss += (o0 * o0 + o1 * o1) + (o2 * o2 + o3 * o3);
;                     cur[bj][n].x = cvt_pk_bf16(o0, o1); cur[bj][n].y = cvt_pk_bf16(o2, o3); }
; #pragma unroll
;             for (int bj = 0; bj < 2; ++bj) { unsigned a0 = cur[bj][0].x, a1 = cur[bj][0].y, b0 = cur[bj][1].x, b1 = cur[bj][1].y;
;                 { auto r = __builtin_amdgcn_permlane16_swap(a0, b0, false, false); a0 = r[0]; b0 = r[1]; }
;                 { auto r = __builtin_amdgcn_permlane16_swap(a1, b1, false, false); a1 = r[0]; b1 = r[1]; }
;                 u32x4 w; w.x = a0; w.y = a1; w.z = b0; w.w = b1; *(u32x4*)(xb + (size_t)row * 1024 + u.pn * BM + wc * 32 + bj * HALF + ((fq & 1) << 4) + ((fq >> 1) << 3)) = w; }
;             ss += __shfl_xor(ss, 16); ss += __shfl_xor(ss, 32);
;             if (fq == 0) atomicAdd(rss_next + row, (unsigned long long)(ss * 4294967296.0f));
.LBB0_1160:
	s_or_b64 exec, exec, s[38:39]
	v_add_u32_e32 v80, 0x80, v146
	s_waitcnt lgkmcnt(0)
	v_ashrrev_i32_e32 v81, 31, v80
	v_lshlrev_b64 v[82:83], 11, v[80:81]
	v_lshl_add_u64 v[82:83], s[26:27], 0, v[82:83]
	v_lshl_add_u64 v[84:85], v[144:145], 1, v[82:83]
	s_waitcnt vmcnt(22)
	v_mov_b64_e32 v[106:107], v[194:195]
	v_mov_b64_e32 v[104:105], v[196:197]
	v_mov_b64_e32 v[102:103], v[198:199]
	v_mov_b64_e32 v[100:101], v[200:201]
	v_lshlrev_b32_e32 v92, 16, v106
	v_add_f32_e32 v76, v76, v92
	v_and_b32_e32 v92, 0xffff0000, v106
	v_add_f32_e32 v77, v77, v92
	v_lshlrev_b32_e32 v92, 16, v107
	v_add_f32_e32 v78, v78, v92
	v_and_b32_e32 v92, 0xffff0000, v107
	v_add_f32_e32 v79, v79, v92
	v_mul_f32_e32 v92, v77, v77
	v_mul_f32_e32 v93, v79, v79
	v_fmac_f32_e32 v92, v76, v76
	v_fmac_f32_e32 v93, v78, v78
	v_cvt_pk_bf16_f32 v76, v76, v77
	v_cvt_pk_bf16_f32 v77, v78, v79
	v_lshlrev_b32_e32 v78, 16, v104
	v_add_f32_e32 v72, v72, v78
	v_and_b32_e32 v78, 0xffff0000, v104
	v_add_f32_e32 v73, v73, v78
	v_lshlrev_b32_e32 v78, 16, v105
	v_add_f32_e32 v74, v74, v78
	v_and_b32_e32 v78, 0xffff0000, v105
	v_add_f32_e32 v75, v75, v78
	v_mul_f32_e32 v78, v73, v73
	v_mul_f32_e32 v79, v75, v75
	v_fmac_f32_e32 v78, v72, v72
	v_fmac_f32_e32 v79, v74, v74
	v_add_f32_e32 v92, v92, v93
	v_add_f32_e32 v78, v78, v79
	v_add_f32_e32 v92, v92, v78
	v_cvt_pk_bf16_f32 v78, v72, v73
	v_lshlrev_b32_e32 v72, 16, v102
	v_add_f32_e32 v68, v68, v72
	v_and_b32_e32 v72, 0xffff0000, v102
	v_add_f32_e32 v69, v69, v72
	v_lshlrev_b32_e32 v72, 16, v103
	v_add_f32_e32 v70, v70, v72
	v_and_b32_e32 v72, 0xffff0000, v103
	v_add_f32_e32 v71, v71, v72
	v_mul_f32_e32 v72, v69, v69
	v_mul_f32_e32 v73, v71, v71
	v_cvt_pk_bf16_f32 v79, v74, v75
	v_fmac_f32_e32 v72, v68, v68
	v_fmac_f32_e32 v73, v70, v70
	v_cvt_pk_bf16_f32 v68, v68, v69
	v_cvt_pk_bf16_f32 v69, v70, v71
	v_lshlrev_b32_e32 v70, 16, v100
	v_add_f32_e32 v64, v64, v70
	v_and_b32_e32 v70, 0xffff0000, v100
	v_add_f32_e32 v65, v65, v70
	v_lshlrev_b32_e32 v70, 16, v101
	v_add_f32_e32 v66, v66, v70
	v_and_b32_e32 v70, 0xffff0000, v101
	v_add_f32_e32 v67, v67, v70
	v_mul_f32_e32 v70, v65, v65
	v_mul_f32_e32 v71, v67, v67
	v_add_f32_e32 v72, v72, v73
	v_fmac_f32_e32 v70, v64, v64
	v_fmac_f32_e32 v71, v66, v66
	v_add_f32_e32 v73, v70, v71
	v_cvt_pk_bf16_f32 v70, v64, v65
	v_cvt_pk_bf16_f32 v71, v66, v67
	v_add_f32_e32 v66, v92, v72
	v_add_f32_e32 v72, v66, v73
	ds_bpermute_b32 v73, v124, v72
	v_lshl_add_u64 v[64:65], s[36:37], 1, v[98:99]
	v_lshl_add_u64 v[64:65], v[64:65], 0, s[10:11]
	v_lshl_add_u64 v[64:65], v[64:65], 0, v[132:133]
	v_lshl_add_u64 v[66:67], v[64:65], 0, v[142:143]
	s_waitcnt lgkmcnt(0)
	v_add_f32_e32 v64, v72, v73
	ds_bpermute_b32 v65, v125, v64
	v_permlane16_swap_b32_e32 v76, v78
	v_permlane16_swap_b32_e32 v77, v79
	v_permlane16_swap_b32_e32 v68, v70
	v_permlane16_swap_b32_e32 v69, v71
	global_store_dwordx4 v[66:67], v[76:79], off
	global_store_dwordx4 v[66:67], v[68:71], off offset:256
	s_and_saveexec_b64 s[38:39], s[4:5]
	s_cbranch_execz .LBB0_1162
	s_waitcnt lgkmcnt(0)
	v_add_f32_e32 v64, v64, v65
	v_mul_f32_e32 v64, 0x4f800000, v64
	v_trunc_f32_e32 v64, v64
	v_mul_f32_e32 v65, 0x2f800000, v64
	v_floor_f32_e32 v65, v65
	v_fmac_f32_e32 v64, 0xcf800000, v65
	v_cvt_u32_f32_e32 v64, v64
	v_cvt_u32_f32_e32 v65, v65
	v_lshl_add_u64 v[66:67], v[96:97], 3, s[16:17]
	global_atomic_add_x2 v[66:67], v[64:65], off
.LBB0_1162:
	s_or_b64 exec, exec, s[38:39]
	v_or_b32_e32 v64, 16, v80
	s_waitcnt lgkmcnt(0)
	v_ashrrev_i32_e32 v65, 31, v64
	v_lshlrev_b64 v[66:67], 11, v[64:65]
	v_lshl_add_u64 v[66:67], s[26:27], 0, v[66:67]
	v_lshl_add_u64 v[68:69], v[144:145], 1, v[66:67]
	s_waitcnt vmcnt(20)
	v_mov_b64_e32 v[90:91], v[202:203]
	v_mov_b64_e32 v[88:89], v[204:205]
	v_mov_b64_e32 v[86:87], v[206:207]
	v_mov_b64_e32 v[84:85], v[208:209]
	v_lshlrev_b32_e32 v76, 16, v90
	v_add_f32_e32 v60, v60, v76
	v_and_b32_e32 v76, 0xffff0000, v90
	v_add_f32_e32 v61, v61, v76
	v_lshlrev_b32_e32 v76, 16, v91
	v_add_f32_e32 v62, v62, v76
	v_and_b32_e32 v76, 0xffff0000, v91
	v_add_f32_e32 v63, v63, v76
	v_mul_f32_e32 v76, v61, v61
	v_mul_f32_e32 v77, v63, v63
	v_fmac_f32_e32 v76, v60, v60
	v_fmac_f32_e32 v77, v62, v62
	v_cvt_pk_bf16_f32 v60, v60, v61
	v_cvt_pk_bf16_f32 v61, v62, v63
	v_lshlrev_b32_e32 v62, 16, v88
	v_add_f32_e32 v56, v56, v62
	v_and_b32_e32 v62, 0xffff0000, v88
	v_add_f32_e32 v57, v57, v62
	v_lshlrev_b32_e32 v62, 16, v89
	v_add_f32_e32 v58, v58, v62
	v_and_b32_e32 v62, 0xffff0000, v89
	v_add_f32_e32 v59, v59, v62
	v_mul_f32_e32 v62, v57, v57
	v_mul_f32_e32 v63, v59, v59
	v_fmac_f32_e32 v62, v56, v56
	v_fmac_f32_e32 v63, v58, v58
	v_add_f32_e32 v76, v76, v77
	v_add_f32_e32 v62, v62, v63
	v_add_f32_e32 v76, v76, v62
	v_cvt_pk_bf16_f32 v62, v56, v57
	v_lshlrev_b32_e32 v56, 16, v86
	v_add_f32_e32 v52, v52, v56
	v_and_b32_e32 v56, 0xffff0000, v86
	v_add_f32_e32 v53, v53, v56
	v_lshlrev_b32_e32 v56, 16, v87
	v_add_f32_e32 v54, v54, v56
	v_and_b32_e32 v56, 0xffff0000, v87
	v_add_f32_e32 v55, v55, v56
	v_mul_f32_e32 v56, v53, v53
	v_mul_f32_e32 v57, v55, v55
	v_cvt_pk_bf16_f32 v63, v58, v59
	v_fmac_f32_e32 v56, v52, v52
	v_fmac_f32_e32 v57, v54, v54
	v_cvt_pk_bf16_f32 v52, v52, v53
	v_cvt_pk_bf16_f32 v53, v54, v55
	v_lshlrev_b32_e32 v54, 16, v84
	v_add_f32_e32 v48, v48, v54
	v_and_b32_e32 v54, 0xffff0000, v84
	v_add_f32_e32 v49, v49, v54
	v_lshlrev_b32_e32 v54, 16, v85
	v_add_f32_e32 v50, v50, v54
	v_and_b32_e32 v54, 0xffff0000, v85
	v_add_f32_e32 v51, v51, v54
	v_mul_f32_e32 v54, v49, v49
	v_mul_f32_e32 v55, v51, v51
	v_add_f32_e32 v56, v56, v57
	v_fmac_f32_e32 v54, v48, v48
	v_fmac_f32_e32 v55, v50, v50
	v_add_f32_e32 v57, v54, v55
	v_cvt_pk_bf16_f32 v54, v48, v49
	v_cvt_pk_bf16_f32 v55, v50, v51
	v_add_f32_e32 v50, v76, v56
	v_add_f32_e32 v56, v50, v57
	ds_bpermute_b32 v57, v124, v56
	v_lshl_add_u64 v[48:49], s[36:37], 1, v[82:83]
	v_lshl_add_u64 v[48:49], v[48:49], 0, s[10:11]
	v_lshl_add_u64 v[48:49], v[48:49], 0, v[132:133]
	v_mov_b32_e32 v143, v133
	v_lshl_add_u64 v[50:51], v[48:49], 0, v[142:143]
	s_waitcnt lgkmcnt(0)
	v_add_f32_e32 v48, v56, v57
	ds_bpermute_b32 v49, v125, v48
	v_permlane16_swap_b32_e32 v60, v62
	v_permlane16_swap_b32_e32 v61, v63
	v_permlane16_swap_b32_e32 v52, v54
	v_permlane16_swap_b32_e32 v53, v55
	global_store_dwordx4 v[50:51], v[60:63], off
	global_store_dwordx4 v[50:51], v[52:55], off offset:256
	s_and_saveexec_b64 s[38:39], s[4:5]
	s_cbranch_execz .LBB0_1164
	s_waitcnt lgkmcnt(0)
	v_add_f32_e32 v48, v48, v49
	v_mul_f32_e32 v48, 0x4f800000, v48
	v_trunc_f32_e32 v48, v48
	v_mul_f32_e32 v49, 0x2f800000, v48
	v_floor_f32_e32 v49, v49
	v_fmac_f32_e32 v48, 0xcf800000, v49
	v_cvt_u32_f32_e32 v48, v48
	v_cvt_u32_f32_e32 v49, v49
	v_lshl_add_u64 v[50:51], v[80:81], 3, s[16:17]
	global_atomic_add_x2 v[50:51], v[48:49], off
; __device__ __forceinline__ unsigned cvt_pk_bf16(float lo, float hi) { unsigned r; asm volatile("v_cvt_pk_bf16_f32 %0, %1, %2" : "=v"(r) : "v"(lo), "v"(hi)); return r; }
;     __device__ __forceinline__ void operator()(const f32x4 (&acc)[2][2][4][2], const Unit& u, int wr, int wc, int fr, int fq, PG8_LAS unsigned char*) const {
;     ...
;         for (int ri = 0; ri < 8; ++ri) {
;             const int ai = ri >> 2, m = ri & 3;
;             const int row = u.pm * BM + ai * HALF + wr * 64 + m * 16 + fr; float ss = 0.f;
;             if (ri < 7) { const int ai2 = (ri + 1) >> 2, m2 = (ri + 1) & 3; const size_t off2 = (size_t)(u.pm * BM + ai2 * HALF + wr * 64 + m2 * 16 + fr) * 1024 + col0;
; #pragma unroll
;                 for (int bj = 0; bj < 2; ++bj)
; #pragma unroll
;                     for (int n = 0; n < 2; ++n) nxt[bj][n] = *(const u32x2*)(xb + off2 + bj * HALF + n * 16); }
; #pragma unroll
;             for (int bj = 0; bj < 2; ++bj)
; #pragma unroll
;                 for (int n = 0; n < 2; ++n) { const u32x2 bb = cur[bj][n]; const f32x4 av = acc[ai][bj][m][n];
;                     const float o0 = __uint_as_float(bb.x << 16) + av[0], o1 = __uint_as_float(bb.x & 0xffff0000u) + av[1], o2 = __uint_as_float(bb.y << 16) + av[2], o3 = __uint_as_float(bb.y & 0xffff0000u) + av[3];
;                     ss += (o0 * o0 + o1 * o1) + (o2 * o2 + o3 * o3);
;                     cur[bj][n].x = cvt_pk_bf16(o0, o1); cur[bj][n].y = cvt_pk_bf16(o2, o3); }
; #pragma unroll
;             for (int bj = 0; bj < 2; ++bj) { unsigned a0 = cur[bj][0].x, a1 = cur[bj][0].y, b0 = cur[bj][1].x, b1 = cur[bj][1].y;
;                 { auto r = __builtin_amdgcn_permlane16_swap(a0, b0, false, false); a0 = r[0]; b0 = r[1]; }
;                 { auto r = __builtin_amdgcn_permlane16_swap(a1, b1, false, false); a1 = r[0]; b1 = r[1]; }
;                 u32x4 w; w.x = a0; w.y = a1; w.z = b0; w.w = b1; *(u32x4*)(xb + (size_t)row * 1024 + u.pn * BM + wc * 32 + bj * HALF + ((fq & 1) << 4) + ((fq >> 1) << 3)) = w; }
;             ss += __shfl_xor(ss, 16); ss += __shfl_xor(ss, 32);
;             if (fq == 0) atomicAdd(rss_next + row, (unsigned long long)(ss * 4294967296.0f));
.LBB0_1164:
	s_or_b64 exec, exec, s[38:39]
	v_or_b32_e32 v48, 32, v80
	s_waitcnt lgkmcnt(0)
	v_ashrrev_i32_e32 v49, 31, v48
	v_lshlrev_b64 v[50:51], 11, v[48:49]
	v_lshl_add_u64 v[50:51], s[26:27], 0, v[50:51]
	v_lshl_add_u64 v[52:53], v[144:145], 1, v[50:51]
	s_waitcnt vmcnt(18)
	v_mov_b64_e32 v[74:75], v[210:211]
	v_mov_b64_e32 v[72:73], v[212:213]
	v_mov_b64_e32 v[70:71], v[216:217]
	v_mov_b64_e32 v[68:69], v[218:219]
	v_lshlrev_b32_e32 v60, 16, v74
	v_add_f32_e32 v44, v44, v60
	v_and_b32_e32 v60, 0xffff0000, v74
	v_add_f32_e32 v45, v45, v60
	v_lshlrev_b32_e32 v60, 16, v75
	v_add_f32_e32 v46, v46, v60
	v_and_b32_e32 v60, 0xffff0000, v75
	v_add_f32_e32 v47, v47, v60
	v_mul_f32_e32 v60, v45, v45
	v_mul_f32_e32 v61, v47, v47
	v_fmac_f32_e32 v60, v44, v44
	v_fmac_f32_e32 v61, v46, v46
	v_cvt_pk_bf16_f32 v44, v44, v45
	v_cvt_pk_bf16_f32 v45, v46, v47
	v_lshlrev_b32_e32 v46, 16, v72
	v_add_f32_e32 v40, v40, v46
	v_and_b32_e32 v46, 0xffff0000, v72
	v_add_f32_e32 v41, v41, v46
	v_lshlrev_b32_e32 v46, 16, v73
	v_add_f32_e32 v42, v42, v46
	v_and_b32_e32 v46, 0xffff0000, v73
	v_add_f32_e32 v43, v43, v46
	v_mul_f32_e32 v46, v41, v41
	v_mul_f32_e32 v47, v43, v43
	v_fmac_f32_e32 v46, v40, v40
	v_fmac_f32_e32 v47, v42, v42
	v_add_f32_e32 v60, v60, v61
	v_add_f32_e32 v46, v46, v47
	v_add_f32_e32 v60, v60, v46
	v_cvt_pk_bf16_f32 v46, v40, v41
	v_lshlrev_b32_e32 v40, 16, v70
	v_add_f32_e32 v36, v36, v40
	v_and_b32_e32 v40, 0xffff0000, v70
	v_add_f32_e32 v37, v37, v40
	v_lshlrev_b32_e32 v40, 16, v71
	v_add_f32_e32 v38, v38, v40
	v_and_b32_e32 v40, 0xffff0000, v71
	v_add_f32_e32 v39, v39, v40
	v_mul_f32_e32 v40, v37, v37
	v_mul_f32_e32 v41, v39, v39
	v_cvt_pk_bf16_f32 v47, v42, v43
	v_fmac_f32_e32 v40, v36, v36
	v_fmac_f32_e32 v41, v38, v38
	v_cvt_pk_bf16_f32 v36, v36, v37
	v_cvt_pk_bf16_f32 v37, v38, v39
	v_lshlrev_b32_e32 v38, 16, v68
	v_add_f32_e32 v32, v32, v38
	v_and_b32_e32 v38, 0xffff0000, v68
	v_add_f32_e32 v33, v33, v38
	v_lshlrev_b32_e32 v38, 16, v69
	v_add_f32_e32 v34, v34, v38
	v_and_b32_e32 v38, 0xffff0000, v69
	v_add_f32_e32 v35, v35, v38
	v_mul_f32_e32 v38, v33, v33
	v_mul_f32_e32 v39, v35, v35
	v_add_f32_e32 v40, v40, v41
	v_fmac_f32_e32 v38, v32, v32
	v_fmac_f32_e32 v39, v34, v34
	v_add_f32_e32 v41, v38, v39
	v_cvt_pk_bf16_f32 v38, v32, v33
	v_cvt_pk_bf16_f32 v39, v34, v35
	v_add_f32_e32 v34, v60, v40
	v_add_f32_e32 v40, v34, v41
	ds_bpermute_b32 v41, v124, v40
	v_lshl_add_u64 v[32:33], s[36:37], 1, v[66:67]
	v_lshl_add_u64 v[32:33], v[32:33], 0, s[10:11]
	v_lshl_add_u64 v[32:33], v[32:33], 0, v[132:133]
	v_lshl_add_u64 v[34:35], v[32:33], 0, v[142:143]
	s_waitcnt lgkmcnt(0)
	v_add_f32_e32 v32, v40, v41
	ds_bpermute_b32 v33, v125, v32
	v_permlane16_swap_b32_e32 v44, v46
	v_permlane16_swap_b32_e32 v45, v47
	v_permlane16_swap_b32_e32 v36, v38
	v_permlane16_swap_b32_e32 v37, v39
	global_store_dwordx4 v[34:35], v[44:47], off
	global_store_dwordx4 v[34:35], v[36:39], off offset:256
	s_and_saveexec_b64 s[38:39], s[4:5]
	s_cbranch_execz .LBB0_1166
	s_waitcnt lgkmcnt(0)
	v_add_f32_e32 v32, v32, v33
	v_mul_f32_e32 v32, 0x4f800000, v32
	v_trunc_f32_e32 v32, v32
	v_mul_f32_e32 v33, 0x2f800000, v32
	v_floor_f32_e32 v33, v33
	v_fmac_f32_e32 v32, 0xcf800000, v33
	v_cvt_u32_f32_e32 v32, v32
	v_cvt_u32_f32_e32 v33, v33
	v_lshl_add_u64 v[34:35], v[64:65], 3, s[16:17]
	global_atomic_add_x2 v[34:35], v[32:33], off
; __device__ __forceinline__ unsigned cvt_pk_bf16(float lo, float hi) { unsigned r; asm volatile("v_cvt_pk_bf16_f32 %0, %1, %2" : "=v"(r) : "v"(lo), "v"(hi)); return r; }
;     __device__ __forceinline__ void operator()(const f32x4 (&acc)[2][2][4][2], const Unit& u, int wr, int wc, int fr, int fq, PG8_LAS unsigned char*) const {
;     ...
;         for (int ri = 0; ri < 8; ++ri) {
;             const int ai = ri >> 2, m = ri & 3;
;             const int row = u.pm * BM + ai * HALF + wr * 64 + m * 16 + fr; float ss = 0.f;
;             if (ri < 7) { const int ai2 = (ri + 1) >> 2, m2 = (ri + 1) & 3; const size_t off2 = (size_t)(u.pm * BM + ai2 * HALF + wr * 64 + m2 * 16 + fr) * 1024 + col0;
; #pragma unroll
;                 for (int bj = 0; bj < 2; ++bj)
; #pragma unroll
;                     for (int n = 0; n < 2; ++n) nxt[bj][n] = *(const u32x2*)(xb + off2 + bj * HALF + n * 16); }
; #pragma unroll
;             for (int bj = 0; bj < 2; ++bj)
; #pragma unroll
;                 for (int n = 0; n < 2; ++n) { const u32x2 bb = cur[bj][n]; const f32x4 av = acc[ai][bj][m][n];
;                     const float o0 = __uint_as_float(bb.x << 16) + av[0], o1 = __uint_as_float(bb.x & 0xffff0000u) + av[1], o2 = __uint_as_float(bb.y << 16) + av[2], o3 = __uint_as_float(bb.y & 0xffff0000u) + av[3];
;                     ss += (o0 * o0 + o1 * o1) + (o2 * o2 + o3 * o3);
;                     cur[bj][n].x = cvt_pk_bf16(o0, o1); cur[bj][n].y = cvt_pk_bf16(o2, o3); }
; #pragma unroll
;             for (int bj = 0; bj < 2; ++bj) { unsigned a0 = cur[bj][0].x, a1 = cur[bj][0].y, b0 = cur[bj][1].x, b1 = cur[bj][1].y;
;                 { auto r = __builtin_amdgcn_permlane16_swap(a0, b0, false, false); a0 = r[0]; b0 = r[1]; }
;                 { auto r = __builtin_amdgcn_permlane16_swap(a1, b1, false, false); a1 = r[0]; b1 = r[1]; }
;                 u32x4 w; w.x = a0; w.y = a1; w.z = b0; w.w = b1; *(u32x4*)(xb + (size_t)row * 1024 + u.pn * BM + wc * 32 + bj * HALF + ((fq & 1) << 4) + ((fq >> 1) << 3)) = w; }
;             ss += __shfl_xor(ss, 16); ss += __shfl_xor(ss, 32);
;             if (fq == 0) atomicAdd(rss_next + row, (unsigned long long)(ss * 4294967296.0f));
; #pragma unroll
;             for (int bj = 0; bj < 2; ++bj)
; #pragma unroll
;                 for (int n = 0; n < 2; ++n) cur[bj][n] = nxt[bj][n];
.LBB0_1166:
	s_or_b64 exec, exec, s[38:39]
	v_or_b32_e32 v32, 48, v80
	s_waitcnt lgkmcnt(0)
	v_ashrrev_i32_e32 v33, 31, v32
	v_lshlrev_b64 v[34:35], 11, v[32:33]
	v_lshl_add_u64 v[34:35], s[26:27], 0, v[34:35]
	v_lshl_add_u64 v[36:37], v[144:145], 1, v[34:35]
	s_waitcnt vmcnt(16)
	v_mov_b64_e32 v[58:59], v[220:221]
	v_mov_b64_e32 v[56:57], v[222:223]
	v_mov_b64_e32 v[54:55], v[224:225]
	v_mov_b64_e32 v[52:53], v[226:227]
	v_lshlrev_b32_e32 v44, 16, v58
	v_add_f32_e32 v28, v28, v44
	v_and_b32_e32 v44, 0xffff0000, v58
	v_add_f32_e32 v29, v29, v44
	v_lshlrev_b32_e32 v44, 16, v59
	v_add_f32_e32 v30, v30, v44
	v_and_b32_e32 v44, 0xffff0000, v59
	v_add_f32_e32 v31, v31, v44
	v_mul_f32_e32 v44, v29, v29
	v_mul_f32_e32 v45, v31, v31
	v_fmac_f32_e32 v44, v28, v28
	v_fmac_f32_e32 v45, v30, v30
	v_cvt_pk_bf16_f32 v28, v28, v29
	v_cvt_pk_bf16_f32 v29, v30, v31
	v_lshlrev_b32_e32 v30, 16, v56
	v_add_f32_e32 v24, v24, v30
	v_and_b32_e32 v30, 0xffff0000, v56
	v_add_f32_e32 v25, v25, v30
	v_lshlrev_b32_e32 v30, 16, v57
	v_add_f32_e32 v26, v26, v30
	v_and_b32_e32 v30, 0xffff0000, v57
	v_add_f32_e32 v27, v27, v30
	v_mul_f32_e32 v30, v25, v25
	v_mul_f32_e32 v31, v27, v27
	v_fmac_f32_e32 v30, v24, v24
	v_fmac_f32_e32 v31, v26, v26
	v_add_f32_e32 v44, v44, v45
	v_add_f32_e32 v30, v30, v31
	v_add_f32_e32 v44, v44, v30
	v_cvt_pk_bf16_f32 v30, v24, v25
	v_lshlrev_b32_e32 v24, 16, v54
	v_add_f32_e32 v20, v20, v24
	v_and_b32_e32 v24, 0xffff0000, v54
	v_add_f32_e32 v21, v21, v24
	v_lshlrev_b32_e32 v24, 16, v55
	v_add_f32_e32 v22, v22, v24
	v_and_b32_e32 v24, 0xffff0000, v55
	v_add_f32_e32 v23, v23, v24
	v_mul_f32_e32 v24, v21, v21
	v_mul_f32_e32 v25, v23, v23
	v_cvt_pk_bf16_f32 v31, v26, v27
	v_fmac_f32_e32 v24, v20, v20
	v_fmac_f32_e32 v25, v22, v22
	v_cvt_pk_bf16_f32 v20, v20, v21
	v_cvt_pk_bf16_f32 v21, v22, v23
	v_lshlrev_b32_e32 v22, 16, v52
	v_add_f32_e32 v16, v16, v22
	v_and_b32_e32 v22, 0xffff0000, v52
	v_add_f32_e32 v17, v17, v22
	v_lshlrev_b32_e32 v22, 16, v53
	v_add_f32_e32 v18, v18, v22
	v_and_b32_e32 v22, 0xffff0000, v53
	v_add_f32_e32 v19, v19, v22
	v_mul_f32_e32 v22, v17, v17
	v_mul_f32_e32 v23, v19, v19
	v_add_f32_e32 v24, v24, v25
	v_fmac_f32_e32 v22, v16, v16
	v_fmac_f32_e32 v23, v18, v18
	v_add_f32_e32 v25, v22, v23
	v_cvt_pk_bf16_f32 v22, v16, v17
	v_cvt_pk_bf16_f32 v23, v18, v19
	v_add_f32_e32 v18, v44, v24
	v_add_f32_e32 v24, v18, v25
	ds_bpermute_b32 v25, v124, v24
	v_lshl_add_u64 v[16:17], s[36:37], 1, v[50:51]
	v_lshl_add_u64 v[16:17], v[16:17], 0, s[10:11]
	v_lshl_add_u64 v[16:17], v[16:17], 0, v[132:133]
	v_mov_b32_e32 v143, v133
	v_lshl_add_u64 v[18:19], v[16:17], 0, v[142:143]
	s_waitcnt lgkmcnt(0)
	v_add_f32_e32 v16, v24, v25
	ds_bpermute_b32 v17, v125, v16
	v_permlane16_swap_b32_e32 v28, v30
	v_permlane16_swap_b32_e32 v29, v31
	v_permlane16_swap_b32_e32 v20, v22
	v_permlane16_swap_b32_e32 v21, v23
	global_store_dwordx4 v[18:19], v[28:31], off
	global_store_dwordx4 v[18:19], v[20:23], off offset:256
	s_and_saveexec_b64 s[38:39], s[4:5]
	s_cbranch_execz .LBB0_1168
	s_waitcnt lgkmcnt(0)
	v_add_f32_e32 v16, v16, v17
	v_mul_f32_e32 v16, 0x4f800000, v16
	v_trunc_f32_e32 v16, v16
	v_mul_f32_e32 v17, 0x2f800000, v16
	v_floor_f32_e32 v17, v17
	v_fmac_f32_e32 v16, 0xcf800000, v17
	v_cvt_u32_f32_e32 v16, v16
	v_cvt_u32_f32_e32 v17, v17
	v_lshl_add_u64 v[18:19], v[48:49], 3, s[16:17]
	global_atomic_add_x2 v[18:19], v[16:17], off
.LBB0_1168:
	s_or_b64 exec, exec, s[38:39]
	s_waitcnt vmcnt(14)
	v_mov_b64_e32 v[42:43], v[228:229]
	v_mov_b64_e32 v[40:41], v[230:231]
	v_mov_b64_e32 v[38:39], v[232:233]
	v_mov_b64_e32 v[36:37], v[234:235]
	v_lshlrev_b32_e32 v16, 16, v42
	v_add_f32_e32 v12, v12, v16
	v_and_b32_e32 v16, 0xffff0000, v42
	v_add_f32_e32 v13, v13, v16
	v_lshlrev_b32_e32 v16, 16, v43
	v_add_f32_e32 v14, v14, v16
	v_and_b32_e32 v16, 0xffff0000, v43
	v_add_f32_e32 v15, v15, v16
	v_mul_f32_e32 v16, v13, v13
	s_waitcnt lgkmcnt(0)
	v_mul_f32_e32 v17, v15, v15
	v_fmac_f32_e32 v16, v12, v12
	v_fmac_f32_e32 v17, v14, v14
	v_cvt_pk_bf16_f32 v12, v12, v13
	v_cvt_pk_bf16_f32 v13, v14, v15
	v_lshlrev_b32_e32 v14, 16, v40
	v_add_f32_e32 v8, v8, v14
	v_and_b32_e32 v14, 0xffff0000, v40
	v_add_f32_e32 v9, v9, v14
	v_lshlrev_b32_e32 v14, 16, v41
	v_add_f32_e32 v10, v10, v14
	v_and_b32_e32 v14, 0xffff0000, v41
	v_add_f32_e32 v11, v11, v14
	v_mul_f32_e32 v14, v9, v9
	v_mul_f32_e32 v15, v11, v11
	v_fmac_f32_e32 v14, v8, v8
	v_fmac_f32_e32 v15, v10, v10
	v_add_f32_e32 v16, v16, v17
	v_add_f32_e32 v14, v14, v15
	v_add_f32_e32 v16, v16, v14
	v_cvt_pk_bf16_f32 v14, v8, v9
	v_lshlrev_b32_e32 v8, 16, v38
	v_add_f32_e32 v4, v4, v8
	v_and_b32_e32 v8, 0xffff0000, v38
	v_add_f32_e32 v5, v5, v8
	v_lshlrev_b32_e32 v8, 16, v39
	v_add_f32_e32 v6, v6, v8
	v_and_b32_e32 v8, 0xffff0000, v39
	v_add_f32_e32 v7, v7, v8
	v_mul_f32_e32 v8, v5, v5
	v_mul_f32_e32 v9, v7, v7
	v_cvt_pk_bf16_f32 v15, v10, v11
	v_fmac_f32_e32 v8, v4, v4
	v_fmac_f32_e32 v9, v6, v6
	v_cvt_pk_bf16_f32 v4, v4, v5
	v_cvt_pk_bf16_f32 v5, v6, v7
	v_lshlrev_b32_e32 v6, 16, v36
	v_add_f32_e32 v0, v0, v6
	v_and_b32_e32 v6, 0xffff0000, v36
	v_add_f32_e32 v1, v1, v6
	v_lshlrev_b32_e32 v6, 16, v37
	v_add_f32_e32 v2, v2, v6
	v_and_b32_e32 v6, 0xffff0000, v37
	v_add_f32_e32 v3, v3, v6
	v_mul_f32_e32 v6, v1, v1
	v_mul_f32_e32 v7, v3, v3
	v_add_f32_e32 v8, v8, v9
	v_fmac_f32_e32 v6, v0, v0
	v_fmac_f32_e32 v7, v2, v2
	v_add_f32_e32 v9, v6, v7
	v_cvt_pk_bf16_f32 v6, v0, v1
	v_cvt_pk_bf16_f32 v7, v2, v3
	v_add_f32_e32 v2, v16, v8
	v_add_f32_e32 v8, v2, v9
	ds_bpermute_b32 v9, v124, v8
	v_lshl_add_u64 v[0:1], s[36:37], 1, v[34:35]
	v_lshl_add_u64 v[0:1], v[0:1], 0, s[10:11]
	v_lshl_add_u64 v[0:1], v[0:1], 0, v[132:133]
	v_lshl_add_u64 v[2:3], v[0:1], 0, v[142:143]
	s_waitcnt lgkmcnt(0)
	v_add_f32_e32 v0, v8, v9
	ds_bpermute_b32 v1, v125, v0
	v_permlane16_swap_b32_e32 v12, v14
	v_permlane16_swap_b32_e32 v13, v15
	v_permlane16_swap_b32_e32 v4, v6
	v_permlane16_swap_b32_e32 v5, v7
	global_store_dwordx4 v[2:3], v[12:15], off
	global_store_dwordx4 v[2:3], v[4:7], off offset:256
	s_and_saveexec_b64 s[36:37], s[4:5]
	s_cbranch_execz .LBB0_1170
	s_waitcnt lgkmcnt(0)
	v_add_f32_e32 v0, v0, v1
	v_mul_f32_e32 v0, 0x4f800000, v0
	v_trunc_f32_e32 v0, v0
	v_mul_f32_e32 v1, 0x2f800000, v0
	v_floor_f32_e32 v1, v1
	v_fmac_f32_e32 v0, 0xcf800000, v1
	v_cvt_u32_f32_e32 v0, v0
	v_cvt_u32_f32_e32 v1, v1
	v_lshl_add_u64 v[2:3], v[32:33], 3, s[16:17]
	global_atomic_add_x2 v[2:3], v[0:1], off

; __global__ void __launch_bounds__(NWAVES * 64, 2) mk_fwd(Args args) {
	.amdhsa_kernel _Z6mk_fwd4Args
		.amdhsa_group_segment_fixed_size 0
		.amdhsa_private_segment_fixed_size 0
		.amdhsa_kernarg_size 408
		.amdhsa_user_sgpr_count 2
		.amdhsa_user_sgpr_dispatch_ptr 0
		.amdhsa_user_sgpr_queue_ptr 0
		.amdhsa_user_sgpr_kernarg_segment_ptr 1
		.amdhsa_user_sgpr_dispatch_id 0
		.amdhsa_user_sgpr_kernarg_preload_length 0
		.amdhsa_user_sgpr_kernarg_preload_offset 0
		.amdhsa_user_sgpr_private_segment_size 0
		.amdhsa_uses_dynamic_stack 0
		.amdhsa_enable_private_segment 0
		.amdhsa_system_sgpr_workgroup_id_x 1
		.amdhsa_system_sgpr_workgroup_id_y 0
		.amdhsa_system_sgpr_workgroup_id_z 0
		.amdhsa_system_sgpr_workgroup_info 0
		.amdhsa_system_vgpr_workitem_id 2
		.amdhsa_next_free_vgpr 256
		.amdhsa_next_free_sgpr 100
		.amdhsa_accum_offset 256
		.amdhsa_reserve_vcc 1
		.amdhsa_float_round_mode_32 0
		.amdhsa_float_round_mode_16_64 0
		.amdhsa_float_denorm_mode_32 3
		.amdhsa_float_denorm_mode_16_64 3
		.amdhsa_dx10_clamp 1
		.amdhsa_ieee_mode 1
		.amdhsa_fp16_overflow 0
		.amdhsa_tg_split 0
		.amdhsa_exception_fp_ieee_invalid_op 0
		.amdhsa_exception_fp_denorm_src 0
		.amdhsa_exception_fp_ieee_div_zero 0
		.amdhsa_exception_fp_ieee_overflow 0
		.amdhsa_exception_fp_ieee_underflow 0
		.amdhsa_exception_fp_ieee_inexact 0
		.amdhsa_exception_int_div_zero 0
	.end_amdhsa_kernel

; __global__ void __launch_bounds__(NWAVES * 64, 2) mk_fwd(Args args) {
amdhsa.kernels:
  - .agpr_count:     0
    .args:
      - .offset:         0
        .size:           152
        .value_kind:     by_value
      - .offset:         152
        .size:           4
        .value_kind:     hidden_block_count_x
      - .offset:         156
        .size:           4
        .value_kind:     hidden_block_count_y
      - .offset:         160
        .size:           4
        .value_kind:     hidden_block_count_z
      - .offset:         164
        .size:           2
        .value_kind:     hidden_group_size_x
      - .offset:         166
        .size:           2
        .value_kind:     hidden_group_size_y
      - .offset:         168
        .size:           2
        .value_kind:     hidden_group_size_z
      - .offset:         170
        .size:           2
        .value_kind:     hidden_remainder_x
      - .offset:         172
        .size:           2
        .value_kind:     hidden_remainder_y
      - .offset:         174
        .size:           2
        .value_kind:     hidden_remainder_z
      - .offset:         192
        .size:           8
        .value_kind:     hidden_global_offset_x
      - .offset:         200
        .size:           8
        .value_kind:     hidden_global_offset_y
      - .offset:         208
        .size:           8
        .value_kind:     hidden_global_offset_z
      - .offset:         216
        .size:           2
        .value_kind:     hidden_grid_dims
      - .offset:         240
        .size:           8
        .value_kind:     hidden_multigrid_sync_arg
      - .offset:         272
        .size:           4
        .value_kind:     hidden_dynamic_lds_size
    .group_segment_fixed_size: 0
    .kernarg_segment_align: 8
    .kernarg_segment_size: 408
    .language:       OpenCL C
    .language_version:
      - 2
      - 0
    .max_flat_workgroup_size: 512
    .name:           _Z6mk_fwd4Args
    .private_segment_fixed_size: 0
    .sgpr_count:     106
    .sgpr_spill_count: 25
    .symbol:         _Z6mk_fwd4Args.kd
    .uniform_work_group_size: 1
    .uses_dynamic_stack: false
    .vgpr_count:     256
    .vgpr_spill_count: 0
    .wavefront_size: 64
